# speedup vs baseline: 1.0045x; 1.0020x over previous
; __device__ __forceinline__ float vfma(float a, float b, float c) { float d; asm("v_fma_f32 %0, %1, %2, %3" : "=v"(d) : "v"(a), "v"(b), "v"(c)); return d; }
; __device__ __forceinline__ float step_compute(float (&S)[4], const StepOp& o) {
;     float d1 = vmul(S[0], o.kk[0]), d2 = vmul(S[0], o.wr[0]), e1 = vmul(S[1], o.kk[1]), e2 = vmul(S[1], o.wr[1]);
;     d1 = vfma(S[2], o.kk[2], d1); d2 = vfma(S[2], o.wr[2], d2); e1 = vfma(S[3], o.kk[3], e1); e2 = vfma(S[3], o.wr[3], e2);
;     d1 = vadd(d1, e1); d2 = vadd(d2, e2);
;     float t0, t1, t2, t3;
;     asm volatile(
;         "v_mul_f32 %[t0], %[s0], %[w0]\n\t"
;         "v_mul_f32 %[t1], %[s1], %[w1]\n\t"
;         "v_add_f32_dpp %[d1], %[d1], %[d1] quad_perm:[1,0,3,2] row_mask:0xf bank_mask:0xf bound_ctrl:1\n\t"
;         "v_add_f32_dpp %[d2], %[d2], %[d2] quad_perm:[1,0,3,2] row_mask:0xf bank_mask:0xf bound_ctrl:1\n\t"
;         "v_mul_f32 %[t2], %[s2], %[w2]\n\t"
;         "v_add_f32_dpp %[d1], %[d1], %[d1] quad_perm:[2,3,0,1] row_mask:0xf bank_mask:0xf bound_ctrl:1\n\t"
;         "v_add_f32_dpp %[d2], %[d2], %[d2] quad_perm:[2,3,0,1] row_mask:0xf bank_mask:0xf bound_ctrl:1\n\t"
;         "v_mul_f32 %[t3], %[s3], %[w3]\n\t"
;         "v_add_f32_dpp %[d1], %[d1], %[d1] row_half_mirror row_mask:0xf bank_mask:0xf bound_ctrl:1\n\t"
;         "v_add_f32_dpp %[d2], %[d2], %[d2] row_half_mirror row_mask:0xf bank_mask:0xf bound_ctrl:1\n\t"
;         "v_fma_f32 %[t0], %[v], %[k0], %[t0]\n\t"
;         "v_add_f32_dpp %[d1], %[d1], %[d1] row_mirror row_mask:0xf bank_mask:0xf bound_ctrl:1\n\t"
;         "v_add_f32_dpp %[d2], %[d2], %[d2] row_mirror row_mask:0xf bank_mask:0xf bound_ctrl:1\n\t"
;         "v_fma_f32 %[t1], %[v], %[k1], %[t1]\n\t"
;         "v_fma_f32 %[t2], %[v], %[k2], %[t2]\n\t"
;         "v_fma_f32 %[t3], %[v], %[k3], %[t3]"
;         : [t0] "=&v"(t0), [t1] "=&v"(t1), [t2] "=&v"(t2), [t3] "=&v"(t3), [d1] "+v"(d1), [d2] "+v"(d2)
;         : [s0] "v"(S[0]), [s1] "v"(S[1]), [s2] "v"(S[2]), [s3] "v"(S[3]), [w0] "v"(o.w[0]), [w1] "v"(o.w[1]), [w2] "v"(o.w[2]), [w3] "v"(o.w[3]),
;           [k0] "v"(o.k[0]), [k1] "v"(o.k[1]), [k2] "v"(o.k[2]), [k3] "v"(o.k[3]), [v] "v"(o.q[0]));
;     S[0] = vnfma(d1, o.b[0], t0); S[1] = vnfma(d1, o.b[1], t1); S[2] = vnfma(d1, o.b[2], t2); S[3] = vnfma(d1, o.b[3], t3);
;     return vfma(o.q[0], o.q[2], vnfma(d1, o.q[1], d2));
.LBB0_774:
	v_cndmask_b32_e64 v2, 0, 1, s[50:51]
	v_cmp_ne_u32_e64 s[8:9], 1, v2
	s_andn2_b64 vcc, exec, s[50:51]
	s_mov_b64 s[78:79], -1
	s_cbranch_vccnz .LBB0_776
	s_and_b64 s[78:79], s[74:75], exec
	s_cselect_b32 s10, 0, s91
	v_add_u32_e32 v3, s10, v149
	s_cselect_b32 s10, s93, s92
	v_add_u32_e32 v4, s10, v150
	ds_read_b128 v[160:163], v3
	ds_read_b128 v[168:171], v3 offset:256
	ds_read_b128 v[172:175], v3 offset:512
	ds_read_b128 v[180:183], v3 offset:1024
	ds_read_b128 v[184:187], v4
	ds_read_b128 v[176:179], v3 offset:768
	v_add_u32_e32 v2, s42, v148
	s_mov_b64 s[78:79], 0
	v_mbcnt_lo_u32_b32 v115, -1, 0
	v_mbcnt_hi_u32_b32 v115, -1, v115
	v_and_b32_e32 v115, 4, v115
	v_xor_b32_e32 v115, 4, v115
	v_mul_u32_u24_e32 v115, 0x2700, v115
	v_add_u32_e32 v2, v2, v115
	ds_read_b128 v[188:191], v3 offset:1536
	ds_read_b128 v[192:195], v3 offset:1792
	ds_read_b128 v[196:199], v3 offset:2048
	ds_read_b128 v[204:207], v3 offset:2560
	ds_read_b128 v[208:211], v4 offset:1536
	ds_read_b128 v[200:203], v3 offset:2304
	s_waitcnt lgkmcnt(6)
	v_mul_f32 v160, v38, v160
	v_mul_f32 v168, v38, v168
	v_fma_f32 v160, v39, v161, v160
	v_fma_f32 v168, v39, v169, v168
	v_fma_f32 v160, v40, v162, v160
	v_fma_f32 v168, v40, v170, v168
	v_fma_f32 v160, v41, v163, v160
	v_fma_f32 v168, v41, v171, v168
	v_mul_f32 v172, v38, v172
	v_add_f32_dpp v160, v160, v160 row_half_mirror row_mask:0xf bank_mask:0x5
	v_add_f32_dpp v160, v168, v168 row_half_mirror row_mask:0xf bank_mask:0xa
	v_mul_f32 v173, v39, v173
	v_mul_f32 v174, v40, v174
	v_add_f32_dpp v160, v160, v160 quad_perm:[1,0,3,2] row_mask:0xf bank_mask:0xf
	v_mul_f32 v175, v41, v175
	v_fma_f32 v172, v184, v180, v172
	v_add_f32_dpp v160, v160, v160 quad_perm:[2,3,0,1] row_mask:0xf bank_mask:0xf
	v_fma_f32 v173, v184, v181, v173
	v_fma_f32 v174, v184, v182, v174
	v_add_f32_dpp v160, v160, v160 row_ror:8 row_mask:0xf bank_mask:0xf
	v_fma_f32 v168, v184, v186, v160
	v_fma_f32 v175, v184, v183, v175
	v_mov_b32_dpp v160, v160 row_half_mirror row_mask:0xf bank_mask:0xa
	v_fma_f32 v159, -v160, v176, v172
	v_fma_f32 v164, -v160, v177, v173
	v_fma_f32 v165, -v160, v178, v174
	v_fma_f32 v167, -v160, v179, v175
	v_fma_f32 v168, -v160, v185, v168
	ds_write_b32 v2, v168
	ds_read_b128 v[160:163], v3 offset:3072
	ds_read_b128 v[168:171], v3 offset:3328
	ds_read_b128 v[172:175], v3 offset:3584
	ds_read_b128 v[180:183], v3 offset:4096
	ds_read_b128 v[184:187], v4 offset:3072
	ds_read_b128 v[176:179], v3 offset:3840
	s_waitcnt lgkmcnt(7)
	v_mul_f32 v188, v159, v188
	v_mul_f32 v192, v159, v192
	v_fma_f32 v188, v164, v189, v188
	v_fma_f32 v192, v164, v193, v192
	v_fma_f32 v188, v165, v190, v188
	v_fma_f32 v192, v165, v194, v192
	v_fma_f32 v188, v167, v191, v188
	v_fma_f32 v192, v167, v195, v192
	v_mul_f32 v196, v159, v196
	v_add_f32_dpp v188, v188, v188 row_half_mirror row_mask:0xf bank_mask:0x5
	v_add_f32_dpp v188, v192, v192 row_half_mirror row_mask:0xf bank_mask:0xa
	v_mul_f32 v197, v164, v197
	v_mul_f32 v198, v165, v198
	v_add_f32_dpp v188, v188, v188 quad_perm:[1,0,3,2] row_mask:0xf bank_mask:0xf
	v_mul_f32 v199, v167, v199
	v_fma_f32 v196, v208, v204, v196
	v_add_f32_dpp v188, v188, v188 quad_perm:[2,3,0,1] row_mask:0xf bank_mask:0xf
	v_fma_f32 v197, v208, v205, v197
	v_fma_f32 v198, v208, v206, v198
	v_add_f32_dpp v188, v188, v188 row_ror:8 row_mask:0xf bank_mask:0xf
	v_fma_f32 v192, v208, v210, v188
	v_fma_f32 v199, v208, v207, v199
	v_mov_b32_dpp v188, v188 row_half_mirror row_mask:0xf bank_mask:0xa
	v_fma_f32 v159, -v188, v200, v196
	v_fma_f32 v164, -v188, v201, v197
	v_fma_f32 v165, -v188, v202, v198
	v_fma_f32 v167, -v188, v203, v199
	v_fma_f32 v192, -v188, v209, v192
	ds_write_b32 v2, v192 offset:64
	ds_read_b128 v[188:191], v3 offset:4608
	ds_read_b128 v[192:195], v3 offset:4864
	ds_read_b128 v[196:199], v3 offset:5120
	ds_read_b128 v[204:207], v3 offset:5632
	ds_read_b128 v[208:211], v4 offset:4608
	ds_read_b128 v[200:203], v3 offset:5376
	s_waitcnt lgkmcnt(7)
	v_mul_f32 v160, v159, v160
	v_mul_f32 v168, v159, v168
	v_fma_f32 v160, v164, v161, v160
	v_fma_f32 v168, v164, v169, v168
	v_fma_f32 v160, v165, v162, v160
	v_fma_f32 v168, v165, v170, v168
	v_fma_f32 v160, v167, v163, v160
	v_fma_f32 v168, v167, v171, v168
	v_mul_f32 v172, v159, v172
	v_add_f32_dpp v160, v160, v160 row_half_mirror row_mask:0xf bank_mask:0x5
	v_add_f32_dpp v160, v168, v168 row_half_mirror row_mask:0xf bank_mask:0xa
	v_mul_f32 v173, v164, v173
	v_mul_f32 v174, v165, v174
	v_add_f32_dpp v160, v160, v160 quad_perm:[1,0,3,2] row_mask:0xf bank_mask:0xf
	v_mul_f32 v175, v167, v175
	v_fma_f32 v172, v184, v180, v172
	v_add_f32_dpp v160, v160, v160 quad_perm:[2,3,0,1] row_mask:0xf bank_mask:0xf
	v_fma_f32 v173, v184, v181, v173
	v_fma_f32 v174, v184, v182, v174
	v_add_f32_dpp v160, v160, v160 row_ror:8 row_mask:0xf bank_mask:0xf
	v_fma_f32 v168, v184, v186, v160
	v_fma_f32 v175, v184, v183, v175
	v_mov_b32_dpp v160, v160 row_half_mirror row_mask:0xf bank_mask:0xa
	v_fma_f32 v159, -v160, v176, v172
	v_fma_f32 v164, -v160, v177, v173
	v_fma_f32 v165, -v160, v178, v174
	v_fma_f32 v167, -v160, v179, v175
	v_fma_f32 v168, -v160, v185, v168
	ds_write_b32 v2, v168 offset:128
	ds_read_b128 v[160:163], v3 offset:6144
	ds_read_b128 v[168:171], v3 offset:6400
	ds_read_b128 v[172:175], v3 offset:6656
	ds_read_b128 v[180:183], v3 offset:7168
	ds_read_b128 v[184:187], v4 offset:6144
	ds_read_b128 v[176:179], v3 offset:6912
	s_waitcnt lgkmcnt(7)
; __device__ __forceinline__ float vfma(float a, float b, float c) { float d; asm("v_fma_f32 %0, %1, %2, %3" : "=v"(d) : "v"(a), "v"(b), "v"(c)); return d; }
; __device__ __forceinline__ float step_compute(float (&S)[4], const StepOp& o) {
;     float d1 = vmul(S[0], o.kk[0]), d2 = vmul(S[0], o.wr[0]), e1 = vmul(S[1], o.kk[1]), e2 = vmul(S[1], o.wr[1]);
;     d1 = vfma(S[2], o.kk[2], d1); d2 = vfma(S[2], o.wr[2], d2); e1 = vfma(S[3], o.kk[3], e1); e2 = vfma(S[3], o.wr[3], e2);
;     d1 = vadd(d1, e1); d2 = vadd(d2, e2);
;     float t0, t1, t2, t3;
;     asm volatile(
;         "v_mul_f32 %[t0], %[s0], %[w0]\n\t"
;         "v_mul_f32 %[t1], %[s1], %[w1]\n\t"
;         "v_add_f32_dpp %[d1], %[d1], %[d1] quad_perm:[1,0,3,2] row_mask:0xf bank_mask:0xf bound_ctrl:1\n\t"
;         "v_add_f32_dpp %[d2], %[d2], %[d2] quad_perm:[1,0,3,2] row_mask:0xf bank_mask:0xf bound_ctrl:1\n\t"
;         "v_mul_f32 %[t2], %[s2], %[w2]\n\t"
;         "v_add_f32_dpp %[d1], %[d1], %[d1] quad_perm:[2,3,0,1] row_mask:0xf bank_mask:0xf bound_ctrl:1\n\t"
;         "v_add_f32_dpp %[d2], %[d2], %[d2] quad_perm:[2,3,0,1] row_mask:0xf bank_mask:0xf bound_ctrl:1\n\t"
;         "v_mul_f32 %[t3], %[s3], %[w3]\n\t"
;         "v_add_f32_dpp %[d1], %[d1], %[d1] row_half_mirror row_mask:0xf bank_mask:0xf bound_ctrl:1\n\t"
;         "v_add_f32_dpp %[d2], %[d2], %[d2] row_half_mirror row_mask:0xf bank_mask:0xf bound_ctrl:1\n\t"
;         "v_fma_f32 %[t0], %[v], %[k0], %[t0]\n\t"
;         "v_add_f32_dpp %[d1], %[d1], %[d1] row_mirror row_mask:0xf bank_mask:0xf bound_ctrl:1\n\t"
;         "v_add_f32_dpp %[d2], %[d2], %[d2] row_mirror row_mask:0xf bank_mask:0xf bound_ctrl:1\n\t"
;         "v_fma_f32 %[t1], %[v], %[k1], %[t1]\n\t"
;         "v_fma_f32 %[t2], %[v], %[k2], %[t2]\n\t"
;         "v_fma_f32 %[t3], %[v], %[k3], %[t3]"
;         : [t0] "=&v"(t0), [t1] "=&v"(t1), [t2] "=&v"(t2), [t3] "=&v"(t3), [d1] "+v"(d1), [d2] "+v"(d2)
;         : [s0] "v"(S[0]), [s1] "v"(S[1]), [s2] "v"(S[2]), [s3] "v"(S[3]), [w0] "v"(o.w[0]), [w1] "v"(o.w[1]), [w2] "v"(o.w[2]), [w3] "v"(o.w[3]),
;           [k0] "v"(o.k[0]), [k1] "v"(o.k[1]), [k2] "v"(o.k[2]), [k3] "v"(o.k[3]), [v] "v"(o.q[0]));
;     S[0] = vnfma(d1, o.b[0], t0); S[1] = vnfma(d1, o.b[1], t1); S[2] = vnfma(d1, o.b[2], t2); S[3] = vnfma(d1, o.b[3], t3);
;     return vfma(o.q[0], o.q[2], vnfma(d1, o.q[1], d2));
	v_mul_f32 v188, v159, v188
	v_mul_f32 v192, v159, v192
	v_fma_f32 v188, v164, v189, v188
	v_fma_f32 v192, v164, v193, v192
	v_fma_f32 v188, v165, v190, v188
	v_fma_f32 v192, v165, v194, v192
	v_fma_f32 v188, v167, v191, v188
	v_fma_f32 v192, v167, v195, v192
	v_mul_f32 v196, v159, v196
	v_add_f32_dpp v188, v188, v188 row_half_mirror row_mask:0xf bank_mask:0x5
	v_add_f32_dpp v188, v192, v192 row_half_mirror row_mask:0xf bank_mask:0xa
	v_mul_f32 v197, v164, v197
	v_mul_f32 v198, v165, v198
	v_add_f32_dpp v188, v188, v188 quad_perm:[1,0,3,2] row_mask:0xf bank_mask:0xf
	v_mul_f32 v199, v167, v199
	v_fma_f32 v196, v208, v204, v196
	v_add_f32_dpp v188, v188, v188 quad_perm:[2,3,0,1] row_mask:0xf bank_mask:0xf
	v_fma_f32 v197, v208, v205, v197
	v_fma_f32 v198, v208, v206, v198
	v_add_f32_dpp v188, v188, v188 row_ror:8 row_mask:0xf bank_mask:0xf
	v_fma_f32 v192, v208, v210, v188
	v_fma_f32 v199, v208, v207, v199
	v_mov_b32_dpp v188, v188 row_half_mirror row_mask:0xf bank_mask:0xa
	v_fma_f32 v159, -v188, v200, v196
	v_fma_f32 v164, -v188, v201, v197
	v_fma_f32 v165, -v188, v202, v198
	v_fma_f32 v167, -v188, v203, v199
	v_fma_f32 v192, -v188, v209, v192
	ds_write_b32 v2, v192 offset:192
	ds_read_b128 v[188:191], v3 offset:7680
	ds_read_b128 v[192:195], v3 offset:7936
	ds_read_b128 v[196:199], v3 offset:8192
	ds_read_b128 v[204:207], v3 offset:8704
	ds_read_b128 v[208:211], v4 offset:7680
	ds_read_b128 v[200:203], v3 offset:8448
	s_waitcnt lgkmcnt(7)
	v_mul_f32 v160, v159, v160
	v_mul_f32 v168, v159, v168
	v_fma_f32 v160, v164, v161, v160
	v_fma_f32 v168, v164, v169, v168
	v_fma_f32 v160, v165, v162, v160
	v_fma_f32 v168, v165, v170, v168
	v_fma_f32 v160, v167, v163, v160
	v_fma_f32 v168, v167, v171, v168
	v_mul_f32 v172, v159, v172
	v_add_f32_dpp v160, v160, v160 row_half_mirror row_mask:0xf bank_mask:0x5
	v_add_f32_dpp v160, v168, v168 row_half_mirror row_mask:0xf bank_mask:0xa
	v_mul_f32 v173, v164, v173
	v_mul_f32 v174, v165, v174
	v_add_f32_dpp v160, v160, v160 quad_perm:[1,0,3,2] row_mask:0xf bank_mask:0xf
	v_mul_f32 v175, v167, v175
	v_fma_f32 v172, v184, v180, v172
	v_add_f32_dpp v160, v160, v160 quad_perm:[2,3,0,1] row_mask:0xf bank_mask:0xf
	v_fma_f32 v173, v184, v181, v173
	v_fma_f32 v174, v184, v182, v174
	v_add_f32_dpp v160, v160, v160 row_ror:8 row_mask:0xf bank_mask:0xf
	v_fma_f32 v168, v184, v186, v160
	v_fma_f32 v175, v184, v183, v175
	v_mov_b32_dpp v160, v160 row_half_mirror row_mask:0xf bank_mask:0xa
	v_fma_f32 v159, -v160, v176, v172
	v_fma_f32 v164, -v160, v177, v173
	v_fma_f32 v165, -v160, v178, v174
	v_fma_f32 v167, -v160, v179, v175
	v_fma_f32 v168, -v160, v185, v168
	ds_write_b32 v2, v168 offset:256
	ds_read_b128 v[160:163], v3 offset:9216
	ds_read_b128 v[168:171], v3 offset:9472
	ds_read_b128 v[172:175], v3 offset:9728
	ds_read_b128 v[180:183], v3 offset:10240
	ds_read_b128 v[184:187], v4 offset:9216
	ds_read_b128 v[176:179], v3 offset:9984
	s_waitcnt lgkmcnt(7)
	v_mul_f32 v188, v159, v188
	v_mul_f32 v192, v159, v192
	v_fma_f32 v188, v164, v189, v188
	v_fma_f32 v192, v164, v193, v192
	v_fma_f32 v188, v165, v190, v188
	v_fma_f32 v192, v165, v194, v192
	v_fma_f32 v188, v167, v191, v188
	v_fma_f32 v192, v167, v195, v192
	v_mul_f32 v196, v159, v196
	v_add_f32_dpp v188, v188, v188 row_half_mirror row_mask:0xf bank_mask:0x5
	v_add_f32_dpp v188, v192, v192 row_half_mirror row_mask:0xf bank_mask:0xa
	v_mul_f32 v197, v164, v197
	v_mul_f32 v198, v165, v198
	v_add_f32_dpp v188, v188, v188 quad_perm:[1,0,3,2] row_mask:0xf bank_mask:0xf
	v_mul_f32 v199, v167, v199
	v_fma_f32 v196, v208, v204, v196
	v_add_f32_dpp v188, v188, v188 quad_perm:[2,3,0,1] row_mask:0xf bank_mask:0xf
	v_fma_f32 v197, v208, v205, v197
	v_fma_f32 v198, v208, v206, v198
	v_add_f32_dpp v188, v188, v188 row_ror:8 row_mask:0xf bank_mask:0xf
	v_fma_f32 v192, v208, v210, v188
	v_fma_f32 v199, v208, v207, v199
	v_mov_b32_dpp v188, v188 row_half_mirror row_mask:0xf bank_mask:0xa
	v_fma_f32 v159, -v188, v200, v196
	v_fma_f32 v164, -v188, v201, v197
	v_fma_f32 v165, -v188, v202, v198
	v_fma_f32 v167, -v188, v203, v199
	v_fma_f32 v192, -v188, v209, v192
	ds_write_b32 v2, v192 offset:320
	ds_read_b128 v[188:191], v3 offset:10752
	ds_read_b128 v[192:195], v3 offset:11008
	ds_read_b128 v[196:199], v3 offset:11264
	ds_read_b128 v[204:207], v3 offset:11776
	ds_read_b128 v[208:211], v4 offset:10752
	ds_read_b128 v[200:203], v3 offset:11520
	s_waitcnt lgkmcnt(7)
	v_mul_f32 v160, v159, v160
	v_mul_f32 v168, v159, v168
	v_fma_f32 v160, v164, v161, v160
	v_fma_f32 v168, v164, v169, v168
	v_fma_f32 v160, v165, v162, v160
	v_fma_f32 v168, v165, v170, v168
	v_fma_f32 v160, v167, v163, v160
	v_fma_f32 v168, v167, v171, v168
	v_mul_f32 v172, v159, v172
	v_add_f32_dpp v160, v160, v160 row_half_mirror row_mask:0xf bank_mask:0x5
	v_add_f32_dpp v160, v168, v168 row_half_mirror row_mask:0xf bank_mask:0xa
	v_mul_f32 v173, v164, v173
	v_mul_f32 v174, v165, v174
	v_add_f32_dpp v160, v160, v160 quad_perm:[1,0,3,2] row_mask:0xf bank_mask:0xf
	v_mul_f32 v175, v167, v175
	v_fma_f32 v172, v184, v180, v172
	v_add_f32_dpp v160, v160, v160 quad_perm:[2,3,0,1] row_mask:0xf bank_mask:0xf
	v_fma_f32 v173, v184, v181, v173
	v_fma_f32 v174, v184, v182, v174
	v_add_f32_dpp v160, v160, v160 row_ror:8 row_mask:0xf bank_mask:0xf
	v_fma_f32 v168, v184, v186, v160
	v_fma_f32 v175, v184, v183, v175
	v_mov_b32_dpp v160, v160 row_half_mirror row_mask:0xf bank_mask:0xa
	v_fma_f32 v159, -v160, v176, v172
	v_fma_f32 v164, -v160, v177, v173
	v_fma_f32 v165, -v160, v178, v174
	v_fma_f32 v167, -v160, v179, v175
	v_fma_f32 v168, -v160, v185, v168
	ds_write_b32 v2, v168 offset:384
	ds_read_b128 v[160:163], v3 offset:12288
	ds_read_b128 v[168:171], v3 offset:12544
	ds_read_b128 v[172:175], v3 offset:12800
	ds_read_b128 v[180:183], v3 offset:13312
	ds_read_b128 v[184:187], v4 offset:12288
	ds_read_b128 v[176:179], v3 offset:13056
	s_waitcnt lgkmcnt(7)
; __device__ __forceinline__ float vfma(float a, float b, float c) { float d; asm("v_fma_f32 %0, %1, %2, %3" : "=v"(d) : "v"(a), "v"(b), "v"(c)); return d; }
; __device__ __forceinline__ float step_compute(float (&S)[4], const StepOp& o) {
;     float d1 = vmul(S[0], o.kk[0]), d2 = vmul(S[0], o.wr[0]), e1 = vmul(S[1], o.kk[1]), e2 = vmul(S[1], o.wr[1]);
;     d1 = vfma(S[2], o.kk[2], d1); d2 = vfma(S[2], o.wr[2], d2); e1 = vfma(S[3], o.kk[3], e1); e2 = vfma(S[3], o.wr[3], e2);
;     d1 = vadd(d1, e1); d2 = vadd(d2, e2);
;     float t0, t1, t2, t3;
;     asm volatile(
;         "v_mul_f32 %[t0], %[s0], %[w0]\n\t"
;         "v_mul_f32 %[t1], %[s1], %[w1]\n\t"
;         "v_add_f32_dpp %[d1], %[d1], %[d1] quad_perm:[1,0,3,2] row_mask:0xf bank_mask:0xf bound_ctrl:1\n\t"
;         "v_add_f32_dpp %[d2], %[d2], %[d2] quad_perm:[1,0,3,2] row_mask:0xf bank_mask:0xf bound_ctrl:1\n\t"
;         "v_mul_f32 %[t2], %[s2], %[w2]\n\t"
;         "v_add_f32_dpp %[d1], %[d1], %[d1] quad_perm:[2,3,0,1] row_mask:0xf bank_mask:0xf bound_ctrl:1\n\t"
;         "v_add_f32_dpp %[d2], %[d2], %[d2] quad_perm:[2,3,0,1] row_mask:0xf bank_mask:0xf bound_ctrl:1\n\t"
;         "v_mul_f32 %[t3], %[s3], %[w3]\n\t"
;         "v_add_f32_dpp %[d1], %[d1], %[d1] row_half_mirror row_mask:0xf bank_mask:0xf bound_ctrl:1\n\t"
;         "v_add_f32_dpp %[d2], %[d2], %[d2] row_half_mirror row_mask:0xf bank_mask:0xf bound_ctrl:1\n\t"
;         "v_fma_f32 %[t0], %[v], %[k0], %[t0]\n\t"
;         "v_add_f32_dpp %[d1], %[d1], %[d1] row_mirror row_mask:0xf bank_mask:0xf bound_ctrl:1\n\t"
;         "v_add_f32_dpp %[d2], %[d2], %[d2] row_mirror row_mask:0xf bank_mask:0xf bound_ctrl:1\n\t"
;         "v_fma_f32 %[t1], %[v], %[k1], %[t1]\n\t"
;         "v_fma_f32 %[t2], %[v], %[k2], %[t2]\n\t"
;         "v_fma_f32 %[t3], %[v], %[k3], %[t3]"
;         : [t0] "=&v"(t0), [t1] "=&v"(t1), [t2] "=&v"(t2), [t3] "=&v"(t3), [d1] "+v"(d1), [d2] "+v"(d2)
;         : [s0] "v"(S[0]), [s1] "v"(S[1]), [s2] "v"(S[2]), [s3] "v"(S[3]), [w0] "v"(o.w[0]), [w1] "v"(o.w[1]), [w2] "v"(o.w[2]), [w3] "v"(o.w[3]),
;           [k0] "v"(o.k[0]), [k1] "v"(o.k[1]), [k2] "v"(o.k[2]), [k3] "v"(o.k[3]), [v] "v"(o.q[0]));
;     S[0] = vnfma(d1, o.b[0], t0); S[1] = vnfma(d1, o.b[1], t1); S[2] = vnfma(d1, o.b[2], t2); S[3] = vnfma(d1, o.b[3], t3);
;     return vfma(o.q[0], o.q[2], vnfma(d1, o.q[1], d2));
	v_mul_f32 v188, v159, v188
	v_mul_f32 v192, v159, v192
	v_fma_f32 v188, v164, v189, v188
	v_fma_f32 v192, v164, v193, v192
	v_fma_f32 v188, v165, v190, v188
	v_fma_f32 v192, v165, v194, v192
	v_fma_f32 v188, v167, v191, v188
	v_fma_f32 v192, v167, v195, v192
	v_mul_f32 v196, v159, v196
	v_add_f32_dpp v188, v188, v188 row_half_mirror row_mask:0xf bank_mask:0x5
	v_add_f32_dpp v188, v192, v192 row_half_mirror row_mask:0xf bank_mask:0xa
	v_mul_f32 v197, v164, v197
	v_mul_f32 v198, v165, v198
	v_add_f32_dpp v188, v188, v188 quad_perm:[1,0,3,2] row_mask:0xf bank_mask:0xf
	v_mul_f32 v199, v167, v199
	v_fma_f32 v196, v208, v204, v196
	v_add_f32_dpp v188, v188, v188 quad_perm:[2,3,0,1] row_mask:0xf bank_mask:0xf
	v_fma_f32 v197, v208, v205, v197
	v_fma_f32 v198, v208, v206, v198
	v_add_f32_dpp v188, v188, v188 row_ror:8 row_mask:0xf bank_mask:0xf
	v_fma_f32 v192, v208, v210, v188
	v_fma_f32 v199, v208, v207, v199
	v_mov_b32_dpp v188, v188 row_half_mirror row_mask:0xf bank_mask:0xa
	v_fma_f32 v159, -v188, v200, v196
	v_fma_f32 v164, -v188, v201, v197
	v_fma_f32 v165, -v188, v202, v198
	v_fma_f32 v167, -v188, v203, v199
	v_fma_f32 v192, -v188, v209, v192
	ds_write_b32 v2, v192 offset:448
	ds_read_b128 v[188:191], v3 offset:13824
	ds_read_b128 v[192:195], v3 offset:14080
	ds_read_b128 v[196:199], v3 offset:14336
	ds_read_b128 v[204:207], v3 offset:14848
	ds_read_b128 v[208:211], v4 offset:13824
	ds_read_b128 v[200:203], v3 offset:14592
	s_waitcnt lgkmcnt(7)
	v_mul_f32 v160, v159, v160
	v_mul_f32 v168, v159, v168
	v_fma_f32 v160, v164, v161, v160
	v_fma_f32 v168, v164, v169, v168
	v_fma_f32 v160, v165, v162, v160
	v_fma_f32 v168, v165, v170, v168
	v_fma_f32 v160, v167, v163, v160
	v_fma_f32 v168, v167, v171, v168
	v_mul_f32 v172, v159, v172
	v_add_f32_dpp v160, v160, v160 row_half_mirror row_mask:0xf bank_mask:0x5
	v_add_f32_dpp v160, v168, v168 row_half_mirror row_mask:0xf bank_mask:0xa
	v_mul_f32 v173, v164, v173
	v_mul_f32 v174, v165, v174
	v_add_f32_dpp v160, v160, v160 quad_perm:[1,0,3,2] row_mask:0xf bank_mask:0xf
	v_mul_f32 v175, v167, v175
	v_fma_f32 v172, v184, v180, v172
	v_add_f32_dpp v160, v160, v160 quad_perm:[2,3,0,1] row_mask:0xf bank_mask:0xf
	v_fma_f32 v173, v184, v181, v173
	v_fma_f32 v174, v184, v182, v174
	v_add_f32_dpp v160, v160, v160 row_ror:8 row_mask:0xf bank_mask:0xf
	v_fma_f32 v168, v184, v186, v160
	v_fma_f32 v175, v184, v183, v175
	v_mov_b32_dpp v160, v160 row_half_mirror row_mask:0xf bank_mask:0xa
	v_fma_f32 v159, -v160, v176, v172
	v_fma_f32 v164, -v160, v177, v173
	v_fma_f32 v165, -v160, v178, v174
	v_fma_f32 v167, -v160, v179, v175
	v_fma_f32 v168, -v160, v185, v168
	ds_write_b32 v2, v168 offset:512
	ds_read_b128 v[160:163], v3 offset:15360
	ds_read_b128 v[168:171], v3 offset:15616
	ds_read_b128 v[172:175], v3 offset:15872
	ds_read_b128 v[180:183], v3 offset:16384
	ds_read_b128 v[184:187], v4 offset:15360
	ds_read_b128 v[176:179], v3 offset:16128
	s_waitcnt lgkmcnt(7)
	v_mul_f32 v188, v159, v188
	v_mul_f32 v192, v159, v192
	v_fma_f32 v188, v164, v189, v188
	v_fma_f32 v192, v164, v193, v192
	v_fma_f32 v188, v165, v190, v188
	v_fma_f32 v192, v165, v194, v192
	v_fma_f32 v188, v167, v191, v188
	v_fma_f32 v192, v167, v195, v192
	v_mul_f32 v196, v159, v196
	v_add_f32_dpp v188, v188, v188 row_half_mirror row_mask:0xf bank_mask:0x5
	v_add_f32_dpp v188, v192, v192 row_half_mirror row_mask:0xf bank_mask:0xa
	v_mul_f32 v197, v164, v197
	v_mul_f32 v198, v165, v198
	v_add_f32_dpp v188, v188, v188 quad_perm:[1,0,3,2] row_mask:0xf bank_mask:0xf
	v_mul_f32 v199, v167, v199
	v_fma_f32 v196, v208, v204, v196
	v_add_f32_dpp v188, v188, v188 quad_perm:[2,3,0,1] row_mask:0xf bank_mask:0xf
	v_fma_f32 v197, v208, v205, v197
	v_fma_f32 v198, v208, v206, v198
	v_add_f32_dpp v188, v188, v188 row_ror:8 row_mask:0xf bank_mask:0xf
	v_fma_f32 v192, v208, v210, v188
	v_fma_f32 v199, v208, v207, v199
	v_mov_b32_dpp v188, v188 row_half_mirror row_mask:0xf bank_mask:0xa
	v_fma_f32 v159, -v188, v200, v196
	v_fma_f32 v164, -v188, v201, v197
	v_fma_f32 v165, -v188, v202, v198
	v_fma_f32 v167, -v188, v203, v199
	v_fma_f32 v192, -v188, v209, v192
	ds_write_b32 v2, v192 offset:576
	ds_read_b128 v[188:191], v3 offset:16896
	ds_read_b128 v[192:195], v3 offset:17152
	ds_read_b128 v[196:199], v3 offset:17408
	ds_read_b128 v[204:207], v3 offset:17920
	ds_read_b128 v[208:211], v4 offset:16896
	ds_read_b128 v[200:203], v3 offset:17664
	s_waitcnt lgkmcnt(7)
	v_mul_f32 v160, v159, v160
	v_mul_f32 v168, v159, v168
	v_fma_f32 v160, v164, v161, v160
	v_fma_f32 v168, v164, v169, v168
	v_fma_f32 v160, v165, v162, v160
	v_fma_f32 v168, v165, v170, v168
	v_fma_f32 v160, v167, v163, v160
	v_fma_f32 v168, v167, v171, v168
	v_mul_f32 v172, v159, v172
	v_add_f32_dpp v160, v160, v160 row_half_mirror row_mask:0xf bank_mask:0x5
	v_add_f32_dpp v160, v168, v168 row_half_mirror row_mask:0xf bank_mask:0xa
	v_mul_f32 v173, v164, v173
	v_mul_f32 v174, v165, v174
	v_add_f32_dpp v160, v160, v160 quad_perm:[1,0,3,2] row_mask:0xf bank_mask:0xf
	v_mul_f32 v175, v167, v175
	v_fma_f32 v172, v184, v180, v172
	v_add_f32_dpp v160, v160, v160 quad_perm:[2,3,0,1] row_mask:0xf bank_mask:0xf
	v_fma_f32 v173, v184, v181, v173
	v_fma_f32 v174, v184, v182, v174
	v_add_f32_dpp v160, v160, v160 row_ror:8 row_mask:0xf bank_mask:0xf
	v_fma_f32 v168, v184, v186, v160
	v_fma_f32 v175, v184, v183, v175
	v_mov_b32_dpp v160, v160 row_half_mirror row_mask:0xf bank_mask:0xa
	v_fma_f32 v159, -v160, v176, v172
	v_fma_f32 v164, -v160, v177, v173
	v_fma_f32 v165, -v160, v178, v174
	v_fma_f32 v167, -v160, v179, v175
	v_fma_f32 v168, -v160, v185, v168
	ds_write_b32 v2, v168 offset:640
	ds_read_b128 v[160:163], v3 offset:18432
	ds_read_b128 v[168:171], v3 offset:18688
	ds_read_b128 v[172:175], v3 offset:18944
	ds_read_b128 v[180:183], v3 offset:19456
	ds_read_b128 v[184:187], v4 offset:18432
	ds_read_b128 v[176:179], v3 offset:19200
	s_waitcnt lgkmcnt(7)
; __device__ __forceinline__ float vfma(float a, float b, float c) { float d; asm("v_fma_f32 %0, %1, %2, %3" : "=v"(d) : "v"(a), "v"(b), "v"(c)); return d; }
; __device__ __forceinline__ float step_compute(float (&S)[4], const StepOp& o) {
;     float d1 = vmul(S[0], o.kk[0]), d2 = vmul(S[0], o.wr[0]), e1 = vmul(S[1], o.kk[1]), e2 = vmul(S[1], o.wr[1]);
;     d1 = vfma(S[2], o.kk[2], d1); d2 = vfma(S[2], o.wr[2], d2); e1 = vfma(S[3], o.kk[3], e1); e2 = vfma(S[3], o.wr[3], e2);
;     d1 = vadd(d1, e1); d2 = vadd(d2, e2);
;     float t0, t1, t2, t3;
;     asm volatile(
;         "v_mul_f32 %[t0], %[s0], %[w0]\n\t"
;         "v_mul_f32 %[t1], %[s1], %[w1]\n\t"
;         "v_add_f32_dpp %[d1], %[d1], %[d1] quad_perm:[1,0,3,2] row_mask:0xf bank_mask:0xf bound_ctrl:1\n\t"
;         "v_add_f32_dpp %[d2], %[d2], %[d2] quad_perm:[1,0,3,2] row_mask:0xf bank_mask:0xf bound_ctrl:1\n\t"
;         "v_mul_f32 %[t2], %[s2], %[w2]\n\t"
;         "v_add_f32_dpp %[d1], %[d1], %[d1] quad_perm:[2,3,0,1] row_mask:0xf bank_mask:0xf bound_ctrl:1\n\t"
;         "v_add_f32_dpp %[d2], %[d2], %[d2] quad_perm:[2,3,0,1] row_mask:0xf bank_mask:0xf bound_ctrl:1\n\t"
;         "v_mul_f32 %[t3], %[s3], %[w3]\n\t"
;         "v_add_f32_dpp %[d1], %[d1], %[d1] row_half_mirror row_mask:0xf bank_mask:0xf bound_ctrl:1\n\t"
;         "v_add_f32_dpp %[d2], %[d2], %[d2] row_half_mirror row_mask:0xf bank_mask:0xf bound_ctrl:1\n\t"
;         "v_fma_f32 %[t0], %[v], %[k0], %[t0]\n\t"
;         "v_add_f32_dpp %[d1], %[d1], %[d1] row_mirror row_mask:0xf bank_mask:0xf bound_ctrl:1\n\t"
;         "v_add_f32_dpp %[d2], %[d2], %[d2] row_mirror row_mask:0xf bank_mask:0xf bound_ctrl:1\n\t"
;         "v_fma_f32 %[t1], %[v], %[k1], %[t1]\n\t"
;         "v_fma_f32 %[t2], %[v], %[k2], %[t2]\n\t"
;         "v_fma_f32 %[t3], %[v], %[k3], %[t3]"
;         : [t0] "=&v"(t0), [t1] "=&v"(t1), [t2] "=&v"(t2), [t3] "=&v"(t3), [d1] "+v"(d1), [d2] "+v"(d2)
;         : [s0] "v"(S[0]), [s1] "v"(S[1]), [s2] "v"(S[2]), [s3] "v"(S[3]), [w0] "v"(o.w[0]), [w1] "v"(o.w[1]), [w2] "v"(o.w[2]), [w3] "v"(o.w[3]),
;           [k0] "v"(o.k[0]), [k1] "v"(o.k[1]), [k2] "v"(o.k[2]), [k3] "v"(o.k[3]), [v] "v"(o.q[0]));
;     S[0] = vnfma(d1, o.b[0], t0); S[1] = vnfma(d1, o.b[1], t1); S[2] = vnfma(d1, o.b[2], t2); S[3] = vnfma(d1, o.b[3], t3);
;     return vfma(o.q[0], o.q[2], vnfma(d1, o.q[1], d2));
	v_mul_f32 v188, v159, v188
	v_mul_f32 v192, v159, v192
	v_fma_f32 v188, v164, v189, v188
	v_fma_f32 v192, v164, v193, v192
	v_fma_f32 v188, v165, v190, v188
	v_fma_f32 v192, v165, v194, v192
	v_fma_f32 v188, v167, v191, v188
	v_fma_f32 v192, v167, v195, v192
	v_mul_f32 v196, v159, v196
	v_add_f32_dpp v188, v188, v188 row_half_mirror row_mask:0xf bank_mask:0x5
	v_add_f32_dpp v188, v192, v192 row_half_mirror row_mask:0xf bank_mask:0xa
	v_mul_f32 v197, v164, v197
	v_mul_f32 v198, v165, v198
	v_add_f32_dpp v188, v188, v188 quad_perm:[1,0,3,2] row_mask:0xf bank_mask:0xf
	v_mul_f32 v199, v167, v199
	v_fma_f32 v196, v208, v204, v196
	v_add_f32_dpp v188, v188, v188 quad_perm:[2,3,0,1] row_mask:0xf bank_mask:0xf
	v_fma_f32 v197, v208, v205, v197
	v_fma_f32 v198, v208, v206, v198
	v_add_f32_dpp v188, v188, v188 row_ror:8 row_mask:0xf bank_mask:0xf
	v_fma_f32 v192, v208, v210, v188
	v_fma_f32 v199, v208, v207, v199
	v_mov_b32_dpp v188, v188 row_half_mirror row_mask:0xf bank_mask:0xa
	v_fma_f32 v159, -v188, v200, v196
	v_fma_f32 v164, -v188, v201, v197
	v_fma_f32 v165, -v188, v202, v198
	v_fma_f32 v167, -v188, v203, v199
	v_fma_f32 v192, -v188, v209, v192
	ds_write_b32 v2, v192 offset:704
	ds_read_b128 v[188:191], v3 offset:19968
	ds_read_b128 v[192:195], v3 offset:20224
	ds_read_b128 v[196:199], v3 offset:20480
	ds_read_b128 v[204:207], v3 offset:20992
	ds_read_b128 v[208:211], v4 offset:19968
	ds_read_b128 v[200:203], v3 offset:20736
	s_waitcnt lgkmcnt(7)
	v_mul_f32 v160, v159, v160
	v_mul_f32 v168, v159, v168
	v_fma_f32 v160, v164, v161, v160
	v_fma_f32 v168, v164, v169, v168
	v_fma_f32 v160, v165, v162, v160
	v_fma_f32 v168, v165, v170, v168
	v_fma_f32 v160, v167, v163, v160
	v_fma_f32 v168, v167, v171, v168
	v_mul_f32 v172, v159, v172
	v_add_f32_dpp v160, v160, v160 row_half_mirror row_mask:0xf bank_mask:0x5
	v_add_f32_dpp v160, v168, v168 row_half_mirror row_mask:0xf bank_mask:0xa
	v_mul_f32 v173, v164, v173
	v_mul_f32 v174, v165, v174
	v_add_f32_dpp v160, v160, v160 quad_perm:[1,0,3,2] row_mask:0xf bank_mask:0xf
	v_mul_f32 v175, v167, v175
	v_fma_f32 v172, v184, v180, v172
	v_add_f32_dpp v160, v160, v160 quad_perm:[2,3,0,1] row_mask:0xf bank_mask:0xf
	v_fma_f32 v173, v184, v181, v173
	v_fma_f32 v174, v184, v182, v174
	v_add_f32_dpp v160, v160, v160 row_ror:8 row_mask:0xf bank_mask:0xf
	v_fma_f32 v168, v184, v186, v160
	v_fma_f32 v175, v184, v183, v175
	v_mov_b32_dpp v160, v160 row_half_mirror row_mask:0xf bank_mask:0xa
	v_fma_f32 v159, -v160, v176, v172
	v_fma_f32 v164, -v160, v177, v173
	v_fma_f32 v165, -v160, v178, v174
	v_fma_f32 v167, -v160, v179, v175
	v_fma_f32 v168, -v160, v185, v168
	ds_write_b32 v2, v168 offset:768
	ds_read_b128 v[160:163], v3 offset:21504
	ds_read_b128 v[168:171], v3 offset:21760
	ds_read_b128 v[172:175], v3 offset:22016
	ds_read_b128 v[180:183], v3 offset:22528
	ds_read_b128 v[184:187], v4 offset:21504
	ds_read_b128 v[176:179], v3 offset:22272
	s_waitcnt lgkmcnt(7)
	v_mul_f32 v188, v159, v188
	v_mul_f32 v192, v159, v192
	v_fma_f32 v188, v164, v189, v188
	v_fma_f32 v192, v164, v193, v192
	v_fma_f32 v188, v165, v190, v188
	v_fma_f32 v192, v165, v194, v192
	v_fma_f32 v188, v167, v191, v188
	v_fma_f32 v192, v167, v195, v192
	v_mul_f32 v196, v159, v196
	v_add_f32_dpp v188, v188, v188 row_half_mirror row_mask:0xf bank_mask:0x5
	v_add_f32_dpp v188, v192, v192 row_half_mirror row_mask:0xf bank_mask:0xa
	v_mul_f32 v197, v164, v197
	v_mul_f32 v198, v165, v198
	v_add_f32_dpp v188, v188, v188 quad_perm:[1,0,3,2] row_mask:0xf bank_mask:0xf
	v_mul_f32 v199, v167, v199
	v_fma_f32 v196, v208, v204, v196
	v_add_f32_dpp v188, v188, v188 quad_perm:[2,3,0,1] row_mask:0xf bank_mask:0xf
	v_fma_f32 v197, v208, v205, v197
	v_fma_f32 v198, v208, v206, v198
	v_add_f32_dpp v188, v188, v188 row_ror:8 row_mask:0xf bank_mask:0xf
	v_fma_f32 v192, v208, v210, v188
	v_fma_f32 v199, v208, v207, v199
	v_mov_b32_dpp v188, v188 row_half_mirror row_mask:0xf bank_mask:0xa
	v_fma_f32 v159, -v188, v200, v196
	v_fma_f32 v164, -v188, v201, v197
	v_fma_f32 v165, -v188, v202, v198
	v_fma_f32 v167, -v188, v203, v199
	v_fma_f32 v192, -v188, v209, v192
	ds_write_b32 v2, v192 offset:832
	ds_read_b128 v[188:191], v3 offset:23040
	ds_read_b128 v[192:195], v3 offset:23296
	ds_read_b128 v[196:199], v3 offset:23552
	ds_read_b128 v[204:207], v3 offset:24064
	ds_read_b128 v[208:211], v4 offset:23040
	ds_read_b128 v[200:203], v3 offset:23808
	s_waitcnt lgkmcnt(7)
	v_mul_f32 v160, v159, v160
	v_mul_f32 v168, v159, v168
	v_fma_f32 v160, v164, v161, v160
	v_fma_f32 v168, v164, v169, v168
	v_fma_f32 v160, v165, v162, v160
	v_fma_f32 v168, v165, v170, v168
	v_fma_f32 v160, v167, v163, v160
	v_fma_f32 v168, v167, v171, v168
	v_mul_f32 v172, v159, v172
	v_add_f32_dpp v160, v160, v160 row_half_mirror row_mask:0xf bank_mask:0x5
	v_add_f32_dpp v160, v168, v168 row_half_mirror row_mask:0xf bank_mask:0xa
	v_mul_f32 v173, v164, v173
	v_mul_f32 v174, v165, v174
	v_add_f32_dpp v160, v160, v160 quad_perm:[1,0,3,2] row_mask:0xf bank_mask:0xf
	v_mul_f32 v175, v167, v175
	v_fma_f32 v172, v184, v180, v172
	v_add_f32_dpp v160, v160, v160 quad_perm:[2,3,0,1] row_mask:0xf bank_mask:0xf
	v_fma_f32 v173, v184, v181, v173
	v_fma_f32 v174, v184, v182, v174
	v_add_f32_dpp v160, v160, v160 row_ror:8 row_mask:0xf bank_mask:0xf
	v_fma_f32 v168, v184, v186, v160
	v_fma_f32 v175, v184, v183, v175
	v_mov_b32_dpp v160, v160 row_half_mirror row_mask:0xf bank_mask:0xa
	v_fma_f32 v159, -v160, v176, v172
	v_fma_f32 v164, -v160, v177, v173
	v_fma_f32 v165, -v160, v178, v174
	v_fma_f32 v167, -v160, v179, v175
	v_fma_f32 v168, -v160, v185, v168
	ds_write_b32 v2, v168 offset:896
	ds_read_b128 v[160:163], v3 offset:24576
	ds_read_b128 v[168:171], v3 offset:24832
	ds_read_b128 v[172:175], v3 offset:25088
	ds_read_b128 v[180:183], v3 offset:25600
	ds_read_b128 v[184:187], v4 offset:24576
	ds_read_b128 v[176:179], v3 offset:25344
	s_waitcnt lgkmcnt(7)
; __device__ __forceinline__ float vfma(float a, float b, float c) { float d; asm("v_fma_f32 %0, %1, %2, %3" : "=v"(d) : "v"(a), "v"(b), "v"(c)); return d; }
; __device__ __forceinline__ float step_compute(float (&S)[4], const StepOp& o) {
;     float d1 = vmul(S[0], o.kk[0]), d2 = vmul(S[0], o.wr[0]), e1 = vmul(S[1], o.kk[1]), e2 = vmul(S[1], o.wr[1]);
;     d1 = vfma(S[2], o.kk[2], d1); d2 = vfma(S[2], o.wr[2], d2); e1 = vfma(S[3], o.kk[3], e1); e2 = vfma(S[3], o.wr[3], e2);
;     d1 = vadd(d1, e1); d2 = vadd(d2, e2);
;     float t0, t1, t2, t3;
;     asm volatile(
;         "v_mul_f32 %[t0], %[s0], %[w0]\n\t"
;         "v_mul_f32 %[t1], %[s1], %[w1]\n\t"
;         "v_add_f32_dpp %[d1], %[d1], %[d1] quad_perm:[1,0,3,2] row_mask:0xf bank_mask:0xf bound_ctrl:1\n\t"
;         "v_add_f32_dpp %[d2], %[d2], %[d2] quad_perm:[1,0,3,2] row_mask:0xf bank_mask:0xf bound_ctrl:1\n\t"
;         "v_mul_f32 %[t2], %[s2], %[w2]\n\t"
;         "v_add_f32_dpp %[d1], %[d1], %[d1] quad_perm:[2,3,0,1] row_mask:0xf bank_mask:0xf bound_ctrl:1\n\t"
;         "v_add_f32_dpp %[d2], %[d2], %[d2] quad_perm:[2,3,0,1] row_mask:0xf bank_mask:0xf bound_ctrl:1\n\t"
;         "v_mul_f32 %[t3], %[s3], %[w3]\n\t"
;         "v_add_f32_dpp %[d1], %[d1], %[d1] row_half_mirror row_mask:0xf bank_mask:0xf bound_ctrl:1\n\t"
;         "v_add_f32_dpp %[d2], %[d2], %[d2] row_half_mirror row_mask:0xf bank_mask:0xf bound_ctrl:1\n\t"
;         "v_fma_f32 %[t0], %[v], %[k0], %[t0]\n\t"
;         "v_add_f32_dpp %[d1], %[d1], %[d1] row_mirror row_mask:0xf bank_mask:0xf bound_ctrl:1\n\t"
;         "v_add_f32_dpp %[d2], %[d2], %[d2] row_mirror row_mask:0xf bank_mask:0xf bound_ctrl:1\n\t"
;         "v_fma_f32 %[t1], %[v], %[k1], %[t1]\n\t"
;         "v_fma_f32 %[t2], %[v], %[k2], %[t2]\n\t"
;         "v_fma_f32 %[t3], %[v], %[k3], %[t3]"
;         : [t0] "=&v"(t0), [t1] "=&v"(t1), [t2] "=&v"(t2), [t3] "=&v"(t3), [d1] "+v"(d1), [d2] "+v"(d2)
;         : [s0] "v"(S[0]), [s1] "v"(S[1]), [s2] "v"(S[2]), [s3] "v"(S[3]), [w0] "v"(o.w[0]), [w1] "v"(o.w[1]), [w2] "v"(o.w[2]), [w3] "v"(o.w[3]),
;           [k0] "v"(o.k[0]), [k1] "v"(o.k[1]), [k2] "v"(o.k[2]), [k3] "v"(o.k[3]), [v] "v"(o.q[0]));
;     S[0] = vnfma(d1, o.b[0], t0); S[1] = vnfma(d1, o.b[1], t1); S[2] = vnfma(d1, o.b[2], t2); S[3] = vnfma(d1, o.b[3], t3);
;     return vfma(o.q[0], o.q[2], vnfma(d1, o.q[1], d2));
	v_mul_f32 v188, v159, v188
	v_mul_f32 v192, v159, v192
	v_fma_f32 v188, v164, v189, v188
	v_fma_f32 v192, v164, v193, v192
	v_fma_f32 v188, v165, v190, v188
	v_fma_f32 v192, v165, v194, v192
	v_fma_f32 v188, v167, v191, v188
	v_fma_f32 v192, v167, v195, v192
	v_mul_f32 v196, v159, v196
	v_add_f32_dpp v188, v188, v188 row_half_mirror row_mask:0xf bank_mask:0x5
	v_add_f32_dpp v188, v192, v192 row_half_mirror row_mask:0xf bank_mask:0xa
	v_mul_f32 v197, v164, v197
	v_mul_f32 v198, v165, v198
	v_add_f32_dpp v188, v188, v188 quad_perm:[1,0,3,2] row_mask:0xf bank_mask:0xf
	v_mul_f32 v199, v167, v199
	v_fma_f32 v196, v208, v204, v196
	v_add_f32_dpp v188, v188, v188 quad_perm:[2,3,0,1] row_mask:0xf bank_mask:0xf
	v_fma_f32 v197, v208, v205, v197
	v_fma_f32 v198, v208, v206, v198
	v_add_f32_dpp v188, v188, v188 row_ror:8 row_mask:0xf bank_mask:0xf
	v_fma_f32 v192, v208, v210, v188
	v_fma_f32 v199, v208, v207, v199
	v_mov_b32_dpp v188, v188 row_half_mirror row_mask:0xf bank_mask:0xa
	v_fma_f32 v159, -v188, v200, v196
	v_fma_f32 v164, -v188, v201, v197
	v_fma_f32 v165, -v188, v202, v198
	v_fma_f32 v167, -v188, v203, v199
	v_fma_f32 v192, -v188, v209, v192
	ds_write_b32 v2, v192 offset:960
	ds_read_b128 v[188:191], v3 offset:26112
	ds_read_b128 v[192:195], v3 offset:26368
	ds_read_b128 v[196:199], v3 offset:26624
	ds_read_b128 v[204:207], v3 offset:27136
	ds_read_b128 v[208:211], v4 offset:26112
	ds_read_b128 v[200:203], v3 offset:26880
	s_waitcnt lgkmcnt(7)
	v_mul_f32 v160, v159, v160
	v_mul_f32 v168, v159, v168
	v_fma_f32 v160, v164, v161, v160
	v_fma_f32 v168, v164, v169, v168
	v_fma_f32 v160, v165, v162, v160
	v_fma_f32 v168, v165, v170, v168
	v_fma_f32 v160, v167, v163, v160
	v_fma_f32 v168, v167, v171, v168
	v_mul_f32 v172, v159, v172
	v_add_f32_dpp v160, v160, v160 row_half_mirror row_mask:0xf bank_mask:0x5
	v_add_f32_dpp v160, v168, v168 row_half_mirror row_mask:0xf bank_mask:0xa
	v_mul_f32 v173, v164, v173
	v_mul_f32 v174, v165, v174
	v_add_f32_dpp v160, v160, v160 quad_perm:[1,0,3,2] row_mask:0xf bank_mask:0xf
	v_mul_f32 v175, v167, v175
	v_fma_f32 v172, v184, v180, v172
	v_add_f32_dpp v160, v160, v160 quad_perm:[2,3,0,1] row_mask:0xf bank_mask:0xf
	v_fma_f32 v173, v184, v181, v173
	v_fma_f32 v174, v184, v182, v174
	v_add_f32_dpp v160, v160, v160 row_ror:8 row_mask:0xf bank_mask:0xf
	v_fma_f32 v168, v184, v186, v160
	v_fma_f32 v175, v184, v183, v175
	v_mov_b32_dpp v160, v160 row_half_mirror row_mask:0xf bank_mask:0xa
	v_fma_f32 v159, -v160, v176, v172
	v_fma_f32 v164, -v160, v177, v173
	v_fma_f32 v165, -v160, v178, v174
	v_fma_f32 v167, -v160, v179, v175
	v_fma_f32 v168, -v160, v185, v168
	ds_write_b32 v2, v168 offset:1024
	ds_read_b128 v[160:163], v3 offset:27648
	ds_read_b128 v[168:171], v3 offset:27904
	ds_read_b128 v[172:175], v3 offset:28160
	ds_read_b128 v[180:183], v3 offset:28672
	ds_read_b128 v[184:187], v4 offset:27648
	ds_read_b128 v[176:179], v3 offset:28416
	s_waitcnt lgkmcnt(7)
	v_mul_f32 v188, v159, v188
	v_mul_f32 v192, v159, v192
	v_fma_f32 v188, v164, v189, v188
	v_fma_f32 v192, v164, v193, v192
	v_fma_f32 v188, v165, v190, v188
	v_fma_f32 v192, v165, v194, v192
	v_fma_f32 v188, v167, v191, v188
	v_fma_f32 v192, v167, v195, v192
	v_mul_f32 v196, v159, v196
	v_add_f32_dpp v188, v188, v188 row_half_mirror row_mask:0xf bank_mask:0x5
	v_add_f32_dpp v188, v192, v192 row_half_mirror row_mask:0xf bank_mask:0xa
	v_mul_f32 v197, v164, v197
	v_mul_f32 v198, v165, v198
	v_add_f32_dpp v188, v188, v188 quad_perm:[1,0,3,2] row_mask:0xf bank_mask:0xf
	v_mul_f32 v199, v167, v199
	v_fma_f32 v196, v208, v204, v196
	v_add_f32_dpp v188, v188, v188 quad_perm:[2,3,0,1] row_mask:0xf bank_mask:0xf
	v_fma_f32 v197, v208, v205, v197
	v_fma_f32 v198, v208, v206, v198
	v_add_f32_dpp v188, v188, v188 row_ror:8 row_mask:0xf bank_mask:0xf
	v_fma_f32 v192, v208, v210, v188
	v_fma_f32 v199, v208, v207, v199
	v_mov_b32_dpp v188, v188 row_half_mirror row_mask:0xf bank_mask:0xa
	v_fma_f32 v159, -v188, v200, v196
	v_fma_f32 v164, -v188, v201, v197
	v_fma_f32 v165, -v188, v202, v198
	v_fma_f32 v167, -v188, v203, v199
	v_fma_f32 v192, -v188, v209, v192
	ds_write_b32 v2, v192 offset:1088
	ds_read_b128 v[188:191], v3 offset:29184
	ds_read_b128 v[192:195], v3 offset:29440
	ds_read_b128 v[196:199], v3 offset:29696
	ds_read_b128 v[204:207], v3 offset:30208
	ds_read_b128 v[208:211], v4 offset:29184
	ds_read_b128 v[200:203], v3 offset:29952
	s_waitcnt lgkmcnt(7)
	v_mul_f32 v160, v159, v160
	v_mul_f32 v168, v159, v168
	v_fma_f32 v160, v164, v161, v160
	v_fma_f32 v168, v164, v169, v168
	v_fma_f32 v160, v165, v162, v160
	v_fma_f32 v168, v165, v170, v168
	v_fma_f32 v160, v167, v163, v160
	v_fma_f32 v168, v167, v171, v168
	v_mul_f32 v172, v159, v172
	v_add_f32_dpp v160, v160, v160 row_half_mirror row_mask:0xf bank_mask:0x5
	v_add_f32_dpp v160, v168, v168 row_half_mirror row_mask:0xf bank_mask:0xa
	v_mul_f32 v173, v164, v173
	v_mul_f32 v174, v165, v174
	v_add_f32_dpp v160, v160, v160 quad_perm:[1,0,3,2] row_mask:0xf bank_mask:0xf
	v_mul_f32 v175, v167, v175
	v_fma_f32 v172, v184, v180, v172
	v_add_f32_dpp v160, v160, v160 quad_perm:[2,3,0,1] row_mask:0xf bank_mask:0xf
	v_fma_f32 v173, v184, v181, v173
	v_fma_f32 v174, v184, v182, v174
	v_add_f32_dpp v160, v160, v160 row_ror:8 row_mask:0xf bank_mask:0xf
	v_fma_f32 v168, v184, v186, v160
	v_fma_f32 v175, v184, v183, v175
	v_mov_b32_dpp v160, v160 row_half_mirror row_mask:0xf bank_mask:0xa
	v_fma_f32 v159, -v160, v176, v172
	v_fma_f32 v164, -v160, v177, v173
	v_fma_f32 v165, -v160, v178, v174
	v_fma_f32 v167, -v160, v179, v175
	v_fma_f32 v168, -v160, v185, v168
	ds_write_b32 v2, v168 offset:1152
	ds_read_b128 v[160:163], v3 offset:30720
	ds_read_b128 v[168:171], v3 offset:30976
	ds_read_b128 v[172:175], v3 offset:31232
	ds_read_b128 v[180:183], v3 offset:31744
	ds_read_b128 v[184:187], v4 offset:30720
	ds_read_b128 v[176:179], v3 offset:31488
	s_waitcnt lgkmcnt(7)
; __device__ __forceinline__ float vfma(float a, float b, float c) { float d; asm("v_fma_f32 %0, %1, %2, %3" : "=v"(d) : "v"(a), "v"(b), "v"(c)); return d; }
; __device__ __forceinline__ float step_compute(float (&S)[4], const StepOp& o) {
;     float d1 = vmul(S[0], o.kk[0]), d2 = vmul(S[0], o.wr[0]), e1 = vmul(S[1], o.kk[1]), e2 = vmul(S[1], o.wr[1]);
;     d1 = vfma(S[2], o.kk[2], d1); d2 = vfma(S[2], o.wr[2], d2); e1 = vfma(S[3], o.kk[3], e1); e2 = vfma(S[3], o.wr[3], e2);
;     d1 = vadd(d1, e1); d2 = vadd(d2, e2);
;     float t0, t1, t2, t3;
;     asm volatile(
;         "v_mul_f32 %[t0], %[s0], %[w0]\n\t"
;         "v_mul_f32 %[t1], %[s1], %[w1]\n\t"
;         "v_add_f32_dpp %[d1], %[d1], %[d1] quad_perm:[1,0,3,2] row_mask:0xf bank_mask:0xf bound_ctrl:1\n\t"
;         "v_add_f32_dpp %[d2], %[d2], %[d2] quad_perm:[1,0,3,2] row_mask:0xf bank_mask:0xf bound_ctrl:1\n\t"
;         "v_mul_f32 %[t2], %[s2], %[w2]\n\t"
;         "v_add_f32_dpp %[d1], %[d1], %[d1] quad_perm:[2,3,0,1] row_mask:0xf bank_mask:0xf bound_ctrl:1\n\t"
;         "v_add_f32_dpp %[d2], %[d2], %[d2] quad_perm:[2,3,0,1] row_mask:0xf bank_mask:0xf bound_ctrl:1\n\t"
;         "v_mul_f32 %[t3], %[s3], %[w3]\n\t"
;         "v_add_f32_dpp %[d1], %[d1], %[d1] row_half_mirror row_mask:0xf bank_mask:0xf bound_ctrl:1\n\t"
;         "v_add_f32_dpp %[d2], %[d2], %[d2] row_half_mirror row_mask:0xf bank_mask:0xf bound_ctrl:1\n\t"
;         "v_fma_f32 %[t0], %[v], %[k0], %[t0]\n\t"
;         "v_add_f32_dpp %[d1], %[d1], %[d1] row_mirror row_mask:0xf bank_mask:0xf bound_ctrl:1\n\t"
;         "v_add_f32_dpp %[d2], %[d2], %[d2] row_mirror row_mask:0xf bank_mask:0xf bound_ctrl:1\n\t"
;         "v_fma_f32 %[t1], %[v], %[k1], %[t1]\n\t"
;         "v_fma_f32 %[t2], %[v], %[k2], %[t2]\n\t"
;         "v_fma_f32 %[t3], %[v], %[k3], %[t3]"
;         : [t0] "=&v"(t0), [t1] "=&v"(t1), [t2] "=&v"(t2), [t3] "=&v"(t3), [d1] "+v"(d1), [d2] "+v"(d2)
;         : [s0] "v"(S[0]), [s1] "v"(S[1]), [s2] "v"(S[2]), [s3] "v"(S[3]), [w0] "v"(o.w[0]), [w1] "v"(o.w[1]), [w2] "v"(o.w[2]), [w3] "v"(o.w[3]),
;           [k0] "v"(o.k[0]), [k1] "v"(o.k[1]), [k2] "v"(o.k[2]), [k3] "v"(o.k[3]), [v] "v"(o.q[0]));
;     S[0] = vnfma(d1, o.b[0], t0); S[1] = vnfma(d1, o.b[1], t1); S[2] = vnfma(d1, o.b[2], t2); S[3] = vnfma(d1, o.b[3], t3);
;     return vfma(o.q[0], o.q[2], vnfma(d1, o.q[1], d2));
	v_mul_f32 v188, v159, v188
	v_mul_f32 v192, v159, v192
	v_fma_f32 v188, v164, v189, v188
	v_fma_f32 v192, v164, v193, v192
	v_fma_f32 v188, v165, v190, v188
	v_fma_f32 v192, v165, v194, v192
	v_fma_f32 v188, v167, v191, v188
	v_fma_f32 v192, v167, v195, v192
	v_mul_f32 v196, v159, v196
	v_add_f32_dpp v188, v188, v188 row_half_mirror row_mask:0xf bank_mask:0x5
	v_add_f32_dpp v188, v192, v192 row_half_mirror row_mask:0xf bank_mask:0xa
	v_mul_f32 v197, v164, v197
	v_mul_f32 v198, v165, v198
	v_add_f32_dpp v188, v188, v188 quad_perm:[1,0,3,2] row_mask:0xf bank_mask:0xf
	v_mul_f32 v199, v167, v199
	v_fma_f32 v196, v208, v204, v196
	v_add_f32_dpp v188, v188, v188 quad_perm:[2,3,0,1] row_mask:0xf bank_mask:0xf
	v_fma_f32 v197, v208, v205, v197
	v_fma_f32 v198, v208, v206, v198
	v_add_f32_dpp v188, v188, v188 row_ror:8 row_mask:0xf bank_mask:0xf
	v_fma_f32 v192, v208, v210, v188
	v_fma_f32 v199, v208, v207, v199
	v_mov_b32_dpp v188, v188 row_half_mirror row_mask:0xf bank_mask:0xa
	v_fma_f32 v159, -v188, v200, v196
	v_fma_f32 v164, -v188, v201, v197
	v_fma_f32 v165, -v188, v202, v198
	v_fma_f32 v167, -v188, v203, v199
	v_fma_f32 v192, -v188, v209, v192
	ds_write_b32 v2, v192 offset:1216
	ds_read_b128 v[188:191], v3 offset:32256
	ds_read_b128 v[192:195], v3 offset:32512
	ds_read_b128 v[196:199], v3 offset:32768
	ds_read_b128 v[204:207], v3 offset:33280
	ds_read_b128 v[208:211], v4 offset:32256
	ds_read_b128 v[200:203], v3 offset:33024
	s_waitcnt lgkmcnt(7)
	v_mul_f32 v160, v159, v160
	v_mul_f32 v168, v159, v168
	v_fma_f32 v160, v164, v161, v160
	v_fma_f32 v168, v164, v169, v168
	v_fma_f32 v160, v165, v162, v160
	v_fma_f32 v168, v165, v170, v168
	v_fma_f32 v160, v167, v163, v160
	v_fma_f32 v168, v167, v171, v168
	v_mul_f32 v172, v159, v172
	v_add_f32_dpp v160, v160, v160 row_half_mirror row_mask:0xf bank_mask:0x5
	v_add_f32_dpp v160, v168, v168 row_half_mirror row_mask:0xf bank_mask:0xa
	v_mul_f32 v173, v164, v173
	v_mul_f32 v174, v165, v174
	v_add_f32_dpp v160, v160, v160 quad_perm:[1,0,3,2] row_mask:0xf bank_mask:0xf
	v_mul_f32 v175, v167, v175
	v_fma_f32 v172, v184, v180, v172
	v_add_f32_dpp v160, v160, v160 quad_perm:[2,3,0,1] row_mask:0xf bank_mask:0xf
	v_fma_f32 v173, v184, v181, v173
	v_fma_f32 v174, v184, v182, v174
	v_add_f32_dpp v160, v160, v160 row_ror:8 row_mask:0xf bank_mask:0xf
	v_fma_f32 v168, v184, v186, v160
	v_fma_f32 v175, v184, v183, v175
	v_mov_b32_dpp v160, v160 row_half_mirror row_mask:0xf bank_mask:0xa
	v_fma_f32 v159, -v160, v176, v172
	v_fma_f32 v164, -v160, v177, v173
	v_fma_f32 v165, -v160, v178, v174
	v_fma_f32 v167, -v160, v179, v175
	v_fma_f32 v168, -v160, v185, v168
	ds_write_b32 v2, v168 offset:1280
	ds_read_b128 v[160:163], v3 offset:33792
	ds_read_b128 v[168:171], v3 offset:34048
	ds_read_b128 v[172:175], v3 offset:34304
	ds_read_b128 v[180:183], v3 offset:34816
	ds_read_b128 v[184:187], v4 offset:33792
	ds_read_b128 v[176:179], v3 offset:34560
	s_waitcnt lgkmcnt(7)
	v_mul_f32 v188, v159, v188
	v_mul_f32 v192, v159, v192
	v_fma_f32 v188, v164, v189, v188
	v_fma_f32 v192, v164, v193, v192
	v_fma_f32 v188, v165, v190, v188
	v_fma_f32 v192, v165, v194, v192
	v_fma_f32 v188, v167, v191, v188
	v_fma_f32 v192, v167, v195, v192
	v_mul_f32 v196, v159, v196
	v_add_f32_dpp v188, v188, v188 row_half_mirror row_mask:0xf bank_mask:0x5
	v_add_f32_dpp v188, v192, v192 row_half_mirror row_mask:0xf bank_mask:0xa
	v_mul_f32 v197, v164, v197
	v_mul_f32 v198, v165, v198
	v_add_f32_dpp v188, v188, v188 quad_perm:[1,0,3,2] row_mask:0xf bank_mask:0xf
	v_mul_f32 v199, v167, v199
	v_fma_f32 v196, v208, v204, v196
	v_add_f32_dpp v188, v188, v188 quad_perm:[2,3,0,1] row_mask:0xf bank_mask:0xf
	v_fma_f32 v197, v208, v205, v197
	v_fma_f32 v198, v208, v206, v198
	v_add_f32_dpp v188, v188, v188 row_ror:8 row_mask:0xf bank_mask:0xf
	v_fma_f32 v192, v208, v210, v188
	v_fma_f32 v199, v208, v207, v199
	v_mov_b32_dpp v188, v188 row_half_mirror row_mask:0xf bank_mask:0xa
	v_fma_f32 v159, -v188, v200, v196
	v_fma_f32 v164, -v188, v201, v197
	v_fma_f32 v165, -v188, v202, v198
	v_fma_f32 v167, -v188, v203, v199
	v_fma_f32 v192, -v188, v209, v192
	ds_write_b32 v2, v192 offset:1344
	ds_read_b128 v[188:191], v3 offset:35328
	ds_read_b128 v[192:195], v3 offset:35584
	ds_read_b128 v[196:199], v3 offset:35840
	ds_read_b128 v[204:207], v3 offset:36352
	ds_read_b128 v[208:211], v4 offset:35328
	ds_read_b128 v[200:203], v3 offset:36096
	s_waitcnt lgkmcnt(7)
	v_mul_f32 v160, v159, v160
	v_mul_f32 v168, v159, v168
	v_fma_f32 v160, v164, v161, v160
	v_fma_f32 v168, v164, v169, v168
	v_fma_f32 v160, v165, v162, v160
	v_fma_f32 v168, v165, v170, v168
	v_fma_f32 v160, v167, v163, v160
	v_fma_f32 v168, v167, v171, v168
	v_mul_f32 v172, v159, v172
	v_add_f32_dpp v160, v160, v160 row_half_mirror row_mask:0xf bank_mask:0x5
	v_add_f32_dpp v160, v168, v168 row_half_mirror row_mask:0xf bank_mask:0xa
	v_mul_f32 v173, v164, v173
	v_mul_f32 v174, v165, v174
	v_add_f32_dpp v160, v160, v160 quad_perm:[1,0,3,2] row_mask:0xf bank_mask:0xf
	v_mul_f32 v175, v167, v175
	v_fma_f32 v172, v184, v180, v172
	v_add_f32_dpp v160, v160, v160 quad_perm:[2,3,0,1] row_mask:0xf bank_mask:0xf
	v_fma_f32 v173, v184, v181, v173
	v_fma_f32 v174, v184, v182, v174
	v_add_f32_dpp v160, v160, v160 row_ror:8 row_mask:0xf bank_mask:0xf
	v_fma_f32 v168, v184, v186, v160
	v_fma_f32 v175, v184, v183, v175
	v_mov_b32_dpp v160, v160 row_half_mirror row_mask:0xf bank_mask:0xa
	v_fma_f32 v159, -v160, v176, v172
	v_fma_f32 v164, -v160, v177, v173
	v_fma_f32 v165, -v160, v178, v174
	v_fma_f32 v167, -v160, v179, v175
	v_fma_f32 v168, -v160, v185, v168
	ds_write_b32 v2, v168 offset:1408
	ds_read_b128 v[160:163], v3 offset:36864
	ds_read_b128 v[168:171], v3 offset:37120
	ds_read_b128 v[172:175], v3 offset:37376
	ds_read_b128 v[180:183], v3 offset:37888
	ds_read_b128 v[184:187], v4 offset:36864
	ds_read_b128 v[176:179], v3 offset:37632
	s_waitcnt lgkmcnt(7)
; __device__ __forceinline__ float vfma(float a, float b, float c) { float d; asm("v_fma_f32 %0, %1, %2, %3" : "=v"(d) : "v"(a), "v"(b), "v"(c)); return d; }
; __device__ __forceinline__ float step_compute(float (&S)[4], const StepOp& o) {
;     float d1 = vmul(S[0], o.kk[0]), d2 = vmul(S[0], o.wr[0]), e1 = vmul(S[1], o.kk[1]), e2 = vmul(S[1], o.wr[1]);
;     d1 = vfma(S[2], o.kk[2], d1); d2 = vfma(S[2], o.wr[2], d2); e1 = vfma(S[3], o.kk[3], e1); e2 = vfma(S[3], o.wr[3], e2);
;     d1 = vadd(d1, e1); d2 = vadd(d2, e2);
;     float t0, t1, t2, t3;
;     asm volatile(
;         "v_mul_f32 %[t0], %[s0], %[w0]\n\t"
;         "v_mul_f32 %[t1], %[s1], %[w1]\n\t"
;         "v_add_f32_dpp %[d1], %[d1], %[d1] quad_perm:[1,0,3,2] row_mask:0xf bank_mask:0xf bound_ctrl:1\n\t"
;         "v_add_f32_dpp %[d2], %[d2], %[d2] quad_perm:[1,0,3,2] row_mask:0xf bank_mask:0xf bound_ctrl:1\n\t"
;         "v_mul_f32 %[t2], %[s2], %[w2]\n\t"
;         "v_add_f32_dpp %[d1], %[d1], %[d1] quad_perm:[2,3,0,1] row_mask:0xf bank_mask:0xf bound_ctrl:1\n\t"
;         "v_add_f32_dpp %[d2], %[d2], %[d2] quad_perm:[2,3,0,1] row_mask:0xf bank_mask:0xf bound_ctrl:1\n\t"
;         "v_mul_f32 %[t3], %[s3], %[w3]\n\t"
;         "v_add_f32_dpp %[d1], %[d1], %[d1] row_half_mirror row_mask:0xf bank_mask:0xf bound_ctrl:1\n\t"
;         "v_add_f32_dpp %[d2], %[d2], %[d2] row_half_mirror row_mask:0xf bank_mask:0xf bound_ctrl:1\n\t"
;         "v_fma_f32 %[t0], %[v], %[k0], %[t0]\n\t"
;         "v_add_f32_dpp %[d1], %[d1], %[d1] row_mirror row_mask:0xf bank_mask:0xf bound_ctrl:1\n\t"
;         "v_add_f32_dpp %[d2], %[d2], %[d2] row_mirror row_mask:0xf bank_mask:0xf bound_ctrl:1\n\t"
;         "v_fma_f32 %[t1], %[v], %[k1], %[t1]\n\t"
;         "v_fma_f32 %[t2], %[v], %[k2], %[t2]\n\t"
;         "v_fma_f32 %[t3], %[v], %[k3], %[t3]"
;         : [t0] "=&v"(t0), [t1] "=&v"(t1), [t2] "=&v"(t2), [t3] "=&v"(t3), [d1] "+v"(d1), [d2] "+v"(d2)
;         : [s0] "v"(S[0]), [s1] "v"(S[1]), [s2] "v"(S[2]), [s3] "v"(S[3]), [w0] "v"(o.w[0]), [w1] "v"(o.w[1]), [w2] "v"(o.w[2]), [w3] "v"(o.w[3]),
;           [k0] "v"(o.k[0]), [k1] "v"(o.k[1]), [k2] "v"(o.k[2]), [k3] "v"(o.k[3]), [v] "v"(o.q[0]));
;     S[0] = vnfma(d1, o.b[0], t0); S[1] = vnfma(d1, o.b[1], t1); S[2] = vnfma(d1, o.b[2], t2); S[3] = vnfma(d1, o.b[3], t3);
;     return vfma(o.q[0], o.q[2], vnfma(d1, o.q[1], d2));
	v_mul_f32 v188, v159, v188
	v_mul_f32 v192, v159, v192
	v_fma_f32 v188, v164, v189, v188
	v_fma_f32 v192, v164, v193, v192
	v_fma_f32 v188, v165, v190, v188
	v_fma_f32 v192, v165, v194, v192
	v_fma_f32 v188, v167, v191, v188
	v_fma_f32 v192, v167, v195, v192
	v_mul_f32 v196, v159, v196
	v_add_f32_dpp v188, v188, v188 row_half_mirror row_mask:0xf bank_mask:0x5
	v_add_f32_dpp v188, v192, v192 row_half_mirror row_mask:0xf bank_mask:0xa
	v_mul_f32 v197, v164, v197
	v_mul_f32 v198, v165, v198
	v_add_f32_dpp v188, v188, v188 quad_perm:[1,0,3,2] row_mask:0xf bank_mask:0xf
	v_mul_f32 v199, v167, v199
	v_fma_f32 v196, v208, v204, v196
	v_add_f32_dpp v188, v188, v188 quad_perm:[2,3,0,1] row_mask:0xf bank_mask:0xf
	v_fma_f32 v197, v208, v205, v197
	v_fma_f32 v198, v208, v206, v198
	v_add_f32_dpp v188, v188, v188 row_ror:8 row_mask:0xf bank_mask:0xf
	v_fma_f32 v192, v208, v210, v188
	v_fma_f32 v199, v208, v207, v199
	v_mov_b32_dpp v188, v188 row_half_mirror row_mask:0xf bank_mask:0xa
	v_fma_f32 v159, -v188, v200, v196
	v_fma_f32 v164, -v188, v201, v197
	v_fma_f32 v165, -v188, v202, v198
	v_fma_f32 v167, -v188, v203, v199
	v_fma_f32 v192, -v188, v209, v192
	ds_write_b32 v2, v192 offset:1472
	ds_read_b128 v[188:191], v3 offset:38400
	ds_read_b128 v[192:195], v3 offset:38656
	ds_read_b128 v[196:199], v3 offset:38912
	ds_read_b128 v[204:207], v3 offset:39424
	ds_read_b128 v[208:211], v4 offset:38400
	ds_read_b128 v[200:203], v3 offset:39168
	s_waitcnt lgkmcnt(7)
	v_mul_f32 v160, v159, v160
	v_mul_f32 v168, v159, v168
	v_fma_f32 v160, v164, v161, v160
	v_fma_f32 v168, v164, v169, v168
	v_fma_f32 v160, v165, v162, v160
	v_fma_f32 v168, v165, v170, v168
	v_fma_f32 v160, v167, v163, v160
	v_fma_f32 v168, v167, v171, v168
	v_mul_f32 v172, v159, v172
	v_add_f32_dpp v160, v160, v160 row_half_mirror row_mask:0xf bank_mask:0x5
	v_add_f32_dpp v160, v168, v168 row_half_mirror row_mask:0xf bank_mask:0xa
	v_mul_f32 v173, v164, v173
	v_mul_f32 v174, v165, v174
	v_add_f32_dpp v160, v160, v160 quad_perm:[1,0,3,2] row_mask:0xf bank_mask:0xf
	v_mul_f32 v175, v167, v175
	v_fma_f32 v172, v184, v180, v172
	v_add_f32_dpp v160, v160, v160 quad_perm:[2,3,0,1] row_mask:0xf bank_mask:0xf
	v_fma_f32 v173, v184, v181, v173
	v_fma_f32 v174, v184, v182, v174
	v_add_f32_dpp v160, v160, v160 row_ror:8 row_mask:0xf bank_mask:0xf
	v_fma_f32 v168, v184, v186, v160
	v_fma_f32 v175, v184, v183, v175
	v_mov_b32_dpp v160, v160 row_half_mirror row_mask:0xf bank_mask:0xa
	v_fma_f32 v159, -v160, v176, v172
	v_fma_f32 v164, -v160, v177, v173
	v_fma_f32 v165, -v160, v178, v174
	v_fma_f32 v167, -v160, v179, v175
	v_fma_f32 v168, -v160, v185, v168
	ds_write_b32 v2, v168 offset:1536
	ds_read_b128 v[160:163], v3 offset:39936
	ds_read_b128 v[168:171], v3 offset:40192
	ds_read_b128 v[172:175], v3 offset:40448
	ds_read_b128 v[180:183], v3 offset:40960
	ds_read_b128 v[184:187], v4 offset:39936
	ds_read_b128 v[176:179], v3 offset:40704
	s_waitcnt lgkmcnt(7)
	v_mul_f32 v188, v159, v188
	v_mul_f32 v192, v159, v192
	v_fma_f32 v188, v164, v189, v188
	v_fma_f32 v192, v164, v193, v192
	v_fma_f32 v188, v165, v190, v188
	v_fma_f32 v192, v165, v194, v192
	v_fma_f32 v188, v167, v191, v188
	v_fma_f32 v192, v167, v195, v192
	v_mul_f32 v196, v159, v196
	v_add_f32_dpp v188, v188, v188 row_half_mirror row_mask:0xf bank_mask:0x5
	v_add_f32_dpp v188, v192, v192 row_half_mirror row_mask:0xf bank_mask:0xa
	v_mul_f32 v197, v164, v197
	v_mul_f32 v198, v165, v198
	v_add_f32_dpp v188, v188, v188 quad_perm:[1,0,3,2] row_mask:0xf bank_mask:0xf
	v_mul_f32 v199, v167, v199
	v_fma_f32 v196, v208, v204, v196
	v_add_f32_dpp v188, v188, v188 quad_perm:[2,3,0,1] row_mask:0xf bank_mask:0xf
	v_fma_f32 v197, v208, v205, v197
	v_fma_f32 v198, v208, v206, v198
	v_add_f32_dpp v188, v188, v188 row_ror:8 row_mask:0xf bank_mask:0xf
	v_fma_f32 v192, v208, v210, v188
	v_fma_f32 v199, v208, v207, v199
	v_mov_b32_dpp v188, v188 row_half_mirror row_mask:0xf bank_mask:0xa
	v_fma_f32 v159, -v188, v200, v196
	v_fma_f32 v164, -v188, v201, v197
	v_fma_f32 v165, -v188, v202, v198
	v_fma_f32 v167, -v188, v203, v199
	v_fma_f32 v192, -v188, v209, v192
	ds_write_b32 v2, v192 offset:1600
	ds_read_b128 v[188:191], v3 offset:41472
	ds_read_b128 v[192:195], v3 offset:41728
	ds_read_b128 v[196:199], v3 offset:41984
	ds_read_b128 v[204:207], v3 offset:42496
	ds_read_b128 v[208:211], v4 offset:41472
	ds_read_b128 v[200:203], v3 offset:42240
	s_waitcnt lgkmcnt(7)
	v_mul_f32 v160, v159, v160
	v_mul_f32 v168, v159, v168
	v_fma_f32 v160, v164, v161, v160
	v_fma_f32 v168, v164, v169, v168
	v_fma_f32 v160, v165, v162, v160
	v_fma_f32 v168, v165, v170, v168
	v_fma_f32 v160, v167, v163, v160
	v_fma_f32 v168, v167, v171, v168
	v_mul_f32 v172, v159, v172
	v_add_f32_dpp v160, v160, v160 row_half_mirror row_mask:0xf bank_mask:0x5
	v_add_f32_dpp v160, v168, v168 row_half_mirror row_mask:0xf bank_mask:0xa
	v_mul_f32 v173, v164, v173
	v_mul_f32 v174, v165, v174
	v_add_f32_dpp v160, v160, v160 quad_perm:[1,0,3,2] row_mask:0xf bank_mask:0xf
	v_mul_f32 v175, v167, v175
	v_fma_f32 v172, v184, v180, v172
	v_add_f32_dpp v160, v160, v160 quad_perm:[2,3,0,1] row_mask:0xf bank_mask:0xf
	v_fma_f32 v173, v184, v181, v173
	v_fma_f32 v174, v184, v182, v174
	v_add_f32_dpp v160, v160, v160 row_ror:8 row_mask:0xf bank_mask:0xf
	v_fma_f32 v168, v184, v186, v160
	v_fma_f32 v175, v184, v183, v175
	v_mov_b32_dpp v160, v160 row_half_mirror row_mask:0xf bank_mask:0xa
	v_fma_f32 v159, -v160, v176, v172
	v_fma_f32 v164, -v160, v177, v173
	v_fma_f32 v165, -v160, v178, v174
	v_fma_f32 v167, -v160, v179, v175
	v_fma_f32 v168, -v160, v185, v168
	ds_write_b32 v2, v168 offset:1664
	ds_read_b128 v[160:163], v3 offset:43008
	ds_read_b128 v[168:171], v3 offset:43264
	ds_read_b128 v[172:175], v3 offset:43520
	ds_read_b128 v[180:183], v3 offset:44032
	ds_read_b128 v[184:187], v4 offset:43008
	ds_read_b128 v[176:179], v3 offset:43776
	s_waitcnt lgkmcnt(7)
; __device__ __forceinline__ float vfma(float a, float b, float c) { float d; asm("v_fma_f32 %0, %1, %2, %3" : "=v"(d) : "v"(a), "v"(b), "v"(c)); return d; }
; __device__ __forceinline__ float step_compute(float (&S)[4], const StepOp& o) {
;     float d1 = vmul(S[0], o.kk[0]), d2 = vmul(S[0], o.wr[0]), e1 = vmul(S[1], o.kk[1]), e2 = vmul(S[1], o.wr[1]);
;     d1 = vfma(S[2], o.kk[2], d1); d2 = vfma(S[2], o.wr[2], d2); e1 = vfma(S[3], o.kk[3], e1); e2 = vfma(S[3], o.wr[3], e2);
;     d1 = vadd(d1, e1); d2 = vadd(d2, e2);
;     float t0, t1, t2, t3;
;     asm volatile(
;         "v_mul_f32 %[t0], %[s0], %[w0]\n\t"
;         "v_mul_f32 %[t1], %[s1], %[w1]\n\t"
;         "v_add_f32_dpp %[d1], %[d1], %[d1] quad_perm:[1,0,3,2] row_mask:0xf bank_mask:0xf bound_ctrl:1\n\t"
;         "v_add_f32_dpp %[d2], %[d2], %[d2] quad_perm:[1,0,3,2] row_mask:0xf bank_mask:0xf bound_ctrl:1\n\t"
;         "v_mul_f32 %[t2], %[s2], %[w2]\n\t"
;         "v_add_f32_dpp %[d1], %[d1], %[d1] quad_perm:[2,3,0,1] row_mask:0xf bank_mask:0xf bound_ctrl:1\n\t"
;         "v_add_f32_dpp %[d2], %[d2], %[d2] quad_perm:[2,3,0,1] row_mask:0xf bank_mask:0xf bound_ctrl:1\n\t"
;         "v_mul_f32 %[t3], %[s3], %[w3]\n\t"
;         "v_add_f32_dpp %[d1], %[d1], %[d1] row_half_mirror row_mask:0xf bank_mask:0xf bound_ctrl:1\n\t"
;         "v_add_f32_dpp %[d2], %[d2], %[d2] row_half_mirror row_mask:0xf bank_mask:0xf bound_ctrl:1\n\t"
;         "v_fma_f32 %[t0], %[v], %[k0], %[t0]\n\t"
;         "v_add_f32_dpp %[d1], %[d1], %[d1] row_mirror row_mask:0xf bank_mask:0xf bound_ctrl:1\n\t"
;         "v_add_f32_dpp %[d2], %[d2], %[d2] row_mirror row_mask:0xf bank_mask:0xf bound_ctrl:1\n\t"
;         "v_fma_f32 %[t1], %[v], %[k1], %[t1]\n\t"
;         "v_fma_f32 %[t2], %[v], %[k2], %[t2]\n\t"
;         "v_fma_f32 %[t3], %[v], %[k3], %[t3]"
;         : [t0] "=&v"(t0), [t1] "=&v"(t1), [t2] "=&v"(t2), [t3] "=&v"(t3), [d1] "+v"(d1), [d2] "+v"(d2)
;         : [s0] "v"(S[0]), [s1] "v"(S[1]), [s2] "v"(S[2]), [s3] "v"(S[3]), [w0] "v"(o.w[0]), [w1] "v"(o.w[1]), [w2] "v"(o.w[2]), [w3] "v"(o.w[3]),
;           [k0] "v"(o.k[0]), [k1] "v"(o.k[1]), [k2] "v"(o.k[2]), [k3] "v"(o.k[3]), [v] "v"(o.q[0]));
;     S[0] = vnfma(d1, o.b[0], t0); S[1] = vnfma(d1, o.b[1], t1); S[2] = vnfma(d1, o.b[2], t2); S[3] = vnfma(d1, o.b[3], t3);
;     return vfma(o.q[0], o.q[2], vnfma(d1, o.q[1], d2));
	v_mul_f32 v188, v159, v188
	v_mul_f32 v192, v159, v192
	v_fma_f32 v188, v164, v189, v188
	v_fma_f32 v192, v164, v193, v192
	v_fma_f32 v188, v165, v190, v188
	v_fma_f32 v192, v165, v194, v192
	v_fma_f32 v188, v167, v191, v188
	v_fma_f32 v192, v167, v195, v192
	v_mul_f32 v196, v159, v196
	v_add_f32_dpp v188, v188, v188 row_half_mirror row_mask:0xf bank_mask:0x5
	v_add_f32_dpp v188, v192, v192 row_half_mirror row_mask:0xf bank_mask:0xa
	v_mul_f32 v197, v164, v197
	v_mul_f32 v198, v165, v198
	v_add_f32_dpp v188, v188, v188 quad_perm:[1,0,3,2] row_mask:0xf bank_mask:0xf
	v_mul_f32 v199, v167, v199
	v_fma_f32 v196, v208, v204, v196
	v_add_f32_dpp v188, v188, v188 quad_perm:[2,3,0,1] row_mask:0xf bank_mask:0xf
	v_fma_f32 v197, v208, v205, v197
	v_fma_f32 v198, v208, v206, v198
	v_add_f32_dpp v188, v188, v188 row_ror:8 row_mask:0xf bank_mask:0xf
	v_fma_f32 v192, v208, v210, v188
	v_fma_f32 v199, v208, v207, v199
	v_mov_b32_dpp v188, v188 row_half_mirror row_mask:0xf bank_mask:0xa
	v_fma_f32 v159, -v188, v200, v196
	v_fma_f32 v164, -v188, v201, v197
	v_fma_f32 v165, -v188, v202, v198
	v_fma_f32 v167, -v188, v203, v199
	v_fma_f32 v192, -v188, v209, v192
	ds_write_b32 v2, v192 offset:1728
	ds_read_b128 v[188:191], v3 offset:44544
	ds_read_b128 v[192:195], v3 offset:44800
	ds_read_b128 v[196:199], v3 offset:45056
	ds_read_b128 v[204:207], v3 offset:45568
	ds_read_b128 v[208:211], v4 offset:44544
	ds_read_b128 v[200:203], v3 offset:45312
	s_waitcnt lgkmcnt(7)
	v_mul_f32 v160, v159, v160
	v_mul_f32 v168, v159, v168
	v_fma_f32 v160, v164, v161, v160
	v_fma_f32 v168, v164, v169, v168
	v_fma_f32 v160, v165, v162, v160
	v_fma_f32 v168, v165, v170, v168
	v_fma_f32 v160, v167, v163, v160
	v_fma_f32 v168, v167, v171, v168
	v_mul_f32 v172, v159, v172
	v_add_f32_dpp v160, v160, v160 row_half_mirror row_mask:0xf bank_mask:0x5
	v_add_f32_dpp v160, v168, v168 row_half_mirror row_mask:0xf bank_mask:0xa
	v_mul_f32 v173, v164, v173
	v_mul_f32 v174, v165, v174
	v_add_f32_dpp v160, v160, v160 quad_perm:[1,0,3,2] row_mask:0xf bank_mask:0xf
	v_mul_f32 v175, v167, v175
	v_fma_f32 v172, v184, v180, v172
	v_add_f32_dpp v160, v160, v160 quad_perm:[2,3,0,1] row_mask:0xf bank_mask:0xf
	v_fma_f32 v173, v184, v181, v173
	v_fma_f32 v174, v184, v182, v174
	v_add_f32_dpp v160, v160, v160 row_ror:8 row_mask:0xf bank_mask:0xf
	v_fma_f32 v168, v184, v186, v160
	v_fma_f32 v175, v184, v183, v175
	v_mov_b32_dpp v160, v160 row_half_mirror row_mask:0xf bank_mask:0xa
	v_fma_f32 v159, -v160, v176, v172
	v_fma_f32 v164, -v160, v177, v173
	v_fma_f32 v165, -v160, v178, v174
	v_fma_f32 v167, -v160, v179, v175
	v_fma_f32 v168, -v160, v185, v168
	ds_write_b32 v2, v168 offset:1792
	ds_read_b128 v[160:163], v3 offset:46080
	ds_read_b128 v[168:171], v3 offset:46336
	ds_read_b128 v[172:175], v3 offset:46592
	ds_read_b128 v[180:183], v3 offset:47104
	ds_read_b128 v[184:187], v4 offset:46080
	ds_read_b128 v[176:179], v3 offset:46848
	s_waitcnt lgkmcnt(7)
	v_mul_f32 v188, v159, v188
	v_mul_f32 v192, v159, v192
	v_fma_f32 v188, v164, v189, v188
	v_fma_f32 v192, v164, v193, v192
	v_fma_f32 v188, v165, v190, v188
	v_fma_f32 v192, v165, v194, v192
	v_fma_f32 v188, v167, v191, v188
	v_fma_f32 v192, v167, v195, v192
	v_mul_f32 v196, v159, v196
	v_add_f32_dpp v188, v188, v188 row_half_mirror row_mask:0xf bank_mask:0x5
	v_add_f32_dpp v188, v192, v192 row_half_mirror row_mask:0xf bank_mask:0xa
	v_mul_f32 v197, v164, v197
	v_mul_f32 v198, v165, v198
	v_add_f32_dpp v188, v188, v188 quad_perm:[1,0,3,2] row_mask:0xf bank_mask:0xf
	v_mul_f32 v199, v167, v199
	v_fma_f32 v196, v208, v204, v196
	v_add_f32_dpp v188, v188, v188 quad_perm:[2,3,0,1] row_mask:0xf bank_mask:0xf
	v_fma_f32 v197, v208, v205, v197
	v_fma_f32 v198, v208, v206, v198
	v_add_f32_dpp v188, v188, v188 row_ror:8 row_mask:0xf bank_mask:0xf
	v_fma_f32 v192, v208, v210, v188
	v_fma_f32 v199, v208, v207, v199
	v_mov_b32_dpp v188, v188 row_half_mirror row_mask:0xf bank_mask:0xa
	v_fma_f32 v159, -v188, v200, v196
	v_fma_f32 v164, -v188, v201, v197
	v_fma_f32 v165, -v188, v202, v198
	v_fma_f32 v167, -v188, v203, v199
	v_fma_f32 v192, -v188, v209, v192
	ds_write_b32 v2, v192 offset:1856
	ds_read_b128 v[188:191], v3 offset:47616
	ds_read_b128 v[192:195], v3 offset:47872
	ds_read_b128 v[196:199], v3 offset:48128
	ds_read_b128 v[204:207], v3 offset:48640
	ds_read_b128 v[208:211], v4 offset:47616
	ds_read_b128 v[200:203], v3 offset:48384
	s_waitcnt lgkmcnt(7)
	v_mul_f32 v160, v159, v160
	v_mul_f32 v168, v159, v168
	v_fma_f32 v160, v164, v161, v160
	v_fma_f32 v168, v164, v169, v168
	v_fma_f32 v160, v165, v162, v160
	v_fma_f32 v168, v165, v170, v168
	v_fma_f32 v160, v167, v163, v160
	v_fma_f32 v168, v167, v171, v168
	v_mul_f32 v172, v159, v172
	v_add_f32_dpp v160, v160, v160 row_half_mirror row_mask:0xf bank_mask:0x5
	v_add_f32_dpp v160, v168, v168 row_half_mirror row_mask:0xf bank_mask:0xa
	v_mul_f32 v173, v164, v173
	v_mul_f32 v174, v165, v174
	v_add_f32_dpp v160, v160, v160 quad_perm:[1,0,3,2] row_mask:0xf bank_mask:0xf
	v_mul_f32 v175, v167, v175
	v_fma_f32 v172, v184, v180, v172
	v_add_f32_dpp v160, v160, v160 quad_perm:[2,3,0,1] row_mask:0xf bank_mask:0xf
	v_fma_f32 v173, v184, v181, v173
	v_fma_f32 v174, v184, v182, v174
	v_add_f32_dpp v160, v160, v160 row_ror:8 row_mask:0xf bank_mask:0xf
	v_fma_f32 v168, v184, v186, v160
	v_fma_f32 v175, v184, v183, v175
	v_mov_b32_dpp v160, v160 row_half_mirror row_mask:0xf bank_mask:0xa
	v_fma_f32 v159, -v160, v176, v172
	v_fma_f32 v164, -v160, v177, v173
	v_fma_f32 v165, -v160, v178, v174
	v_fma_f32 v167, -v160, v179, v175
	v_fma_f32 v168, -v160, v185, v168
	ds_write_b32 v2, v168 offset:1920
	s_waitcnt lgkmcnt(1)
	v_mul_f32 v188, v159, v188
	v_mul_f32 v192, v159, v192
	v_fma_f32 v188, v164, v189, v188
	v_fma_f32 v192, v164, v193, v192
	v_fma_f32 v188, v165, v190, v188
	v_fma_f32 v192, v165, v194, v192
	v_fma_f32 v188, v167, v191, v188
	v_fma_f32 v192, v167, v195, v192
	v_mul_f32 v196, v159, v196
	v_add_f32_dpp v188, v188, v188 row_half_mirror row_mask:0xf bank_mask:0x5
	v_add_f32_dpp v188, v192, v192 row_half_mirror row_mask:0xf bank_mask:0xa
	v_mul_f32 v197, v164, v197
	v_mul_f32 v198, v165, v198
	v_add_f32_dpp v188, v188, v188 quad_perm:[1,0,3,2] row_mask:0xf bank_mask:0xf
	v_mul_f32 v199, v167, v199
	v_fma_f32 v196, v208, v204, v196
	v_add_f32_dpp v188, v188, v188 quad_perm:[2,3,0,1] row_mask:0xf bank_mask:0xf
	v_fma_f32 v197, v208, v205, v197
	v_fma_f32 v198, v208, v206, v198
	v_add_f32_dpp v188, v188, v188 row_ror:8 row_mask:0xf bank_mask:0xf
	v_fma_f32 v192, v208, v210, v188
	v_fma_f32 v199, v208, v207, v199
	v_mov_b32_dpp v188, v188 row_half_mirror row_mask:0xf bank_mask:0xa
	v_fma_f32 v3, -v188, v200, v196
	v_fma_f32 v4, -v188, v201, v197
	v_fma_f32 v115, -v188, v202, v198
	v_fma_f32 v129, -v188, v203, v199
	v_fma_f32 v192, -v188, v209, v192
	ds_write_b32 v2, v192 offset:1984

; __device__ __forceinline__ float vfma(float a, float b, float c) { float d; asm("v_fma_f32 %0, %1, %2, %3" : "=v"(d) : "v"(a), "v"(b), "v"(c)); return d; }
; __device__ __forceinline__ float step_compute(float (&S)[4], const StepOp& o) {
;     float d1 = vmul(S[0], o.kk[0]), d2 = vmul(S[0], o.wr[0]), e1 = vmul(S[1], o.kk[1]), e2 = vmul(S[1], o.wr[1]);
;     d1 = vfma(S[2], o.kk[2], d1); d2 = vfma(S[2], o.wr[2], d2); e1 = vfma(S[3], o.kk[3], e1); e2 = vfma(S[3], o.wr[3], e2);
;     d1 = vadd(d1, e1); d2 = vadd(d2, e2);
;     float t0, t1, t2, t3;
;     asm volatile(
;         "v_mul_f32 %[t0], %[s0], %[w0]\n\t"
;         "v_mul_f32 %[t1], %[s1], %[w1]\n\t"
;         "v_add_f32_dpp %[d1], %[d1], %[d1] quad_perm:[1,0,3,2] row_mask:0xf bank_mask:0xf bound_ctrl:1\n\t"
;         "v_add_f32_dpp %[d2], %[d2], %[d2] quad_perm:[1,0,3,2] row_mask:0xf bank_mask:0xf bound_ctrl:1\n\t"
;         "v_mul_f32 %[t2], %[s2], %[w2]\n\t"
;         "v_add_f32_dpp %[d1], %[d1], %[d1] quad_perm:[2,3,0,1] row_mask:0xf bank_mask:0xf bound_ctrl:1\n\t"
;         "v_add_f32_dpp %[d2], %[d2], %[d2] quad_perm:[2,3,0,1] row_mask:0xf bank_mask:0xf bound_ctrl:1\n\t"
;         "v_mul_f32 %[t3], %[s3], %[w3]\n\t"
;         "v_add_f32_dpp %[d1], %[d1], %[d1] row_half_mirror row_mask:0xf bank_mask:0xf bound_ctrl:1\n\t"
;         "v_add_f32_dpp %[d2], %[d2], %[d2] row_half_mirror row_mask:0xf bank_mask:0xf bound_ctrl:1\n\t"
;         "v_fma_f32 %[t0], %[v], %[k0], %[t0]\n\t"
;         "v_add_f32_dpp %[d1], %[d1], %[d1] row_mirror row_mask:0xf bank_mask:0xf bound_ctrl:1\n\t"
;         "v_add_f32_dpp %[d2], %[d2], %[d2] row_mirror row_mask:0xf bank_mask:0xf bound_ctrl:1\n\t"
;         "v_fma_f32 %[t1], %[v], %[k1], %[t1]\n\t"
;         "v_fma_f32 %[t2], %[v], %[k2], %[t2]\n\t"
;         "v_fma_f32 %[t3], %[v], %[k3], %[t3]"
;         : [t0] "=&v"(t0), [t1] "=&v"(t1), [t2] "=&v"(t2), [t3] "=&v"(t3), [d1] "+v"(d1), [d2] "+v"(d2)
;         : [s0] "v"(S[0]), [s1] "v"(S[1]), [s2] "v"(S[2]), [s3] "v"(S[3]), [w0] "v"(o.w[0]), [w1] "v"(o.w[1]), [w2] "v"(o.w[2]), [w3] "v"(o.w[3]),
;           [k0] "v"(o.k[0]), [k1] "v"(o.k[1]), [k2] "v"(o.k[2]), [k3] "v"(o.k[3]), [v] "v"(o.q[0]));
;     S[0] = vnfma(d1, o.b[0], t0); S[1] = vnfma(d1, o.b[1], t1); S[2] = vnfma(d1, o.b[2], t2); S[3] = vnfma(d1, o.b[3], t3);
;     return vfma(o.q[0], o.q[2], vnfma(d1, o.q[1], d2));
.LBB0_818:
	s_and_b32 s43, s18, 1
	s_cmp_eq_u32 s43, 0
	s_cselect_b64 s[30:31], -1, 0
	s_and_b64 vcc, exec, s[6:7]
	s_mov_b64 s[76:77], -1
	s_cbranch_vccnz .LBB0_820
	s_and_b64 s[76:77], s[30:31], exec
	s_cselect_b32 s76, 0, s91
	v_lshl_add_u32 v2, s43, 11, v148
	v_add_u32_e32 v3, s76, v149
	s_cselect_b32 s43, s93, s92
	v_add_u32_e32 v4, s43, v150
	ds_read_b128 v[160:163], v3
	ds_read_b128 v[168:171], v3 offset:256
	ds_read_b128 v[172:175], v3 offset:512
	ds_read_b128 v[180:183], v3 offset:1024
	ds_read_b128 v[184:187], v4
	ds_read_b128 v[176:179], v3 offset:768
	s_mov_b64 s[76:77], 0
	v_mbcnt_lo_u32_b32 v115, -1, 0
	v_mbcnt_hi_u32_b32 v115, -1, v115
	v_and_b32_e32 v115, 4, v115
	v_xor_b32_e32 v115, 4, v115
	v_mul_u32_u24_e32 v115, 0x2700, v115
	v_add_u32_e32 v2, v2, v115
	ds_read_b128 v[188:191], v3 offset:1536
	ds_read_b128 v[192:195], v3 offset:1792
	ds_read_b128 v[196:199], v3 offset:2048
	ds_read_b128 v[204:207], v3 offset:2560
	ds_read_b128 v[208:211], v4 offset:1536
	ds_read_b128 v[200:203], v3 offset:2304
	s_waitcnt lgkmcnt(6)
	v_mul_f32 v160, v78, v160
	v_mul_f32 v168, v78, v168
	v_fma_f32 v160, v79, v161, v160
	v_fma_f32 v168, v79, v169, v168
	v_fma_f32 v160, v80, v162, v160
	v_fma_f32 v168, v80, v170, v168
	v_fma_f32 v160, v81, v163, v160
	v_fma_f32 v168, v81, v171, v168
	v_mul_f32 v172, v78, v172
	v_add_f32_dpp v160, v160, v160 row_half_mirror row_mask:0xf bank_mask:0x5
	v_add_f32_dpp v160, v168, v168 row_half_mirror row_mask:0xf bank_mask:0xa
	v_mul_f32 v173, v79, v173
	v_mul_f32 v174, v80, v174
	v_add_f32_dpp v160, v160, v160 quad_perm:[1,0,3,2] row_mask:0xf bank_mask:0xf
	v_mul_f32 v175, v81, v175
	v_fma_f32 v172, v184, v180, v172
	v_add_f32_dpp v160, v160, v160 quad_perm:[2,3,0,1] row_mask:0xf bank_mask:0xf
	v_fma_f32 v173, v184, v181, v173
	v_fma_f32 v174, v184, v182, v174
	v_add_f32_dpp v160, v160, v160 row_ror:8 row_mask:0xf bank_mask:0xf
	v_fma_f32 v168, v184, v186, v160
	v_fma_f32 v175, v184, v183, v175
	v_mov_b32_dpp v160, v160 row_half_mirror row_mask:0xf bank_mask:0xa
	v_fma_f32 v159, -v160, v176, v172
	v_fma_f32 v164, -v160, v177, v173
	v_fma_f32 v165, -v160, v178, v174
	v_fma_f32 v167, -v160, v179, v175
	v_fma_f32 v168, -v160, v185, v168
	ds_write_b32 v2, v168
	ds_read_b128 v[160:163], v3 offset:3072
	ds_read_b128 v[168:171], v3 offset:3328
	ds_read_b128 v[172:175], v3 offset:3584
	ds_read_b128 v[180:183], v3 offset:4096
	ds_read_b128 v[184:187], v4 offset:3072
	ds_read_b128 v[176:179], v3 offset:3840
	s_waitcnt lgkmcnt(7)
	v_mul_f32 v188, v159, v188
	v_mul_f32 v192, v159, v192
	v_fma_f32 v188, v164, v189, v188
	v_fma_f32 v192, v164, v193, v192
	v_fma_f32 v188, v165, v190, v188
	v_fma_f32 v192, v165, v194, v192
	v_fma_f32 v188, v167, v191, v188
	v_fma_f32 v192, v167, v195, v192
	v_mul_f32 v196, v159, v196
	v_add_f32_dpp v188, v188, v188 row_half_mirror row_mask:0xf bank_mask:0x5
	v_add_f32_dpp v188, v192, v192 row_half_mirror row_mask:0xf bank_mask:0xa
	v_mul_f32 v197, v164, v197
	v_mul_f32 v198, v165, v198
	v_add_f32_dpp v188, v188, v188 quad_perm:[1,0,3,2] row_mask:0xf bank_mask:0xf
	v_mul_f32 v199, v167, v199
	v_fma_f32 v196, v208, v204, v196
	v_add_f32_dpp v188, v188, v188 quad_perm:[2,3,0,1] row_mask:0xf bank_mask:0xf
	v_fma_f32 v197, v208, v205, v197
	v_fma_f32 v198, v208, v206, v198
	v_add_f32_dpp v188, v188, v188 row_ror:8 row_mask:0xf bank_mask:0xf
	v_fma_f32 v192, v208, v210, v188
	v_fma_f32 v199, v208, v207, v199
	v_mov_b32_dpp v188, v188 row_half_mirror row_mask:0xf bank_mask:0xa
	v_fma_f32 v159, -v188, v200, v196
	v_fma_f32 v164, -v188, v201, v197
	v_fma_f32 v165, -v188, v202, v198
	v_fma_f32 v167, -v188, v203, v199
	v_fma_f32 v192, -v188, v209, v192
	ds_write_b32 v2, v192 offset:64
	ds_read_b128 v[188:191], v3 offset:4608
	ds_read_b128 v[192:195], v3 offset:4864
	ds_read_b128 v[196:199], v3 offset:5120
	ds_read_b128 v[204:207], v3 offset:5632
	ds_read_b128 v[208:211], v4 offset:4608
	ds_read_b128 v[200:203], v3 offset:5376
	s_waitcnt lgkmcnt(7)
	v_mul_f32 v160, v159, v160
	v_mul_f32 v168, v159, v168
	v_fma_f32 v160, v164, v161, v160
	v_fma_f32 v168, v164, v169, v168
	v_fma_f32 v160, v165, v162, v160
	v_fma_f32 v168, v165, v170, v168
	v_fma_f32 v160, v167, v163, v160
	v_fma_f32 v168, v167, v171, v168
	v_mul_f32 v172, v159, v172
	v_add_f32_dpp v160, v160, v160 row_half_mirror row_mask:0xf bank_mask:0x5
	v_add_f32_dpp v160, v168, v168 row_half_mirror row_mask:0xf bank_mask:0xa
	v_mul_f32 v173, v164, v173
	v_mul_f32 v174, v165, v174
	v_add_f32_dpp v160, v160, v160 quad_perm:[1,0,3,2] row_mask:0xf bank_mask:0xf
	v_mul_f32 v175, v167, v175
	v_fma_f32 v172, v184, v180, v172
	v_add_f32_dpp v160, v160, v160 quad_perm:[2,3,0,1] row_mask:0xf bank_mask:0xf
	v_fma_f32 v173, v184, v181, v173
	v_fma_f32 v174, v184, v182, v174
	v_add_f32_dpp v160, v160, v160 row_ror:8 row_mask:0xf bank_mask:0xf
	v_fma_f32 v168, v184, v186, v160
	v_fma_f32 v175, v184, v183, v175
	v_mov_b32_dpp v160, v160 row_half_mirror row_mask:0xf bank_mask:0xa
	v_fma_f32 v159, -v160, v176, v172
	v_fma_f32 v164, -v160, v177, v173
	v_fma_f32 v165, -v160, v178, v174
	v_fma_f32 v167, -v160, v179, v175
	v_fma_f32 v168, -v160, v185, v168
	ds_write_b32 v2, v168 offset:128
	ds_read_b128 v[160:163], v3 offset:6144
	ds_read_b128 v[168:171], v3 offset:6400
	ds_read_b128 v[172:175], v3 offset:6656
	ds_read_b128 v[180:183], v3 offset:7168
	ds_read_b128 v[184:187], v4 offset:6144
	ds_read_b128 v[176:179], v3 offset:6912
	s_waitcnt lgkmcnt(7)
; __device__ __forceinline__ float vfma(float a, float b, float c) { float d; asm("v_fma_f32 %0, %1, %2, %3" : "=v"(d) : "v"(a), "v"(b), "v"(c)); return d; }
; __device__ __forceinline__ float step_compute(float (&S)[4], const StepOp& o) {
;     float d1 = vmul(S[0], o.kk[0]), d2 = vmul(S[0], o.wr[0]), e1 = vmul(S[1], o.kk[1]), e2 = vmul(S[1], o.wr[1]);
;     d1 = vfma(S[2], o.kk[2], d1); d2 = vfma(S[2], o.wr[2], d2); e1 = vfma(S[3], o.kk[3], e1); e2 = vfma(S[3], o.wr[3], e2);
;     d1 = vadd(d1, e1); d2 = vadd(d2, e2);
;     float t0, t1, t2, t3;
;     asm volatile(
;         "v_mul_f32 %[t0], %[s0], %[w0]\n\t"
;         "v_mul_f32 %[t1], %[s1], %[w1]\n\t"
;         "v_add_f32_dpp %[d1], %[d1], %[d1] quad_perm:[1,0,3,2] row_mask:0xf bank_mask:0xf bound_ctrl:1\n\t"
;         "v_add_f32_dpp %[d2], %[d2], %[d2] quad_perm:[1,0,3,2] row_mask:0xf bank_mask:0xf bound_ctrl:1\n\t"
;         "v_mul_f32 %[t2], %[s2], %[w2]\n\t"
;         "v_add_f32_dpp %[d1], %[d1], %[d1] quad_perm:[2,3,0,1] row_mask:0xf bank_mask:0xf bound_ctrl:1\n\t"
;         "v_add_f32_dpp %[d2], %[d2], %[d2] quad_perm:[2,3,0,1] row_mask:0xf bank_mask:0xf bound_ctrl:1\n\t"
;         "v_mul_f32 %[t3], %[s3], %[w3]\n\t"
;         "v_add_f32_dpp %[d1], %[d1], %[d1] row_half_mirror row_mask:0xf bank_mask:0xf bound_ctrl:1\n\t"
;         "v_add_f32_dpp %[d2], %[d2], %[d2] row_half_mirror row_mask:0xf bank_mask:0xf bound_ctrl:1\n\t"
;         "v_fma_f32 %[t0], %[v], %[k0], %[t0]\n\t"
;         "v_add_f32_dpp %[d1], %[d1], %[d1] row_mirror row_mask:0xf bank_mask:0xf bound_ctrl:1\n\t"
;         "v_add_f32_dpp %[d2], %[d2], %[d2] row_mirror row_mask:0xf bank_mask:0xf bound_ctrl:1\n\t"
;         "v_fma_f32 %[t1], %[v], %[k1], %[t1]\n\t"
;         "v_fma_f32 %[t2], %[v], %[k2], %[t2]\n\t"
;         "v_fma_f32 %[t3], %[v], %[k3], %[t3]"
;         : [t0] "=&v"(t0), [t1] "=&v"(t1), [t2] "=&v"(t2), [t3] "=&v"(t3), [d1] "+v"(d1), [d2] "+v"(d2)
;         : [s0] "v"(S[0]), [s1] "v"(S[1]), [s2] "v"(S[2]), [s3] "v"(S[3]), [w0] "v"(o.w[0]), [w1] "v"(o.w[1]), [w2] "v"(o.w[2]), [w3] "v"(o.w[3]),
;           [k0] "v"(o.k[0]), [k1] "v"(o.k[1]), [k2] "v"(o.k[2]), [k3] "v"(o.k[3]), [v] "v"(o.q[0]));
;     S[0] = vnfma(d1, o.b[0], t0); S[1] = vnfma(d1, o.b[1], t1); S[2] = vnfma(d1, o.b[2], t2); S[3] = vnfma(d1, o.b[3], t3);
;     return vfma(o.q[0], o.q[2], vnfma(d1, o.q[1], d2));
	v_mul_f32 v188, v159, v188
	v_mul_f32 v192, v159, v192
	v_fma_f32 v188, v164, v189, v188
	v_fma_f32 v192, v164, v193, v192
	v_fma_f32 v188, v165, v190, v188
	v_fma_f32 v192, v165, v194, v192
	v_fma_f32 v188, v167, v191, v188
	v_fma_f32 v192, v167, v195, v192
	v_mul_f32 v196, v159, v196
	v_add_f32_dpp v188, v188, v188 row_half_mirror row_mask:0xf bank_mask:0x5
	v_add_f32_dpp v188, v192, v192 row_half_mirror row_mask:0xf bank_mask:0xa
	v_mul_f32 v197, v164, v197
	v_mul_f32 v198, v165, v198
	v_add_f32_dpp v188, v188, v188 quad_perm:[1,0,3,2] row_mask:0xf bank_mask:0xf
	v_mul_f32 v199, v167, v199
	v_fma_f32 v196, v208, v204, v196
	v_add_f32_dpp v188, v188, v188 quad_perm:[2,3,0,1] row_mask:0xf bank_mask:0xf
	v_fma_f32 v197, v208, v205, v197
	v_fma_f32 v198, v208, v206, v198
	v_add_f32_dpp v188, v188, v188 row_ror:8 row_mask:0xf bank_mask:0xf
	v_fma_f32 v192, v208, v210, v188
	v_fma_f32 v199, v208, v207, v199
	v_mov_b32_dpp v188, v188 row_half_mirror row_mask:0xf bank_mask:0xa
	v_fma_f32 v159, -v188, v200, v196
	v_fma_f32 v164, -v188, v201, v197
	v_fma_f32 v165, -v188, v202, v198
	v_fma_f32 v167, -v188, v203, v199
	v_fma_f32 v192, -v188, v209, v192
	ds_write_b32 v2, v192 offset:192
	ds_read_b128 v[188:191], v3 offset:7680
	ds_read_b128 v[192:195], v3 offset:7936
	ds_read_b128 v[196:199], v3 offset:8192
	ds_read_b128 v[204:207], v3 offset:8704
	ds_read_b128 v[208:211], v4 offset:7680
	ds_read_b128 v[200:203], v3 offset:8448
	s_waitcnt lgkmcnt(7)
	v_mul_f32 v160, v159, v160
	v_mul_f32 v168, v159, v168
	v_fma_f32 v160, v164, v161, v160
	v_fma_f32 v168, v164, v169, v168
	v_fma_f32 v160, v165, v162, v160
	v_fma_f32 v168, v165, v170, v168
	v_fma_f32 v160, v167, v163, v160
	v_fma_f32 v168, v167, v171, v168
	v_mul_f32 v172, v159, v172
	v_add_f32_dpp v160, v160, v160 row_half_mirror row_mask:0xf bank_mask:0x5
	v_add_f32_dpp v160, v168, v168 row_half_mirror row_mask:0xf bank_mask:0xa
	v_mul_f32 v173, v164, v173
	v_mul_f32 v174, v165, v174
	v_add_f32_dpp v160, v160, v160 quad_perm:[1,0,3,2] row_mask:0xf bank_mask:0xf
	v_mul_f32 v175, v167, v175
	v_fma_f32 v172, v184, v180, v172
	v_add_f32_dpp v160, v160, v160 quad_perm:[2,3,0,1] row_mask:0xf bank_mask:0xf
	v_fma_f32 v173, v184, v181, v173
	v_fma_f32 v174, v184, v182, v174
	v_add_f32_dpp v160, v160, v160 row_ror:8 row_mask:0xf bank_mask:0xf
	v_fma_f32 v168, v184, v186, v160
	v_fma_f32 v175, v184, v183, v175
	v_mov_b32_dpp v160, v160 row_half_mirror row_mask:0xf bank_mask:0xa
	v_fma_f32 v159, -v160, v176, v172
	v_fma_f32 v164, -v160, v177, v173
	v_fma_f32 v165, -v160, v178, v174
	v_fma_f32 v167, -v160, v179, v175
	v_fma_f32 v168, -v160, v185, v168
	ds_write_b32 v2, v168 offset:256
	ds_read_b128 v[160:163], v3 offset:9216
	ds_read_b128 v[168:171], v3 offset:9472
	ds_read_b128 v[172:175], v3 offset:9728
	ds_read_b128 v[180:183], v3 offset:10240
	ds_read_b128 v[184:187], v4 offset:9216
	ds_read_b128 v[176:179], v3 offset:9984
	s_waitcnt lgkmcnt(7)
	v_mul_f32 v188, v159, v188
	v_mul_f32 v192, v159, v192
	v_fma_f32 v188, v164, v189, v188
	v_fma_f32 v192, v164, v193, v192
	v_fma_f32 v188, v165, v190, v188
	v_fma_f32 v192, v165, v194, v192
	v_fma_f32 v188, v167, v191, v188
	v_fma_f32 v192, v167, v195, v192
	v_mul_f32 v196, v159, v196
	v_add_f32_dpp v188, v188, v188 row_half_mirror row_mask:0xf bank_mask:0x5
	v_add_f32_dpp v188, v192, v192 row_half_mirror row_mask:0xf bank_mask:0xa
	v_mul_f32 v197, v164, v197
	v_mul_f32 v198, v165, v198
	v_add_f32_dpp v188, v188, v188 quad_perm:[1,0,3,2] row_mask:0xf bank_mask:0xf
	v_mul_f32 v199, v167, v199
	v_fma_f32 v196, v208, v204, v196
	v_add_f32_dpp v188, v188, v188 quad_perm:[2,3,0,1] row_mask:0xf bank_mask:0xf
	v_fma_f32 v197, v208, v205, v197
	v_fma_f32 v198, v208, v206, v198
	v_add_f32_dpp v188, v188, v188 row_ror:8 row_mask:0xf bank_mask:0xf
	v_fma_f32 v192, v208, v210, v188
	v_fma_f32 v199, v208, v207, v199
	v_mov_b32_dpp v188, v188 row_half_mirror row_mask:0xf bank_mask:0xa
	v_fma_f32 v159, -v188, v200, v196
	v_fma_f32 v164, -v188, v201, v197
	v_fma_f32 v165, -v188, v202, v198
	v_fma_f32 v167, -v188, v203, v199
	v_fma_f32 v192, -v188, v209, v192
	ds_write_b32 v2, v192 offset:320
	ds_read_b128 v[188:191], v3 offset:10752
	ds_read_b128 v[192:195], v3 offset:11008
	ds_read_b128 v[196:199], v3 offset:11264
	ds_read_b128 v[204:207], v3 offset:11776
	ds_read_b128 v[208:211], v4 offset:10752
	ds_read_b128 v[200:203], v3 offset:11520
	s_waitcnt lgkmcnt(7)
	v_mul_f32 v160, v159, v160
	v_mul_f32 v168, v159, v168
	v_fma_f32 v160, v164, v161, v160
	v_fma_f32 v168, v164, v169, v168
	v_fma_f32 v160, v165, v162, v160
	v_fma_f32 v168, v165, v170, v168
	v_fma_f32 v160, v167, v163, v160
	v_fma_f32 v168, v167, v171, v168
	v_mul_f32 v172, v159, v172
	v_add_f32_dpp v160, v160, v160 row_half_mirror row_mask:0xf bank_mask:0x5
	v_add_f32_dpp v160, v168, v168 row_half_mirror row_mask:0xf bank_mask:0xa
	v_mul_f32 v173, v164, v173
	v_mul_f32 v174, v165, v174
	v_add_f32_dpp v160, v160, v160 quad_perm:[1,0,3,2] row_mask:0xf bank_mask:0xf
	v_mul_f32 v175, v167, v175
	v_fma_f32 v172, v184, v180, v172
	v_add_f32_dpp v160, v160, v160 quad_perm:[2,3,0,1] row_mask:0xf bank_mask:0xf
	v_fma_f32 v173, v184, v181, v173
	v_fma_f32 v174, v184, v182, v174
	v_add_f32_dpp v160, v160, v160 row_ror:8 row_mask:0xf bank_mask:0xf
	v_fma_f32 v168, v184, v186, v160
	v_fma_f32 v175, v184, v183, v175
	v_mov_b32_dpp v160, v160 row_half_mirror row_mask:0xf bank_mask:0xa
	v_fma_f32 v159, -v160, v176, v172
	v_fma_f32 v164, -v160, v177, v173
	v_fma_f32 v165, -v160, v178, v174
	v_fma_f32 v167, -v160, v179, v175
	v_fma_f32 v168, -v160, v185, v168
	ds_write_b32 v2, v168 offset:384
	ds_read_b128 v[160:163], v3 offset:12288
	ds_read_b128 v[168:171], v3 offset:12544
	ds_read_b128 v[172:175], v3 offset:12800
	ds_read_b128 v[180:183], v3 offset:13312
	ds_read_b128 v[184:187], v4 offset:12288
	ds_read_b128 v[176:179], v3 offset:13056
	s_waitcnt lgkmcnt(7)
; __device__ __forceinline__ float vfma(float a, float b, float c) { float d; asm("v_fma_f32 %0, %1, %2, %3" : "=v"(d) : "v"(a), "v"(b), "v"(c)); return d; }
; __device__ __forceinline__ float step_compute(float (&S)[4], const StepOp& o) {
;     float d1 = vmul(S[0], o.kk[0]), d2 = vmul(S[0], o.wr[0]), e1 = vmul(S[1], o.kk[1]), e2 = vmul(S[1], o.wr[1]);
;     d1 = vfma(S[2], o.kk[2], d1); d2 = vfma(S[2], o.wr[2], d2); e1 = vfma(S[3], o.kk[3], e1); e2 = vfma(S[3], o.wr[3], e2);
;     d1 = vadd(d1, e1); d2 = vadd(d2, e2);
;     float t0, t1, t2, t3;
;     asm volatile(
;         "v_mul_f32 %[t0], %[s0], %[w0]\n\t"
;         "v_mul_f32 %[t1], %[s1], %[w1]\n\t"
;         "v_add_f32_dpp %[d1], %[d1], %[d1] quad_perm:[1,0,3,2] row_mask:0xf bank_mask:0xf bound_ctrl:1\n\t"
;         "v_add_f32_dpp %[d2], %[d2], %[d2] quad_perm:[1,0,3,2] row_mask:0xf bank_mask:0xf bound_ctrl:1\n\t"
;         "v_mul_f32 %[t2], %[s2], %[w2]\n\t"
;         "v_add_f32_dpp %[d1], %[d1], %[d1] quad_perm:[2,3,0,1] row_mask:0xf bank_mask:0xf bound_ctrl:1\n\t"
;         "v_add_f32_dpp %[d2], %[d2], %[d2] quad_perm:[2,3,0,1] row_mask:0xf bank_mask:0xf bound_ctrl:1\n\t"
;         "v_mul_f32 %[t3], %[s3], %[w3]\n\t"
;         "v_add_f32_dpp %[d1], %[d1], %[d1] row_half_mirror row_mask:0xf bank_mask:0xf bound_ctrl:1\n\t"
;         "v_add_f32_dpp %[d2], %[d2], %[d2] row_half_mirror row_mask:0xf bank_mask:0xf bound_ctrl:1\n\t"
;         "v_fma_f32 %[t0], %[v], %[k0], %[t0]\n\t"
;         "v_add_f32_dpp %[d1], %[d1], %[d1] row_mirror row_mask:0xf bank_mask:0xf bound_ctrl:1\n\t"
;         "v_add_f32_dpp %[d2], %[d2], %[d2] row_mirror row_mask:0xf bank_mask:0xf bound_ctrl:1\n\t"
;         "v_fma_f32 %[t1], %[v], %[k1], %[t1]\n\t"
;         "v_fma_f32 %[t2], %[v], %[k2], %[t2]\n\t"
;         "v_fma_f32 %[t3], %[v], %[k3], %[t3]"
;         : [t0] "=&v"(t0), [t1] "=&v"(t1), [t2] "=&v"(t2), [t3] "=&v"(t3), [d1] "+v"(d1), [d2] "+v"(d2)
;         : [s0] "v"(S[0]), [s1] "v"(S[1]), [s2] "v"(S[2]), [s3] "v"(S[3]), [w0] "v"(o.w[0]), [w1] "v"(o.w[1]), [w2] "v"(o.w[2]), [w3] "v"(o.w[3]),
;           [k0] "v"(o.k[0]), [k1] "v"(o.k[1]), [k2] "v"(o.k[2]), [k3] "v"(o.k[3]), [v] "v"(o.q[0]));
;     S[0] = vnfma(d1, o.b[0], t0); S[1] = vnfma(d1, o.b[1], t1); S[2] = vnfma(d1, o.b[2], t2); S[3] = vnfma(d1, o.b[3], t3);
;     return vfma(o.q[0], o.q[2], vnfma(d1, o.q[1], d2));
	v_mul_f32 v188, v159, v188
	v_mul_f32 v192, v159, v192
	v_fma_f32 v188, v164, v189, v188
	v_fma_f32 v192, v164, v193, v192
	v_fma_f32 v188, v165, v190, v188
	v_fma_f32 v192, v165, v194, v192
	v_fma_f32 v188, v167, v191, v188
	v_fma_f32 v192, v167, v195, v192
	v_mul_f32 v196, v159, v196
	v_add_f32_dpp v188, v188, v188 row_half_mirror row_mask:0xf bank_mask:0x5
	v_add_f32_dpp v188, v192, v192 row_half_mirror row_mask:0xf bank_mask:0xa
	v_mul_f32 v197, v164, v197
	v_mul_f32 v198, v165, v198
	v_add_f32_dpp v188, v188, v188 quad_perm:[1,0,3,2] row_mask:0xf bank_mask:0xf
	v_mul_f32 v199, v167, v199
	v_fma_f32 v196, v208, v204, v196
	v_add_f32_dpp v188, v188, v188 quad_perm:[2,3,0,1] row_mask:0xf bank_mask:0xf
	v_fma_f32 v197, v208, v205, v197
	v_fma_f32 v198, v208, v206, v198
	v_add_f32_dpp v188, v188, v188 row_ror:8 row_mask:0xf bank_mask:0xf
	v_fma_f32 v192, v208, v210, v188
	v_fma_f32 v199, v208, v207, v199
	v_mov_b32_dpp v188, v188 row_half_mirror row_mask:0xf bank_mask:0xa
	v_fma_f32 v159, -v188, v200, v196
	v_fma_f32 v164, -v188, v201, v197
	v_fma_f32 v165, -v188, v202, v198
	v_fma_f32 v167, -v188, v203, v199
	v_fma_f32 v192, -v188, v209, v192
	ds_write_b32 v2, v192 offset:448
	ds_read_b128 v[188:191], v3 offset:13824
	ds_read_b128 v[192:195], v3 offset:14080
	ds_read_b128 v[196:199], v3 offset:14336
	ds_read_b128 v[204:207], v3 offset:14848
	ds_read_b128 v[208:211], v4 offset:13824
	ds_read_b128 v[200:203], v3 offset:14592
	s_waitcnt lgkmcnt(7)
	v_mul_f32 v160, v159, v160
	v_mul_f32 v168, v159, v168
	v_fma_f32 v160, v164, v161, v160
	v_fma_f32 v168, v164, v169, v168
	v_fma_f32 v160, v165, v162, v160
	v_fma_f32 v168, v165, v170, v168
	v_fma_f32 v160, v167, v163, v160
	v_fma_f32 v168, v167, v171, v168
	v_mul_f32 v172, v159, v172
	v_add_f32_dpp v160, v160, v160 row_half_mirror row_mask:0xf bank_mask:0x5
	v_add_f32_dpp v160, v168, v168 row_half_mirror row_mask:0xf bank_mask:0xa
	v_mul_f32 v173, v164, v173
	v_mul_f32 v174, v165, v174
	v_add_f32_dpp v160, v160, v160 quad_perm:[1,0,3,2] row_mask:0xf bank_mask:0xf
	v_mul_f32 v175, v167, v175
	v_fma_f32 v172, v184, v180, v172
	v_add_f32_dpp v160, v160, v160 quad_perm:[2,3,0,1] row_mask:0xf bank_mask:0xf
	v_fma_f32 v173, v184, v181, v173
	v_fma_f32 v174, v184, v182, v174
	v_add_f32_dpp v160, v160, v160 row_ror:8 row_mask:0xf bank_mask:0xf
	v_fma_f32 v168, v184, v186, v160
	v_fma_f32 v175, v184, v183, v175
	v_mov_b32_dpp v160, v160 row_half_mirror row_mask:0xf bank_mask:0xa
	v_fma_f32 v159, -v160, v176, v172
	v_fma_f32 v164, -v160, v177, v173
	v_fma_f32 v165, -v160, v178, v174
	v_fma_f32 v167, -v160, v179, v175
	v_fma_f32 v168, -v160, v185, v168
	ds_write_b32 v2, v168 offset:512
	ds_read_b128 v[160:163], v3 offset:15360
	ds_read_b128 v[168:171], v3 offset:15616
	ds_read_b128 v[172:175], v3 offset:15872
	ds_read_b128 v[180:183], v3 offset:16384
	ds_read_b128 v[184:187], v4 offset:15360
	ds_read_b128 v[176:179], v3 offset:16128
	s_waitcnt lgkmcnt(7)
	v_mul_f32 v188, v159, v188
	v_mul_f32 v192, v159, v192
	v_fma_f32 v188, v164, v189, v188
	v_fma_f32 v192, v164, v193, v192
	v_fma_f32 v188, v165, v190, v188
	v_fma_f32 v192, v165, v194, v192
	v_fma_f32 v188, v167, v191, v188
	v_fma_f32 v192, v167, v195, v192
	v_mul_f32 v196, v159, v196
	v_add_f32_dpp v188, v188, v188 row_half_mirror row_mask:0xf bank_mask:0x5
	v_add_f32_dpp v188, v192, v192 row_half_mirror row_mask:0xf bank_mask:0xa
	v_mul_f32 v197, v164, v197
	v_mul_f32 v198, v165, v198
	v_add_f32_dpp v188, v188, v188 quad_perm:[1,0,3,2] row_mask:0xf bank_mask:0xf
	v_mul_f32 v199, v167, v199
	v_fma_f32 v196, v208, v204, v196
	v_add_f32_dpp v188, v188, v188 quad_perm:[2,3,0,1] row_mask:0xf bank_mask:0xf
	v_fma_f32 v197, v208, v205, v197
	v_fma_f32 v198, v208, v206, v198
	v_add_f32_dpp v188, v188, v188 row_ror:8 row_mask:0xf bank_mask:0xf
	v_fma_f32 v192, v208, v210, v188
	v_fma_f32 v199, v208, v207, v199
	v_mov_b32_dpp v188, v188 row_half_mirror row_mask:0xf bank_mask:0xa
	v_fma_f32 v159, -v188, v200, v196
	v_fma_f32 v164, -v188, v201, v197
	v_fma_f32 v165, -v188, v202, v198
	v_fma_f32 v167, -v188, v203, v199
	v_fma_f32 v192, -v188, v209, v192
	ds_write_b32 v2, v192 offset:576
	ds_read_b128 v[188:191], v3 offset:16896
	ds_read_b128 v[192:195], v3 offset:17152
	ds_read_b128 v[196:199], v3 offset:17408
	ds_read_b128 v[204:207], v3 offset:17920
	ds_read_b128 v[208:211], v4 offset:16896
	ds_read_b128 v[200:203], v3 offset:17664
	s_waitcnt lgkmcnt(7)
	v_mul_f32 v160, v159, v160
	v_mul_f32 v168, v159, v168
	v_fma_f32 v160, v164, v161, v160
	v_fma_f32 v168, v164, v169, v168
	v_fma_f32 v160, v165, v162, v160
	v_fma_f32 v168, v165, v170, v168
	v_fma_f32 v160, v167, v163, v160
	v_fma_f32 v168, v167, v171, v168
	v_mul_f32 v172, v159, v172
	v_add_f32_dpp v160, v160, v160 row_half_mirror row_mask:0xf bank_mask:0x5
	v_add_f32_dpp v160, v168, v168 row_half_mirror row_mask:0xf bank_mask:0xa
	v_mul_f32 v173, v164, v173
	v_mul_f32 v174, v165, v174
	v_add_f32_dpp v160, v160, v160 quad_perm:[1,0,3,2] row_mask:0xf bank_mask:0xf
	v_mul_f32 v175, v167, v175
	v_fma_f32 v172, v184, v180, v172
	v_add_f32_dpp v160, v160, v160 quad_perm:[2,3,0,1] row_mask:0xf bank_mask:0xf
	v_fma_f32 v173, v184, v181, v173
	v_fma_f32 v174, v184, v182, v174
	v_add_f32_dpp v160, v160, v160 row_ror:8 row_mask:0xf bank_mask:0xf
	v_fma_f32 v168, v184, v186, v160
	v_fma_f32 v175, v184, v183, v175
	v_mov_b32_dpp v160, v160 row_half_mirror row_mask:0xf bank_mask:0xa
	v_fma_f32 v159, -v160, v176, v172
	v_fma_f32 v164, -v160, v177, v173
	v_fma_f32 v165, -v160, v178, v174
	v_fma_f32 v167, -v160, v179, v175
	v_fma_f32 v168, -v160, v185, v168
	ds_write_b32 v2, v168 offset:640
	ds_read_b128 v[160:163], v3 offset:18432
	ds_read_b128 v[168:171], v3 offset:18688
	ds_read_b128 v[172:175], v3 offset:18944
	ds_read_b128 v[180:183], v3 offset:19456
	ds_read_b128 v[184:187], v4 offset:18432
	ds_read_b128 v[176:179], v3 offset:19200
	s_waitcnt lgkmcnt(7)
; __device__ __forceinline__ float vfma(float a, float b, float c) { float d; asm("v_fma_f32 %0, %1, %2, %3" : "=v"(d) : "v"(a), "v"(b), "v"(c)); return d; }
; __device__ __forceinline__ float step_compute(float (&S)[4], const StepOp& o) {
;     float d1 = vmul(S[0], o.kk[0]), d2 = vmul(S[0], o.wr[0]), e1 = vmul(S[1], o.kk[1]), e2 = vmul(S[1], o.wr[1]);
;     d1 = vfma(S[2], o.kk[2], d1); d2 = vfma(S[2], o.wr[2], d2); e1 = vfma(S[3], o.kk[3], e1); e2 = vfma(S[3], o.wr[3], e2);
;     d1 = vadd(d1, e1); d2 = vadd(d2, e2);
;     float t0, t1, t2, t3;
;     asm volatile(
;         "v_mul_f32 %[t0], %[s0], %[w0]\n\t"
;         "v_mul_f32 %[t1], %[s1], %[w1]\n\t"
;         "v_add_f32_dpp %[d1], %[d1], %[d1] quad_perm:[1,0,3,2] row_mask:0xf bank_mask:0xf bound_ctrl:1\n\t"
;         "v_add_f32_dpp %[d2], %[d2], %[d2] quad_perm:[1,0,3,2] row_mask:0xf bank_mask:0xf bound_ctrl:1\n\t"
;         "v_mul_f32 %[t2], %[s2], %[w2]\n\t"
;         "v_add_f32_dpp %[d1], %[d1], %[d1] quad_perm:[2,3,0,1] row_mask:0xf bank_mask:0xf bound_ctrl:1\n\t"
;         "v_add_f32_dpp %[d2], %[d2], %[d2] quad_perm:[2,3,0,1] row_mask:0xf bank_mask:0xf bound_ctrl:1\n\t"
;         "v_mul_f32 %[t3], %[s3], %[w3]\n\t"
;         "v_add_f32_dpp %[d1], %[d1], %[d1] row_half_mirror row_mask:0xf bank_mask:0xf bound_ctrl:1\n\t"
;         "v_add_f32_dpp %[d2], %[d2], %[d2] row_half_mirror row_mask:0xf bank_mask:0xf bound_ctrl:1\n\t"
;         "v_fma_f32 %[t0], %[v], %[k0], %[t0]\n\t"
;         "v_add_f32_dpp %[d1], %[d1], %[d1] row_mirror row_mask:0xf bank_mask:0xf bound_ctrl:1\n\t"
;         "v_add_f32_dpp %[d2], %[d2], %[d2] row_mirror row_mask:0xf bank_mask:0xf bound_ctrl:1\n\t"
;         "v_fma_f32 %[t1], %[v], %[k1], %[t1]\n\t"
;         "v_fma_f32 %[t2], %[v], %[k2], %[t2]\n\t"
;         "v_fma_f32 %[t3], %[v], %[k3], %[t3]"
;         : [t0] "=&v"(t0), [t1] "=&v"(t1), [t2] "=&v"(t2), [t3] "=&v"(t3), [d1] "+v"(d1), [d2] "+v"(d2)
;         : [s0] "v"(S[0]), [s1] "v"(S[1]), [s2] "v"(S[2]), [s3] "v"(S[3]), [w0] "v"(o.w[0]), [w1] "v"(o.w[1]), [w2] "v"(o.w[2]), [w3] "v"(o.w[3]),
;           [k0] "v"(o.k[0]), [k1] "v"(o.k[1]), [k2] "v"(o.k[2]), [k3] "v"(o.k[3]), [v] "v"(o.q[0]));
;     S[0] = vnfma(d1, o.b[0], t0); S[1] = vnfma(d1, o.b[1], t1); S[2] = vnfma(d1, o.b[2], t2); S[3] = vnfma(d1, o.b[3], t3);
;     return vfma(o.q[0], o.q[2], vnfma(d1, o.q[1], d2));
	v_mul_f32 v188, v159, v188
	v_mul_f32 v192, v159, v192
	v_fma_f32 v188, v164, v189, v188
	v_fma_f32 v192, v164, v193, v192
	v_fma_f32 v188, v165, v190, v188
	v_fma_f32 v192, v165, v194, v192
	v_fma_f32 v188, v167, v191, v188
	v_fma_f32 v192, v167, v195, v192
	v_mul_f32 v196, v159, v196
	v_add_f32_dpp v188, v188, v188 row_half_mirror row_mask:0xf bank_mask:0x5
	v_add_f32_dpp v188, v192, v192 row_half_mirror row_mask:0xf bank_mask:0xa
	v_mul_f32 v197, v164, v197
	v_mul_f32 v198, v165, v198
	v_add_f32_dpp v188, v188, v188 quad_perm:[1,0,3,2] row_mask:0xf bank_mask:0xf
	v_mul_f32 v199, v167, v199
	v_fma_f32 v196, v208, v204, v196
	v_add_f32_dpp v188, v188, v188 quad_perm:[2,3,0,1] row_mask:0xf bank_mask:0xf
	v_fma_f32 v197, v208, v205, v197
	v_fma_f32 v198, v208, v206, v198
	v_add_f32_dpp v188, v188, v188 row_ror:8 row_mask:0xf bank_mask:0xf
	v_fma_f32 v192, v208, v210, v188
	v_fma_f32 v199, v208, v207, v199
	v_mov_b32_dpp v188, v188 row_half_mirror row_mask:0xf bank_mask:0xa
	v_fma_f32 v159, -v188, v200, v196
	v_fma_f32 v164, -v188, v201, v197
	v_fma_f32 v165, -v188, v202, v198
	v_fma_f32 v167, -v188, v203, v199
	v_fma_f32 v192, -v188, v209, v192
	ds_write_b32 v2, v192 offset:704
	ds_read_b128 v[188:191], v3 offset:19968
	ds_read_b128 v[192:195], v3 offset:20224
	ds_read_b128 v[196:199], v3 offset:20480
	ds_read_b128 v[204:207], v3 offset:20992
	ds_read_b128 v[208:211], v4 offset:19968
	ds_read_b128 v[200:203], v3 offset:20736
	s_waitcnt lgkmcnt(7)
	v_mul_f32 v160, v159, v160
	v_mul_f32 v168, v159, v168
	v_fma_f32 v160, v164, v161, v160
	v_fma_f32 v168, v164, v169, v168
	v_fma_f32 v160, v165, v162, v160
	v_fma_f32 v168, v165, v170, v168
	v_fma_f32 v160, v167, v163, v160
	v_fma_f32 v168, v167, v171, v168
	v_mul_f32 v172, v159, v172
	v_add_f32_dpp v160, v160, v160 row_half_mirror row_mask:0xf bank_mask:0x5
	v_add_f32_dpp v160, v168, v168 row_half_mirror row_mask:0xf bank_mask:0xa
	v_mul_f32 v173, v164, v173
	v_mul_f32 v174, v165, v174
	v_add_f32_dpp v160, v160, v160 quad_perm:[1,0,3,2] row_mask:0xf bank_mask:0xf
	v_mul_f32 v175, v167, v175
	v_fma_f32 v172, v184, v180, v172
	v_add_f32_dpp v160, v160, v160 quad_perm:[2,3,0,1] row_mask:0xf bank_mask:0xf
	v_fma_f32 v173, v184, v181, v173
	v_fma_f32 v174, v184, v182, v174
	v_add_f32_dpp v160, v160, v160 row_ror:8 row_mask:0xf bank_mask:0xf
	v_fma_f32 v168, v184, v186, v160
	v_fma_f32 v175, v184, v183, v175
	v_mov_b32_dpp v160, v160 row_half_mirror row_mask:0xf bank_mask:0xa
	v_fma_f32 v159, -v160, v176, v172
	v_fma_f32 v164, -v160, v177, v173
	v_fma_f32 v165, -v160, v178, v174
	v_fma_f32 v167, -v160, v179, v175
	v_fma_f32 v168, -v160, v185, v168
	ds_write_b32 v2, v168 offset:768
	ds_read_b128 v[160:163], v3 offset:21504
	ds_read_b128 v[168:171], v3 offset:21760
	ds_read_b128 v[172:175], v3 offset:22016
	ds_read_b128 v[180:183], v3 offset:22528
	ds_read_b128 v[184:187], v4 offset:21504
	ds_read_b128 v[176:179], v3 offset:22272
	s_waitcnt lgkmcnt(7)
	v_mul_f32 v188, v159, v188
	v_mul_f32 v192, v159, v192
	v_fma_f32 v188, v164, v189, v188
	v_fma_f32 v192, v164, v193, v192
	v_fma_f32 v188, v165, v190, v188
	v_fma_f32 v192, v165, v194, v192
	v_fma_f32 v188, v167, v191, v188
	v_fma_f32 v192, v167, v195, v192
	v_mul_f32 v196, v159, v196
	v_add_f32_dpp v188, v188, v188 row_half_mirror row_mask:0xf bank_mask:0x5
	v_add_f32_dpp v188, v192, v192 row_half_mirror row_mask:0xf bank_mask:0xa
	v_mul_f32 v197, v164, v197
	v_mul_f32 v198, v165, v198
	v_add_f32_dpp v188, v188, v188 quad_perm:[1,0,3,2] row_mask:0xf bank_mask:0xf
	v_mul_f32 v199, v167, v199
	v_fma_f32 v196, v208, v204, v196
	v_add_f32_dpp v188, v188, v188 quad_perm:[2,3,0,1] row_mask:0xf bank_mask:0xf
	v_fma_f32 v197, v208, v205, v197
	v_fma_f32 v198, v208, v206, v198
	v_add_f32_dpp v188, v188, v188 row_ror:8 row_mask:0xf bank_mask:0xf
	v_fma_f32 v192, v208, v210, v188
	v_fma_f32 v199, v208, v207, v199
	v_mov_b32_dpp v188, v188 row_half_mirror row_mask:0xf bank_mask:0xa
	v_fma_f32 v159, -v188, v200, v196
	v_fma_f32 v164, -v188, v201, v197
	v_fma_f32 v165, -v188, v202, v198
	v_fma_f32 v167, -v188, v203, v199
	v_fma_f32 v192, -v188, v209, v192
	ds_write_b32 v2, v192 offset:832
	ds_read_b128 v[188:191], v3 offset:23040
	ds_read_b128 v[192:195], v3 offset:23296
	ds_read_b128 v[196:199], v3 offset:23552
	ds_read_b128 v[204:207], v3 offset:24064
	ds_read_b128 v[208:211], v4 offset:23040
	ds_read_b128 v[200:203], v3 offset:23808
	s_waitcnt lgkmcnt(7)
	v_mul_f32 v160, v159, v160
	v_mul_f32 v168, v159, v168
	v_fma_f32 v160, v164, v161, v160
	v_fma_f32 v168, v164, v169, v168
	v_fma_f32 v160, v165, v162, v160
	v_fma_f32 v168, v165, v170, v168
	v_fma_f32 v160, v167, v163, v160
	v_fma_f32 v168, v167, v171, v168
	v_mul_f32 v172, v159, v172
	v_add_f32_dpp v160, v160, v160 row_half_mirror row_mask:0xf bank_mask:0x5
	v_add_f32_dpp v160, v168, v168 row_half_mirror row_mask:0xf bank_mask:0xa
	v_mul_f32 v173, v164, v173
	v_mul_f32 v174, v165, v174
	v_add_f32_dpp v160, v160, v160 quad_perm:[1,0,3,2] row_mask:0xf bank_mask:0xf
	v_mul_f32 v175, v167, v175
	v_fma_f32 v172, v184, v180, v172
	v_add_f32_dpp v160, v160, v160 quad_perm:[2,3,0,1] row_mask:0xf bank_mask:0xf
	v_fma_f32 v173, v184, v181, v173
	v_fma_f32 v174, v184, v182, v174
	v_add_f32_dpp v160, v160, v160 row_ror:8 row_mask:0xf bank_mask:0xf
	v_fma_f32 v168, v184, v186, v160
	v_fma_f32 v175, v184, v183, v175
	v_mov_b32_dpp v160, v160 row_half_mirror row_mask:0xf bank_mask:0xa
	v_fma_f32 v159, -v160, v176, v172
	v_fma_f32 v164, -v160, v177, v173
	v_fma_f32 v165, -v160, v178, v174
	v_fma_f32 v167, -v160, v179, v175
	v_fma_f32 v168, -v160, v185, v168
	ds_write_b32 v2, v168 offset:896
	ds_read_b128 v[160:163], v3 offset:24576
	ds_read_b128 v[168:171], v3 offset:24832
	ds_read_b128 v[172:175], v3 offset:25088
	ds_read_b128 v[180:183], v3 offset:25600
	ds_read_b128 v[184:187], v4 offset:24576
	ds_read_b128 v[176:179], v3 offset:25344
	s_waitcnt lgkmcnt(7)
; __device__ __forceinline__ float vfma(float a, float b, float c) { float d; asm("v_fma_f32 %0, %1, %2, %3" : "=v"(d) : "v"(a), "v"(b), "v"(c)); return d; }
; __device__ __forceinline__ float step_compute(float (&S)[4], const StepOp& o) {
;     float d1 = vmul(S[0], o.kk[0]), d2 = vmul(S[0], o.wr[0]), e1 = vmul(S[1], o.kk[1]), e2 = vmul(S[1], o.wr[1]);
;     d1 = vfma(S[2], o.kk[2], d1); d2 = vfma(S[2], o.wr[2], d2); e1 = vfma(S[3], o.kk[3], e1); e2 = vfma(S[3], o.wr[3], e2);
;     d1 = vadd(d1, e1); d2 = vadd(d2, e2);
;     float t0, t1, t2, t3;
;     asm volatile(
;         "v_mul_f32 %[t0], %[s0], %[w0]\n\t"
;         "v_mul_f32 %[t1], %[s1], %[w1]\n\t"
;         "v_add_f32_dpp %[d1], %[d1], %[d1] quad_perm:[1,0,3,2] row_mask:0xf bank_mask:0xf bound_ctrl:1\n\t"
;         "v_add_f32_dpp %[d2], %[d2], %[d2] quad_perm:[1,0,3,2] row_mask:0xf bank_mask:0xf bound_ctrl:1\n\t"
;         "v_mul_f32 %[t2], %[s2], %[w2]\n\t"
;         "v_add_f32_dpp %[d1], %[d1], %[d1] quad_perm:[2,3,0,1] row_mask:0xf bank_mask:0xf bound_ctrl:1\n\t"
;         "v_add_f32_dpp %[d2], %[d2], %[d2] quad_perm:[2,3,0,1] row_mask:0xf bank_mask:0xf bound_ctrl:1\n\t"
;         "v_mul_f32 %[t3], %[s3], %[w3]\n\t"
;         "v_add_f32_dpp %[d1], %[d1], %[d1] row_half_mirror row_mask:0xf bank_mask:0xf bound_ctrl:1\n\t"
;         "v_add_f32_dpp %[d2], %[d2], %[d2] row_half_mirror row_mask:0xf bank_mask:0xf bound_ctrl:1\n\t"
;         "v_fma_f32 %[t0], %[v], %[k0], %[t0]\n\t"
;         "v_add_f32_dpp %[d1], %[d1], %[d1] row_mirror row_mask:0xf bank_mask:0xf bound_ctrl:1\n\t"
;         "v_add_f32_dpp %[d2], %[d2], %[d2] row_mirror row_mask:0xf bank_mask:0xf bound_ctrl:1\n\t"
;         "v_fma_f32 %[t1], %[v], %[k1], %[t1]\n\t"
;         "v_fma_f32 %[t2], %[v], %[k2], %[t2]\n\t"
;         "v_fma_f32 %[t3], %[v], %[k3], %[t3]"
;         : [t0] "=&v"(t0), [t1] "=&v"(t1), [t2] "=&v"(t2), [t3] "=&v"(t3), [d1] "+v"(d1), [d2] "+v"(d2)
;         : [s0] "v"(S[0]), [s1] "v"(S[1]), [s2] "v"(S[2]), [s3] "v"(S[3]), [w0] "v"(o.w[0]), [w1] "v"(o.w[1]), [w2] "v"(o.w[2]), [w3] "v"(o.w[3]),
;           [k0] "v"(o.k[0]), [k1] "v"(o.k[1]), [k2] "v"(o.k[2]), [k3] "v"(o.k[3]), [v] "v"(o.q[0]));
;     S[0] = vnfma(d1, o.b[0], t0); S[1] = vnfma(d1, o.b[1], t1); S[2] = vnfma(d1, o.b[2], t2); S[3] = vnfma(d1, o.b[3], t3);
;     return vfma(o.q[0], o.q[2], vnfma(d1, o.q[1], d2));
	v_mul_f32 v188, v159, v188
	v_mul_f32 v192, v159, v192
	v_fma_f32 v188, v164, v189, v188
	v_fma_f32 v192, v164, v193, v192
	v_fma_f32 v188, v165, v190, v188
	v_fma_f32 v192, v165, v194, v192
	v_fma_f32 v188, v167, v191, v188
	v_fma_f32 v192, v167, v195, v192
	v_mul_f32 v196, v159, v196
	v_add_f32_dpp v188, v188, v188 row_half_mirror row_mask:0xf bank_mask:0x5
	v_add_f32_dpp v188, v192, v192 row_half_mirror row_mask:0xf bank_mask:0xa
	v_mul_f32 v197, v164, v197
	v_mul_f32 v198, v165, v198
	v_add_f32_dpp v188, v188, v188 quad_perm:[1,0,3,2] row_mask:0xf bank_mask:0xf
	v_mul_f32 v199, v167, v199
	v_fma_f32 v196, v208, v204, v196
	v_add_f32_dpp v188, v188, v188 quad_perm:[2,3,0,1] row_mask:0xf bank_mask:0xf
	v_fma_f32 v197, v208, v205, v197
	v_fma_f32 v198, v208, v206, v198
	v_add_f32_dpp v188, v188, v188 row_ror:8 row_mask:0xf bank_mask:0xf
	v_fma_f32 v192, v208, v210, v188
	v_fma_f32 v199, v208, v207, v199
	v_mov_b32_dpp v188, v188 row_half_mirror row_mask:0xf bank_mask:0xa
	v_fma_f32 v159, -v188, v200, v196
	v_fma_f32 v164, -v188, v201, v197
	v_fma_f32 v165, -v188, v202, v198
	v_fma_f32 v167, -v188, v203, v199
	v_fma_f32 v192, -v188, v209, v192
	ds_write_b32 v2, v192 offset:960
	ds_read_b128 v[188:191], v3 offset:26112
	ds_read_b128 v[192:195], v3 offset:26368
	ds_read_b128 v[196:199], v3 offset:26624
	ds_read_b128 v[204:207], v3 offset:27136
	ds_read_b128 v[208:211], v4 offset:26112
	ds_read_b128 v[200:203], v3 offset:26880
	s_waitcnt lgkmcnt(7)
	v_mul_f32 v160, v159, v160
	v_mul_f32 v168, v159, v168
	v_fma_f32 v160, v164, v161, v160
	v_fma_f32 v168, v164, v169, v168
	v_fma_f32 v160, v165, v162, v160
	v_fma_f32 v168, v165, v170, v168
	v_fma_f32 v160, v167, v163, v160
	v_fma_f32 v168, v167, v171, v168
	v_mul_f32 v172, v159, v172
	v_add_f32_dpp v160, v160, v160 row_half_mirror row_mask:0xf bank_mask:0x5
	v_add_f32_dpp v160, v168, v168 row_half_mirror row_mask:0xf bank_mask:0xa
	v_mul_f32 v173, v164, v173
	v_mul_f32 v174, v165, v174
	v_add_f32_dpp v160, v160, v160 quad_perm:[1,0,3,2] row_mask:0xf bank_mask:0xf
	v_mul_f32 v175, v167, v175
	v_fma_f32 v172, v184, v180, v172
	v_add_f32_dpp v160, v160, v160 quad_perm:[2,3,0,1] row_mask:0xf bank_mask:0xf
	v_fma_f32 v173, v184, v181, v173
	v_fma_f32 v174, v184, v182, v174
	v_add_f32_dpp v160, v160, v160 row_ror:8 row_mask:0xf bank_mask:0xf
	v_fma_f32 v168, v184, v186, v160
	v_fma_f32 v175, v184, v183, v175
	v_mov_b32_dpp v160, v160 row_half_mirror row_mask:0xf bank_mask:0xa
	v_fma_f32 v159, -v160, v176, v172
	v_fma_f32 v164, -v160, v177, v173
	v_fma_f32 v165, -v160, v178, v174
	v_fma_f32 v167, -v160, v179, v175
	v_fma_f32 v168, -v160, v185, v168
	ds_write_b32 v2, v168 offset:1024
	ds_read_b128 v[160:163], v3 offset:27648
	ds_read_b128 v[168:171], v3 offset:27904
	ds_read_b128 v[172:175], v3 offset:28160
	ds_read_b128 v[180:183], v3 offset:28672
	ds_read_b128 v[184:187], v4 offset:27648
	ds_read_b128 v[176:179], v3 offset:28416
	s_waitcnt lgkmcnt(7)
	v_mul_f32 v188, v159, v188
	v_mul_f32 v192, v159, v192
	v_fma_f32 v188, v164, v189, v188
	v_fma_f32 v192, v164, v193, v192
	v_fma_f32 v188, v165, v190, v188
	v_fma_f32 v192, v165, v194, v192
	v_fma_f32 v188, v167, v191, v188
	v_fma_f32 v192, v167, v195, v192
	v_mul_f32 v196, v159, v196
	v_add_f32_dpp v188, v188, v188 row_half_mirror row_mask:0xf bank_mask:0x5
	v_add_f32_dpp v188, v192, v192 row_half_mirror row_mask:0xf bank_mask:0xa
	v_mul_f32 v197, v164, v197
	v_mul_f32 v198, v165, v198
	v_add_f32_dpp v188, v188, v188 quad_perm:[1,0,3,2] row_mask:0xf bank_mask:0xf
	v_mul_f32 v199, v167, v199
	v_fma_f32 v196, v208, v204, v196
	v_add_f32_dpp v188, v188, v188 quad_perm:[2,3,0,1] row_mask:0xf bank_mask:0xf
	v_fma_f32 v197, v208, v205, v197
	v_fma_f32 v198, v208, v206, v198
	v_add_f32_dpp v188, v188, v188 row_ror:8 row_mask:0xf bank_mask:0xf
	v_fma_f32 v192, v208, v210, v188
	v_fma_f32 v199, v208, v207, v199
	v_mov_b32_dpp v188, v188 row_half_mirror row_mask:0xf bank_mask:0xa
	v_fma_f32 v159, -v188, v200, v196
	v_fma_f32 v164, -v188, v201, v197
	v_fma_f32 v165, -v188, v202, v198
	v_fma_f32 v167, -v188, v203, v199
	v_fma_f32 v192, -v188, v209, v192
	ds_write_b32 v2, v192 offset:1088
	ds_read_b128 v[188:191], v3 offset:29184
	ds_read_b128 v[192:195], v3 offset:29440
	ds_read_b128 v[196:199], v3 offset:29696
	ds_read_b128 v[204:207], v3 offset:30208
	ds_read_b128 v[208:211], v4 offset:29184
	ds_read_b128 v[200:203], v3 offset:29952
	s_waitcnt lgkmcnt(7)
	v_mul_f32 v160, v159, v160
	v_mul_f32 v168, v159, v168
	v_fma_f32 v160, v164, v161, v160
	v_fma_f32 v168, v164, v169, v168
	v_fma_f32 v160, v165, v162, v160
	v_fma_f32 v168, v165, v170, v168
	v_fma_f32 v160, v167, v163, v160
	v_fma_f32 v168, v167, v171, v168
	v_mul_f32 v172, v159, v172
	v_add_f32_dpp v160, v160, v160 row_half_mirror row_mask:0xf bank_mask:0x5
	v_add_f32_dpp v160, v168, v168 row_half_mirror row_mask:0xf bank_mask:0xa
	v_mul_f32 v173, v164, v173
	v_mul_f32 v174, v165, v174
	v_add_f32_dpp v160, v160, v160 quad_perm:[1,0,3,2] row_mask:0xf bank_mask:0xf
	v_mul_f32 v175, v167, v175
	v_fma_f32 v172, v184, v180, v172
	v_add_f32_dpp v160, v160, v160 quad_perm:[2,3,0,1] row_mask:0xf bank_mask:0xf
	v_fma_f32 v173, v184, v181, v173
	v_fma_f32 v174, v184, v182, v174
	v_add_f32_dpp v160, v160, v160 row_ror:8 row_mask:0xf bank_mask:0xf
	v_fma_f32 v168, v184, v186, v160
	v_fma_f32 v175, v184, v183, v175
	v_mov_b32_dpp v160, v160 row_half_mirror row_mask:0xf bank_mask:0xa
	v_fma_f32 v159, -v160, v176, v172
	v_fma_f32 v164, -v160, v177, v173
	v_fma_f32 v165, -v160, v178, v174
	v_fma_f32 v167, -v160, v179, v175
	v_fma_f32 v168, -v160, v185, v168
	ds_write_b32 v2, v168 offset:1152
	ds_read_b128 v[160:163], v3 offset:30720
	ds_read_b128 v[168:171], v3 offset:30976
	ds_read_b128 v[172:175], v3 offset:31232
	ds_read_b128 v[180:183], v3 offset:31744
	ds_read_b128 v[184:187], v4 offset:30720
	ds_read_b128 v[176:179], v3 offset:31488
	s_waitcnt lgkmcnt(7)
; __device__ __forceinline__ float vfma(float a, float b, float c) { float d; asm("v_fma_f32 %0, %1, %2, %3" : "=v"(d) : "v"(a), "v"(b), "v"(c)); return d; }
; __device__ __forceinline__ float step_compute(float (&S)[4], const StepOp& o) {
;     float d1 = vmul(S[0], o.kk[0]), d2 = vmul(S[0], o.wr[0]), e1 = vmul(S[1], o.kk[1]), e2 = vmul(S[1], o.wr[1]);
;     d1 = vfma(S[2], o.kk[2], d1); d2 = vfma(S[2], o.wr[2], d2); e1 = vfma(S[3], o.kk[3], e1); e2 = vfma(S[3], o.wr[3], e2);
;     d1 = vadd(d1, e1); d2 = vadd(d2, e2);
;     float t0, t1, t2, t3;
;     asm volatile(
;         "v_mul_f32 %[t0], %[s0], %[w0]\n\t"
;         "v_mul_f32 %[t1], %[s1], %[w1]\n\t"
;         "v_add_f32_dpp %[d1], %[d1], %[d1] quad_perm:[1,0,3,2] row_mask:0xf bank_mask:0xf bound_ctrl:1\n\t"
;         "v_add_f32_dpp %[d2], %[d2], %[d2] quad_perm:[1,0,3,2] row_mask:0xf bank_mask:0xf bound_ctrl:1\n\t"
;         "v_mul_f32 %[t2], %[s2], %[w2]\n\t"
;         "v_add_f32_dpp %[d1], %[d1], %[d1] quad_perm:[2,3,0,1] row_mask:0xf bank_mask:0xf bound_ctrl:1\n\t"
;         "v_add_f32_dpp %[d2], %[d2], %[d2] quad_perm:[2,3,0,1] row_mask:0xf bank_mask:0xf bound_ctrl:1\n\t"
;         "v_mul_f32 %[t3], %[s3], %[w3]\n\t"
;         "v_add_f32_dpp %[d1], %[d1], %[d1] row_half_mirror row_mask:0xf bank_mask:0xf bound_ctrl:1\n\t"
;         "v_add_f32_dpp %[d2], %[d2], %[d2] row_half_mirror row_mask:0xf bank_mask:0xf bound_ctrl:1\n\t"
;         "v_fma_f32 %[t0], %[v], %[k0], %[t0]\n\t"
;         "v_add_f32_dpp %[d1], %[d1], %[d1] row_mirror row_mask:0xf bank_mask:0xf bound_ctrl:1\n\t"
;         "v_add_f32_dpp %[d2], %[d2], %[d2] row_mirror row_mask:0xf bank_mask:0xf bound_ctrl:1\n\t"
;         "v_fma_f32 %[t1], %[v], %[k1], %[t1]\n\t"
;         "v_fma_f32 %[t2], %[v], %[k2], %[t2]\n\t"
;         "v_fma_f32 %[t3], %[v], %[k3], %[t3]"
;         : [t0] "=&v"(t0), [t1] "=&v"(t1), [t2] "=&v"(t2), [t3] "=&v"(t3), [d1] "+v"(d1), [d2] "+v"(d2)
;         : [s0] "v"(S[0]), [s1] "v"(S[1]), [s2] "v"(S[2]), [s3] "v"(S[3]), [w0] "v"(o.w[0]), [w1] "v"(o.w[1]), [w2] "v"(o.w[2]), [w3] "v"(o.w[3]),
;           [k0] "v"(o.k[0]), [k1] "v"(o.k[1]), [k2] "v"(o.k[2]), [k3] "v"(o.k[3]), [v] "v"(o.q[0]));
;     S[0] = vnfma(d1, o.b[0], t0); S[1] = vnfma(d1, o.b[1], t1); S[2] = vnfma(d1, o.b[2], t2); S[3] = vnfma(d1, o.b[3], t3);
;     return vfma(o.q[0], o.q[2], vnfma(d1, o.q[1], d2));
	v_mul_f32 v188, v159, v188
	v_mul_f32 v192, v159, v192
	v_fma_f32 v188, v164, v189, v188
	v_fma_f32 v192, v164, v193, v192
	v_fma_f32 v188, v165, v190, v188
	v_fma_f32 v192, v165, v194, v192
	v_fma_f32 v188, v167, v191, v188
	v_fma_f32 v192, v167, v195, v192
	v_mul_f32 v196, v159, v196
	v_add_f32_dpp v188, v188, v188 row_half_mirror row_mask:0xf bank_mask:0x5
	v_add_f32_dpp v188, v192, v192 row_half_mirror row_mask:0xf bank_mask:0xa
	v_mul_f32 v197, v164, v197
	v_mul_f32 v198, v165, v198
	v_add_f32_dpp v188, v188, v188 quad_perm:[1,0,3,2] row_mask:0xf bank_mask:0xf
	v_mul_f32 v199, v167, v199
	v_fma_f32 v196, v208, v204, v196
	v_add_f32_dpp v188, v188, v188 quad_perm:[2,3,0,1] row_mask:0xf bank_mask:0xf
	v_fma_f32 v197, v208, v205, v197
	v_fma_f32 v198, v208, v206, v198
	v_add_f32_dpp v188, v188, v188 row_ror:8 row_mask:0xf bank_mask:0xf
	v_fma_f32 v192, v208, v210, v188
	v_fma_f32 v199, v208, v207, v199
	v_mov_b32_dpp v188, v188 row_half_mirror row_mask:0xf bank_mask:0xa
	v_fma_f32 v159, -v188, v200, v196
	v_fma_f32 v164, -v188, v201, v197
	v_fma_f32 v165, -v188, v202, v198
	v_fma_f32 v167, -v188, v203, v199
	v_fma_f32 v192, -v188, v209, v192
	ds_write_b32 v2, v192 offset:1216
	ds_read_b128 v[188:191], v3 offset:32256
	ds_read_b128 v[192:195], v3 offset:32512
	ds_read_b128 v[196:199], v3 offset:32768
	ds_read_b128 v[204:207], v3 offset:33280
	ds_read_b128 v[208:211], v4 offset:32256
	ds_read_b128 v[200:203], v3 offset:33024
	s_waitcnt lgkmcnt(7)
	v_mul_f32 v160, v159, v160
	v_mul_f32 v168, v159, v168
	v_fma_f32 v160, v164, v161, v160
	v_fma_f32 v168, v164, v169, v168
	v_fma_f32 v160, v165, v162, v160
	v_fma_f32 v168, v165, v170, v168
	v_fma_f32 v160, v167, v163, v160
	v_fma_f32 v168, v167, v171, v168
	v_mul_f32 v172, v159, v172
	v_add_f32_dpp v160, v160, v160 row_half_mirror row_mask:0xf bank_mask:0x5
	v_add_f32_dpp v160, v168, v168 row_half_mirror row_mask:0xf bank_mask:0xa
	v_mul_f32 v173, v164, v173
	v_mul_f32 v174, v165, v174
	v_add_f32_dpp v160, v160, v160 quad_perm:[1,0,3,2] row_mask:0xf bank_mask:0xf
	v_mul_f32 v175, v167, v175
	v_fma_f32 v172, v184, v180, v172
	v_add_f32_dpp v160, v160, v160 quad_perm:[2,3,0,1] row_mask:0xf bank_mask:0xf
	v_fma_f32 v173, v184, v181, v173
	v_fma_f32 v174, v184, v182, v174
	v_add_f32_dpp v160, v160, v160 row_ror:8 row_mask:0xf bank_mask:0xf
	v_fma_f32 v168, v184, v186, v160
	v_fma_f32 v175, v184, v183, v175
	v_mov_b32_dpp v160, v160 row_half_mirror row_mask:0xf bank_mask:0xa
	v_fma_f32 v159, -v160, v176, v172
	v_fma_f32 v164, -v160, v177, v173
	v_fma_f32 v165, -v160, v178, v174
	v_fma_f32 v167, -v160, v179, v175
	v_fma_f32 v168, -v160, v185, v168
	ds_write_b32 v2, v168 offset:1280
	ds_read_b128 v[160:163], v3 offset:33792
	ds_read_b128 v[168:171], v3 offset:34048
	ds_read_b128 v[172:175], v3 offset:34304
	ds_read_b128 v[180:183], v3 offset:34816
	ds_read_b128 v[184:187], v4 offset:33792
	ds_read_b128 v[176:179], v3 offset:34560
	s_waitcnt lgkmcnt(7)
	v_mul_f32 v188, v159, v188
	v_mul_f32 v192, v159, v192
	v_fma_f32 v188, v164, v189, v188
	v_fma_f32 v192, v164, v193, v192
	v_fma_f32 v188, v165, v190, v188
	v_fma_f32 v192, v165, v194, v192
	v_fma_f32 v188, v167, v191, v188
	v_fma_f32 v192, v167, v195, v192
	v_mul_f32 v196, v159, v196
	v_add_f32_dpp v188, v188, v188 row_half_mirror row_mask:0xf bank_mask:0x5
	v_add_f32_dpp v188, v192, v192 row_half_mirror row_mask:0xf bank_mask:0xa
	v_mul_f32 v197, v164, v197
	v_mul_f32 v198, v165, v198
	v_add_f32_dpp v188, v188, v188 quad_perm:[1,0,3,2] row_mask:0xf bank_mask:0xf
	v_mul_f32 v199, v167, v199
	v_fma_f32 v196, v208, v204, v196
	v_add_f32_dpp v188, v188, v188 quad_perm:[2,3,0,1] row_mask:0xf bank_mask:0xf
	v_fma_f32 v197, v208, v205, v197
	v_fma_f32 v198, v208, v206, v198
	v_add_f32_dpp v188, v188, v188 row_ror:8 row_mask:0xf bank_mask:0xf
	v_fma_f32 v192, v208, v210, v188
	v_fma_f32 v199, v208, v207, v199
	v_mov_b32_dpp v188, v188 row_half_mirror row_mask:0xf bank_mask:0xa
	v_fma_f32 v159, -v188, v200, v196
	v_fma_f32 v164, -v188, v201, v197
	v_fma_f32 v165, -v188, v202, v198
	v_fma_f32 v167, -v188, v203, v199
	v_fma_f32 v192, -v188, v209, v192
	ds_write_b32 v2, v192 offset:1344
	ds_read_b128 v[188:191], v3 offset:35328
	ds_read_b128 v[192:195], v3 offset:35584
	ds_read_b128 v[196:199], v3 offset:35840
	ds_read_b128 v[204:207], v3 offset:36352
	ds_read_b128 v[208:211], v4 offset:35328
	ds_read_b128 v[200:203], v3 offset:36096
	s_waitcnt lgkmcnt(7)
	v_mul_f32 v160, v159, v160
	v_mul_f32 v168, v159, v168
	v_fma_f32 v160, v164, v161, v160
	v_fma_f32 v168, v164, v169, v168
	v_fma_f32 v160, v165, v162, v160
	v_fma_f32 v168, v165, v170, v168
	v_fma_f32 v160, v167, v163, v160
	v_fma_f32 v168, v167, v171, v168
	v_mul_f32 v172, v159, v172
	v_add_f32_dpp v160, v160, v160 row_half_mirror row_mask:0xf bank_mask:0x5
	v_add_f32_dpp v160, v168, v168 row_half_mirror row_mask:0xf bank_mask:0xa
	v_mul_f32 v173, v164, v173
	v_mul_f32 v174, v165, v174
	v_add_f32_dpp v160, v160, v160 quad_perm:[1,0,3,2] row_mask:0xf bank_mask:0xf
	v_mul_f32 v175, v167, v175
	v_fma_f32 v172, v184, v180, v172
	v_add_f32_dpp v160, v160, v160 quad_perm:[2,3,0,1] row_mask:0xf bank_mask:0xf
	v_fma_f32 v173, v184, v181, v173
	v_fma_f32 v174, v184, v182, v174
	v_add_f32_dpp v160, v160, v160 row_ror:8 row_mask:0xf bank_mask:0xf
	v_fma_f32 v168, v184, v186, v160
	v_fma_f32 v175, v184, v183, v175
	v_mov_b32_dpp v160, v160 row_half_mirror row_mask:0xf bank_mask:0xa
	v_fma_f32 v159, -v160, v176, v172
	v_fma_f32 v164, -v160, v177, v173
	v_fma_f32 v165, -v160, v178, v174
	v_fma_f32 v167, -v160, v179, v175
	v_fma_f32 v168, -v160, v185, v168
	ds_write_b32 v2, v168 offset:1408
	ds_read_b128 v[160:163], v3 offset:36864
	ds_read_b128 v[168:171], v3 offset:37120
	ds_read_b128 v[172:175], v3 offset:37376
	ds_read_b128 v[180:183], v3 offset:37888
	ds_read_b128 v[184:187], v4 offset:36864
	ds_read_b128 v[176:179], v3 offset:37632
	s_waitcnt lgkmcnt(7)
; __device__ __forceinline__ float vfma(float a, float b, float c) { float d; asm("v_fma_f32 %0, %1, %2, %3" : "=v"(d) : "v"(a), "v"(b), "v"(c)); return d; }
; __device__ __forceinline__ float step_compute(float (&S)[4], const StepOp& o) {
;     float d1 = vmul(S[0], o.kk[0]), d2 = vmul(S[0], o.wr[0]), e1 = vmul(S[1], o.kk[1]), e2 = vmul(S[1], o.wr[1]);
;     d1 = vfma(S[2], o.kk[2], d1); d2 = vfma(S[2], o.wr[2], d2); e1 = vfma(S[3], o.kk[3], e1); e2 = vfma(S[3], o.wr[3], e2);
;     d1 = vadd(d1, e1); d2 = vadd(d2, e2);
;     float t0, t1, t2, t3;
;     asm volatile(
;         "v_mul_f32 %[t0], %[s0], %[w0]\n\t"
;         "v_mul_f32 %[t1], %[s1], %[w1]\n\t"
;         "v_add_f32_dpp %[d1], %[d1], %[d1] quad_perm:[1,0,3,2] row_mask:0xf bank_mask:0xf bound_ctrl:1\n\t"
;         "v_add_f32_dpp %[d2], %[d2], %[d2] quad_perm:[1,0,3,2] row_mask:0xf bank_mask:0xf bound_ctrl:1\n\t"
;         "v_mul_f32 %[t2], %[s2], %[w2]\n\t"
;         "v_add_f32_dpp %[d1], %[d1], %[d1] quad_perm:[2,3,0,1] row_mask:0xf bank_mask:0xf bound_ctrl:1\n\t"
;         "v_add_f32_dpp %[d2], %[d2], %[d2] quad_perm:[2,3,0,1] row_mask:0xf bank_mask:0xf bound_ctrl:1\n\t"
;         "v_mul_f32 %[t3], %[s3], %[w3]\n\t"
;         "v_add_f32_dpp %[d1], %[d1], %[d1] row_half_mirror row_mask:0xf bank_mask:0xf bound_ctrl:1\n\t"
;         "v_add_f32_dpp %[d2], %[d2], %[d2] row_half_mirror row_mask:0xf bank_mask:0xf bound_ctrl:1\n\t"
;         "v_fma_f32 %[t0], %[v], %[k0], %[t0]\n\t"
;         "v_add_f32_dpp %[d1], %[d1], %[d1] row_mirror row_mask:0xf bank_mask:0xf bound_ctrl:1\n\t"
;         "v_add_f32_dpp %[d2], %[d2], %[d2] row_mirror row_mask:0xf bank_mask:0xf bound_ctrl:1\n\t"
;         "v_fma_f32 %[t1], %[v], %[k1], %[t1]\n\t"
;         "v_fma_f32 %[t2], %[v], %[k2], %[t2]\n\t"
;         "v_fma_f32 %[t3], %[v], %[k3], %[t3]"
;         : [t0] "=&v"(t0), [t1] "=&v"(t1), [t2] "=&v"(t2), [t3] "=&v"(t3), [d1] "+v"(d1), [d2] "+v"(d2)
;         : [s0] "v"(S[0]), [s1] "v"(S[1]), [s2] "v"(S[2]), [s3] "v"(S[3]), [w0] "v"(o.w[0]), [w1] "v"(o.w[1]), [w2] "v"(o.w[2]), [w3] "v"(o.w[3]),
;           [k0] "v"(o.k[0]), [k1] "v"(o.k[1]), [k2] "v"(o.k[2]), [k3] "v"(o.k[3]), [v] "v"(o.q[0]));
;     S[0] = vnfma(d1, o.b[0], t0); S[1] = vnfma(d1, o.b[1], t1); S[2] = vnfma(d1, o.b[2], t2); S[3] = vnfma(d1, o.b[3], t3);
;     return vfma(o.q[0], o.q[2], vnfma(d1, o.q[1], d2));
	v_mul_f32 v188, v159, v188
	v_mul_f32 v192, v159, v192
	v_fma_f32 v188, v164, v189, v188
	v_fma_f32 v192, v164, v193, v192
	v_fma_f32 v188, v165, v190, v188
	v_fma_f32 v192, v165, v194, v192
	v_fma_f32 v188, v167, v191, v188
	v_fma_f32 v192, v167, v195, v192
	v_mul_f32 v196, v159, v196
	v_add_f32_dpp v188, v188, v188 row_half_mirror row_mask:0xf bank_mask:0x5
	v_add_f32_dpp v188, v192, v192 row_half_mirror row_mask:0xf bank_mask:0xa
	v_mul_f32 v197, v164, v197
	v_mul_f32 v198, v165, v198
	v_add_f32_dpp v188, v188, v188 quad_perm:[1,0,3,2] row_mask:0xf bank_mask:0xf
	v_mul_f32 v199, v167, v199
	v_fma_f32 v196, v208, v204, v196
	v_add_f32_dpp v188, v188, v188 quad_perm:[2,3,0,1] row_mask:0xf bank_mask:0xf
	v_fma_f32 v197, v208, v205, v197
	v_fma_f32 v198, v208, v206, v198
	v_add_f32_dpp v188, v188, v188 row_ror:8 row_mask:0xf bank_mask:0xf
	v_fma_f32 v192, v208, v210, v188
	v_fma_f32 v199, v208, v207, v199
	v_mov_b32_dpp v188, v188 row_half_mirror row_mask:0xf bank_mask:0xa
	v_fma_f32 v159, -v188, v200, v196
	v_fma_f32 v164, -v188, v201, v197
	v_fma_f32 v165, -v188, v202, v198
	v_fma_f32 v167, -v188, v203, v199
	v_fma_f32 v192, -v188, v209, v192
	ds_write_b32 v2, v192 offset:1472
	ds_read_b128 v[188:191], v3 offset:38400
	ds_read_b128 v[192:195], v3 offset:38656
	ds_read_b128 v[196:199], v3 offset:38912
	ds_read_b128 v[204:207], v3 offset:39424
	ds_read_b128 v[208:211], v4 offset:38400
	ds_read_b128 v[200:203], v3 offset:39168
	s_waitcnt lgkmcnt(7)
	v_mul_f32 v160, v159, v160
	v_mul_f32 v168, v159, v168
	v_fma_f32 v160, v164, v161, v160
	v_fma_f32 v168, v164, v169, v168
	v_fma_f32 v160, v165, v162, v160
	v_fma_f32 v168, v165, v170, v168
	v_fma_f32 v160, v167, v163, v160
	v_fma_f32 v168, v167, v171, v168
	v_mul_f32 v172, v159, v172
	v_add_f32_dpp v160, v160, v160 row_half_mirror row_mask:0xf bank_mask:0x5
	v_add_f32_dpp v160, v168, v168 row_half_mirror row_mask:0xf bank_mask:0xa
	v_mul_f32 v173, v164, v173
	v_mul_f32 v174, v165, v174
	v_add_f32_dpp v160, v160, v160 quad_perm:[1,0,3,2] row_mask:0xf bank_mask:0xf
	v_mul_f32 v175, v167, v175
	v_fma_f32 v172, v184, v180, v172
	v_add_f32_dpp v160, v160, v160 quad_perm:[2,3,0,1] row_mask:0xf bank_mask:0xf
	v_fma_f32 v173, v184, v181, v173
	v_fma_f32 v174, v184, v182, v174
	v_add_f32_dpp v160, v160, v160 row_ror:8 row_mask:0xf bank_mask:0xf
	v_fma_f32 v168, v184, v186, v160
	v_fma_f32 v175, v184, v183, v175
	v_mov_b32_dpp v160, v160 row_half_mirror row_mask:0xf bank_mask:0xa
	v_fma_f32 v159, -v160, v176, v172
	v_fma_f32 v164, -v160, v177, v173
	v_fma_f32 v165, -v160, v178, v174
	v_fma_f32 v167, -v160, v179, v175
	v_fma_f32 v168, -v160, v185, v168
	ds_write_b32 v2, v168 offset:1536
	ds_read_b128 v[160:163], v3 offset:39936
	ds_read_b128 v[168:171], v3 offset:40192
	ds_read_b128 v[172:175], v3 offset:40448
	ds_read_b128 v[180:183], v3 offset:40960
	ds_read_b128 v[184:187], v4 offset:39936
	ds_read_b128 v[176:179], v3 offset:40704
	s_waitcnt lgkmcnt(7)
	v_mul_f32 v188, v159, v188
	v_mul_f32 v192, v159, v192
	v_fma_f32 v188, v164, v189, v188
	v_fma_f32 v192, v164, v193, v192
	v_fma_f32 v188, v165, v190, v188
	v_fma_f32 v192, v165, v194, v192
	v_fma_f32 v188, v167, v191, v188
	v_fma_f32 v192, v167, v195, v192
	v_mul_f32 v196, v159, v196
	v_add_f32_dpp v188, v188, v188 row_half_mirror row_mask:0xf bank_mask:0x5
	v_add_f32_dpp v188, v192, v192 row_half_mirror row_mask:0xf bank_mask:0xa
	v_mul_f32 v197, v164, v197
	v_mul_f32 v198, v165, v198
	v_add_f32_dpp v188, v188, v188 quad_perm:[1,0,3,2] row_mask:0xf bank_mask:0xf
	v_mul_f32 v199, v167, v199
	v_fma_f32 v196, v208, v204, v196
	v_add_f32_dpp v188, v188, v188 quad_perm:[2,3,0,1] row_mask:0xf bank_mask:0xf
	v_fma_f32 v197, v208, v205, v197
	v_fma_f32 v198, v208, v206, v198
	v_add_f32_dpp v188, v188, v188 row_ror:8 row_mask:0xf bank_mask:0xf
	v_fma_f32 v192, v208, v210, v188
	v_fma_f32 v199, v208, v207, v199
	v_mov_b32_dpp v188, v188 row_half_mirror row_mask:0xf bank_mask:0xa
	v_fma_f32 v159, -v188, v200, v196
	v_fma_f32 v164, -v188, v201, v197
	v_fma_f32 v165, -v188, v202, v198
	v_fma_f32 v167, -v188, v203, v199
	v_fma_f32 v192, -v188, v209, v192
	ds_write_b32 v2, v192 offset:1600
	ds_read_b128 v[188:191], v3 offset:41472
	ds_read_b128 v[192:195], v3 offset:41728
	ds_read_b128 v[196:199], v3 offset:41984
	ds_read_b128 v[204:207], v3 offset:42496
	ds_read_b128 v[208:211], v4 offset:41472
	ds_read_b128 v[200:203], v3 offset:42240
	s_waitcnt lgkmcnt(7)
	v_mul_f32 v160, v159, v160
	v_mul_f32 v168, v159, v168
	v_fma_f32 v160, v164, v161, v160
	v_fma_f32 v168, v164, v169, v168
	v_fma_f32 v160, v165, v162, v160
	v_fma_f32 v168, v165, v170, v168
	v_fma_f32 v160, v167, v163, v160
	v_fma_f32 v168, v167, v171, v168
	v_mul_f32 v172, v159, v172
	v_add_f32_dpp v160, v160, v160 row_half_mirror row_mask:0xf bank_mask:0x5
	v_add_f32_dpp v160, v168, v168 row_half_mirror row_mask:0xf bank_mask:0xa
	v_mul_f32 v173, v164, v173
	v_mul_f32 v174, v165, v174
	v_add_f32_dpp v160, v160, v160 quad_perm:[1,0,3,2] row_mask:0xf bank_mask:0xf
	v_mul_f32 v175, v167, v175
	v_fma_f32 v172, v184, v180, v172
	v_add_f32_dpp v160, v160, v160 quad_perm:[2,3,0,1] row_mask:0xf bank_mask:0xf
	v_fma_f32 v173, v184, v181, v173
	v_fma_f32 v174, v184, v182, v174
	v_add_f32_dpp v160, v160, v160 row_ror:8 row_mask:0xf bank_mask:0xf
	v_fma_f32 v168, v184, v186, v160
	v_fma_f32 v175, v184, v183, v175
	v_mov_b32_dpp v160, v160 row_half_mirror row_mask:0xf bank_mask:0xa
	v_fma_f32 v159, -v160, v176, v172
	v_fma_f32 v164, -v160, v177, v173
	v_fma_f32 v165, -v160, v178, v174
	v_fma_f32 v167, -v160, v179, v175
	v_fma_f32 v168, -v160, v185, v168
	ds_write_b32 v2, v168 offset:1664
	ds_read_b128 v[160:163], v3 offset:43008
	ds_read_b128 v[168:171], v3 offset:43264
	ds_read_b128 v[172:175], v3 offset:43520
	ds_read_b128 v[180:183], v3 offset:44032
	ds_read_b128 v[184:187], v4 offset:43008
	ds_read_b128 v[176:179], v3 offset:43776
	s_waitcnt lgkmcnt(7)
; __device__ __forceinline__ float vfma(float a, float b, float c) { float d; asm("v_fma_f32 %0, %1, %2, %3" : "=v"(d) : "v"(a), "v"(b), "v"(c)); return d; }
; __device__ __forceinline__ float step_compute(float (&S)[4], const StepOp& o) {
;     float d1 = vmul(S[0], o.kk[0]), d2 = vmul(S[0], o.wr[0]), e1 = vmul(S[1], o.kk[1]), e2 = vmul(S[1], o.wr[1]);
;     d1 = vfma(S[2], o.kk[2], d1); d2 = vfma(S[2], o.wr[2], d2); e1 = vfma(S[3], o.kk[3], e1); e2 = vfma(S[3], o.wr[3], e2);
;     d1 = vadd(d1, e1); d2 = vadd(d2, e2);
;     float t0, t1, t2, t3;
;     asm volatile(
;         "v_mul_f32 %[t0], %[s0], %[w0]\n\t"
;         "v_mul_f32 %[t1], %[s1], %[w1]\n\t"
;         "v_add_f32_dpp %[d1], %[d1], %[d1] quad_perm:[1,0,3,2] row_mask:0xf bank_mask:0xf bound_ctrl:1\n\t"
;         "v_add_f32_dpp %[d2], %[d2], %[d2] quad_perm:[1,0,3,2] row_mask:0xf bank_mask:0xf bound_ctrl:1\n\t"
;         "v_mul_f32 %[t2], %[s2], %[w2]\n\t"
;         "v_add_f32_dpp %[d1], %[d1], %[d1] quad_perm:[2,3,0,1] row_mask:0xf bank_mask:0xf bound_ctrl:1\n\t"
;         "v_add_f32_dpp %[d2], %[d2], %[d2] quad_perm:[2,3,0,1] row_mask:0xf bank_mask:0xf bound_ctrl:1\n\t"
;         "v_mul_f32 %[t3], %[s3], %[w3]\n\t"
;         "v_add_f32_dpp %[d1], %[d1], %[d1] row_half_mirror row_mask:0xf bank_mask:0xf bound_ctrl:1\n\t"
;         "v_add_f32_dpp %[d2], %[d2], %[d2] row_half_mirror row_mask:0xf bank_mask:0xf bound_ctrl:1\n\t"
;         "v_fma_f32 %[t0], %[v], %[k0], %[t0]\n\t"
;         "v_add_f32_dpp %[d1], %[d1], %[d1] row_mirror row_mask:0xf bank_mask:0xf bound_ctrl:1\n\t"
;         "v_add_f32_dpp %[d2], %[d2], %[d2] row_mirror row_mask:0xf bank_mask:0xf bound_ctrl:1\n\t"
;         "v_fma_f32 %[t1], %[v], %[k1], %[t1]\n\t"
;         "v_fma_f32 %[t2], %[v], %[k2], %[t2]\n\t"
;         "v_fma_f32 %[t3], %[v], %[k3], %[t3]"
;         : [t0] "=&v"(t0), [t1] "=&v"(t1), [t2] "=&v"(t2), [t3] "=&v"(t3), [d1] "+v"(d1), [d2] "+v"(d2)
;         : [s0] "v"(S[0]), [s1] "v"(S[1]), [s2] "v"(S[2]), [s3] "v"(S[3]), [w0] "v"(o.w[0]), [w1] "v"(o.w[1]), [w2] "v"(o.w[2]), [w3] "v"(o.w[3]),
;           [k0] "v"(o.k[0]), [k1] "v"(o.k[1]), [k2] "v"(o.k[2]), [k3] "v"(o.k[3]), [v] "v"(o.q[0]));
;     S[0] = vnfma(d1, o.b[0], t0); S[1] = vnfma(d1, o.b[1], t1); S[2] = vnfma(d1, o.b[2], t2); S[3] = vnfma(d1, o.b[3], t3);
;     return vfma(o.q[0], o.q[2], vnfma(d1, o.q[1], d2));
	v_mul_f32 v188, v159, v188
	v_mul_f32 v192, v159, v192
	v_fma_f32 v188, v164, v189, v188
	v_fma_f32 v192, v164, v193, v192
	v_fma_f32 v188, v165, v190, v188
	v_fma_f32 v192, v165, v194, v192
	v_fma_f32 v188, v167, v191, v188
	v_fma_f32 v192, v167, v195, v192
	v_mul_f32 v196, v159, v196
	v_add_f32_dpp v188, v188, v188 row_half_mirror row_mask:0xf bank_mask:0x5
	v_add_f32_dpp v188, v192, v192 row_half_mirror row_mask:0xf bank_mask:0xa
	v_mul_f32 v197, v164, v197
	v_mul_f32 v198, v165, v198
	v_add_f32_dpp v188, v188, v188 quad_perm:[1,0,3,2] row_mask:0xf bank_mask:0xf
	v_mul_f32 v199, v167, v199
	v_fma_f32 v196, v208, v204, v196
	v_add_f32_dpp v188, v188, v188 quad_perm:[2,3,0,1] row_mask:0xf bank_mask:0xf
	v_fma_f32 v197, v208, v205, v197
	v_fma_f32 v198, v208, v206, v198
	v_add_f32_dpp v188, v188, v188 row_ror:8 row_mask:0xf bank_mask:0xf
	v_fma_f32 v192, v208, v210, v188
	v_fma_f32 v199, v208, v207, v199
	v_mov_b32_dpp v188, v188 row_half_mirror row_mask:0xf bank_mask:0xa
	v_fma_f32 v159, -v188, v200, v196
	v_fma_f32 v164, -v188, v201, v197
	v_fma_f32 v165, -v188, v202, v198
	v_fma_f32 v167, -v188, v203, v199
	v_fma_f32 v192, -v188, v209, v192
	ds_write_b32 v2, v192 offset:1728
	ds_read_b128 v[188:191], v3 offset:44544
	ds_read_b128 v[192:195], v3 offset:44800
	ds_read_b128 v[196:199], v3 offset:45056
	ds_read_b128 v[204:207], v3 offset:45568
	ds_read_b128 v[208:211], v4 offset:44544
	ds_read_b128 v[200:203], v3 offset:45312
	s_waitcnt lgkmcnt(7)
	v_mul_f32 v160, v159, v160
	v_mul_f32 v168, v159, v168
	v_fma_f32 v160, v164, v161, v160
	v_fma_f32 v168, v164, v169, v168
	v_fma_f32 v160, v165, v162, v160
	v_fma_f32 v168, v165, v170, v168
	v_fma_f32 v160, v167, v163, v160
	v_fma_f32 v168, v167, v171, v168
	v_mul_f32 v172, v159, v172
	v_add_f32_dpp v160, v160, v160 row_half_mirror row_mask:0xf bank_mask:0x5
	v_add_f32_dpp v160, v168, v168 row_half_mirror row_mask:0xf bank_mask:0xa
	v_mul_f32 v173, v164, v173
	v_mul_f32 v174, v165, v174
	v_add_f32_dpp v160, v160, v160 quad_perm:[1,0,3,2] row_mask:0xf bank_mask:0xf
	v_mul_f32 v175, v167, v175
	v_fma_f32 v172, v184, v180, v172
	v_add_f32_dpp v160, v160, v160 quad_perm:[2,3,0,1] row_mask:0xf bank_mask:0xf
	v_fma_f32 v173, v184, v181, v173
	v_fma_f32 v174, v184, v182, v174
	v_add_f32_dpp v160, v160, v160 row_ror:8 row_mask:0xf bank_mask:0xf
	v_fma_f32 v168, v184, v186, v160
	v_fma_f32 v175, v184, v183, v175
	v_mov_b32_dpp v160, v160 row_half_mirror row_mask:0xf bank_mask:0xa
	v_fma_f32 v159, -v160, v176, v172
	v_fma_f32 v164, -v160, v177, v173
	v_fma_f32 v165, -v160, v178, v174
	v_fma_f32 v167, -v160, v179, v175
	v_fma_f32 v168, -v160, v185, v168
	ds_write_b32 v2, v168 offset:1792
	ds_read_b128 v[160:163], v3 offset:46080
	ds_read_b128 v[168:171], v3 offset:46336
	ds_read_b128 v[172:175], v3 offset:46592
	ds_read_b128 v[180:183], v3 offset:47104
	ds_read_b128 v[184:187], v4 offset:46080
	ds_read_b128 v[176:179], v3 offset:46848
	s_waitcnt lgkmcnt(7)
	v_mul_f32 v188, v159, v188
	v_mul_f32 v192, v159, v192
	v_fma_f32 v188, v164, v189, v188
	v_fma_f32 v192, v164, v193, v192
	v_fma_f32 v188, v165, v190, v188
	v_fma_f32 v192, v165, v194, v192
	v_fma_f32 v188, v167, v191, v188
	v_fma_f32 v192, v167, v195, v192
	v_mul_f32 v196, v159, v196
	v_add_f32_dpp v188, v188, v188 row_half_mirror row_mask:0xf bank_mask:0x5
	v_add_f32_dpp v188, v192, v192 row_half_mirror row_mask:0xf bank_mask:0xa
	v_mul_f32 v197, v164, v197
	v_mul_f32 v198, v165, v198
	v_add_f32_dpp v188, v188, v188 quad_perm:[1,0,3,2] row_mask:0xf bank_mask:0xf
	v_mul_f32 v199, v167, v199
	v_fma_f32 v196, v208, v204, v196
	v_add_f32_dpp v188, v188, v188 quad_perm:[2,3,0,1] row_mask:0xf bank_mask:0xf
	v_fma_f32 v197, v208, v205, v197
	v_fma_f32 v198, v208, v206, v198
	v_add_f32_dpp v188, v188, v188 row_ror:8 row_mask:0xf bank_mask:0xf
	v_fma_f32 v192, v208, v210, v188
	v_fma_f32 v199, v208, v207, v199
	v_mov_b32_dpp v188, v188 row_half_mirror row_mask:0xf bank_mask:0xa
	v_fma_f32 v159, -v188, v200, v196
	v_fma_f32 v164, -v188, v201, v197
	v_fma_f32 v165, -v188, v202, v198
	v_fma_f32 v167, -v188, v203, v199
	v_fma_f32 v192, -v188, v209, v192
	ds_write_b32 v2, v192 offset:1856
	ds_read_b128 v[188:191], v3 offset:47616
	ds_read_b128 v[192:195], v3 offset:47872
	ds_read_b128 v[196:199], v3 offset:48128
	ds_read_b128 v[204:207], v3 offset:48640
	ds_read_b128 v[208:211], v4 offset:47616
	ds_read_b128 v[200:203], v3 offset:48384
	s_waitcnt lgkmcnt(7)
	v_mul_f32 v160, v159, v160
	v_mul_f32 v168, v159, v168
	v_fma_f32 v160, v164, v161, v160
	v_fma_f32 v168, v164, v169, v168
	v_fma_f32 v160, v165, v162, v160
	v_fma_f32 v168, v165, v170, v168
	v_fma_f32 v160, v167, v163, v160
	v_fma_f32 v168, v167, v171, v168
	v_mul_f32 v172, v159, v172
	v_add_f32_dpp v160, v160, v160 row_half_mirror row_mask:0xf bank_mask:0x5
	v_add_f32_dpp v160, v168, v168 row_half_mirror row_mask:0xf bank_mask:0xa
	v_mul_f32 v173, v164, v173
	v_mul_f32 v174, v165, v174
	v_add_f32_dpp v160, v160, v160 quad_perm:[1,0,3,2] row_mask:0xf bank_mask:0xf
	v_mul_f32 v175, v167, v175
	v_fma_f32 v172, v184, v180, v172
	v_add_f32_dpp v160, v160, v160 quad_perm:[2,3,0,1] row_mask:0xf bank_mask:0xf
	v_fma_f32 v173, v184, v181, v173
	v_fma_f32 v174, v184, v182, v174
	v_add_f32_dpp v160, v160, v160 row_ror:8 row_mask:0xf bank_mask:0xf
	v_fma_f32 v168, v184, v186, v160
	v_fma_f32 v175, v184, v183, v175
	v_mov_b32_dpp v160, v160 row_half_mirror row_mask:0xf bank_mask:0xa
	v_fma_f32 v159, -v160, v176, v172
	v_fma_f32 v164, -v160, v177, v173
	v_fma_f32 v165, -v160, v178, v174
	v_fma_f32 v167, -v160, v179, v175
	v_fma_f32 v168, -v160, v185, v168
	ds_write_b32 v2, v168 offset:1920
	s_waitcnt lgkmcnt(1)
	v_mul_f32 v188, v159, v188
	v_mul_f32 v192, v159, v192
	v_fma_f32 v188, v164, v189, v188
	v_fma_f32 v192, v164, v193, v192
	v_fma_f32 v188, v165, v190, v188
	v_fma_f32 v192, v165, v194, v192
	v_fma_f32 v188, v167, v191, v188
	v_fma_f32 v192, v167, v195, v192
	v_mul_f32 v196, v159, v196
	v_add_f32_dpp v188, v188, v188 row_half_mirror row_mask:0xf bank_mask:0x5
	v_add_f32_dpp v188, v192, v192 row_half_mirror row_mask:0xf bank_mask:0xa
	v_mul_f32 v197, v164, v197
	v_mul_f32 v198, v165, v198
	v_add_f32_dpp v188, v188, v188 quad_perm:[1,0,3,2] row_mask:0xf bank_mask:0xf
	v_mul_f32 v199, v167, v199
	v_fma_f32 v196, v208, v204, v196
	v_add_f32_dpp v188, v188, v188 quad_perm:[2,3,0,1] row_mask:0xf bank_mask:0xf
	v_fma_f32 v197, v208, v205, v197
	v_fma_f32 v198, v208, v206, v198
	v_add_f32_dpp v188, v188, v188 row_ror:8 row_mask:0xf bank_mask:0xf
	v_fma_f32 v192, v208, v210, v188
	v_fma_f32 v199, v208, v207, v199
	v_mov_b32_dpp v188, v188 row_half_mirror row_mask:0xf bank_mask:0xa
	v_fma_f32 v3, -v188, v200, v196
	v_fma_f32 v4, -v188, v201, v197
	v_fma_f32 v115, -v188, v202, v198
	v_fma_f32 v159, -v188, v203, v199
	v_fma_f32 v192, -v188, v209, v192
	ds_write_b32 v2, v192 offset:1984
